# selected loop v2 (row-major V + transposed LDS reads + register prefetch of next tile pair); fast grid barrier on first seam; window branch rewritten: all 5 tiles resident in LDS, one barrier pair
# speedup vs baseline: 1.1219x; 1.0179x over previous
; __device__ __forceinline__ void tile_issue(TileRegs& r, const int tid, const bf16_t* ksrc, const bf16_t* vsrc, size_t ld, int p0, int pmax) {
;     const int kkey = tid >> 3, kseg = tid & 7, pk = p0 + kkey; const int vkey = tid & 63, vseg = tid >> 6, pv = p0 + vkey;
;     r.k = (u32x4){0u, 0u, 0u, 0u}; r.v = (u32x4){0u, 0u, 0u, 0u};
;     if (pk >= 0 && pk <= pmax) r.k = *(const u32x4*)(ksrc + (size_t)pk * ld + kseg * 8);
;     if (pv >= 0 && pv <= pmax) r.v = *(const u32x4*)(vsrc + (size_t)pv * ld + vseg * 8); }
; __device__ __forceinline__ void nsa_unit(LAS unsigned char* lds, const Ctx& P, int l, int b, int hkv, int tb) {
;     ...
;         const bf16_t* kb = H + (size_t)b * SEQ * LDH + C_KS + hkv * 64; const bf16_t* vb = H + (size_t)b * SEQ * LDH + C_VS + hkv * 64;
;         U &= ((2ull << qb) - 1ull);
;         unsigned long long Ur = ((unsigned long long)(unsigned)__builtin_amdgcn_readfirstlane((int)(U >> 32)) << 32) | (unsigned)__builtin_amdgcn_readfirstlane((int)U);
;         const float cfar = lut[790];
;         while (Ur != 0ull) {
;             const int ja = __builtin_ctzll(Ur); Ur &= Ur - 1ull; const bool hasb = Ur != 0ull; int jb = 0; if (hasb) { jb = __builtin_ctzll(Ur); Ur &= Ur - 1ull; }
;             __syncthreads();
;             load2(kb, vb, LDH, ja * 64, jb * 64, hasb, SEQ - 1);
;             __syncthreads();
.LBB0_407:
	v_add_u32_e32 v102, v150, v148
	v_lshrrev_b32_e32 v78, 2, v97
	v_lshl_add_u32 v78, v103, 2, v78
	v_mul_u32_u24_e32 v78, 0x90, v78
	v_and_b32_e32 v79, 3, v97
	v_lshl_add_u32 v104, v79, 3, v78
	s_mov_b64 s[14:15], s[0:1]
	s_ff1_i32_b64 s0, s[14:15]
	s_add_u32 s4, s14, -1
	s_addc_u32 s5, s15, -1
	s_and_b64 s[14:15], s[14:15], s[4:5]
	s_mov_b32 s13, 1
	s_lshl_b32 s4, s0, 6
	v_add_u32_e32 v54, s4, v144
	v_mul_lo_u32 v54, v54, s75
	v_mov_b32_e32 v55, v1
	v_lshl_add_u64 v[54:55], v[54:55], 1, v[88:89]
	global_load_dwordx4 v[230:233], v[54:55], off
	global_load_dwordx4 v[114:117], v[54:55], off offset:512
	s_cmp_eq_u64 s[14:15], 0
	s_cbranch_scc1 .Lsl2_nob_1
	s_ff1_i32_b64 s1, s[14:15]
	s_add_u32 s4, s14, -1
	s_addc_u32 s5, s15, -1
	s_and_b64 s[14:15], s[14:15], s[4:5]
	s_mov_b32 s13, 3
	s_lshl_b32 s4, s1, 6
	v_add_u32_e32 v56, s4, v144
	v_mul_lo_u32 v56, v56, s75
	v_mov_b32_e32 v57, v1
	v_lshl_add_u64 v[56:57], v[56:57], 1, v[88:89]
	global_load_dwordx4 v[134:137], v[56:57], off
	global_load_dwordx4 v[156:159], v[56:57], off offset:512
.Lsl2_nob_1:
.Lsl2_top:
	s_mov_b32 s20, s0
	s_lshl_b32 s21, s0, 6
	s_mov_b32 s8, s1
	s_lshl_b32 s9, s1, 6
	s_bfe_u32 s12, s13, 0x10001
	s_waitcnt lgkmcnt(0)
	s_barrier
	s_waitcnt vmcnt(0)
	ds_write_b128 v146, v[230:233] offset:16384
	ds_write_b128 v146, v[114:117] offset:25600
	s_cmp_eq_u32 s12, 0
	s_cbranch_scc1 .Lsl2_wnb_2
	ds_write_b128 v146, v[134:137] offset:34816
	ds_write_b128 v146, v[156:159] offset:44032
.Lsl2_wnb_2:
	s_waitcnt lgkmcnt(0)
	s_barrier
	s_cmp_eq_u64 s[14:15], 0
	s_cbranch_scc1 .Lsl2_nonext_3
	s_ff1_i32_b64 s0, s[14:15]
	s_add_u32 s4, s14, -1
	s_addc_u32 s5, s15, -1
	s_and_b64 s[14:15], s[14:15], s[4:5]
	s_mov_b32 s13, 1
	s_lshl_b32 s4, s0, 6
	v_add_u32_e32 v54, s4, v144
	v_mul_lo_u32 v54, v54, s75
	v_mov_b32_e32 v55, v1
	v_lshl_add_u64 v[54:55], v[54:55], 1, v[88:89]
	global_load_dwordx4 v[230:233], v[54:55], off
	global_load_dwordx4 v[114:117], v[54:55], off offset:512
	s_cmp_eq_u64 s[14:15], 0
	s_cbranch_scc1 .Lsl2_nob_5
	s_ff1_i32_b64 s1, s[14:15]
	s_add_u32 s4, s14, -1
	s_addc_u32 s5, s15, -1
	s_and_b64 s[14:15], s[14:15], s[4:5]
	s_mov_b32 s13, 3
	s_lshl_b32 s4, s1, 6
	v_add_u32_e32 v56, s4, v144
	v_mul_lo_u32 v56, v56, s75
	v_mov_b32_e32 v57, v1
	v_lshl_add_u64 v[56:57], v[56:57], 1, v[88:89]
	global_load_dwordx4 v[134:137], v[56:57], off
	global_load_dwordx4 v[156:159], v[56:57], off offset:512

; #define LAS __attribute__((address_space(3)))
; template <int D, class SF>
; __device__ __forceinline__ void attn_step(const bf16x8 (&qf)[D / 32], const LAS bf16_t* Ks, const LAS bf16_t* Vt, f32x4 (&o)[D / 16], float& m, float& lsum, float& alpha_out, bf16x8& pf0_out, bf16x8& pf1_out, const int lane, SF sf) {
;     constexpr int KSTR = D + 8;
;     const int c = lane & 15, i = lane >> 4;
;     f32x4 s[4];
; #pragma unroll
;     for (int t = 0; t < 4; ++t) s[t] = (f32x4){0.f, 0.f, 0.f, 0.f};
; #pragma unroll
;     for (int ks = 0; ks < D / 32; ++ks) {
; #pragma unroll
;         for (int t = 0; t < 4; ++t) { const bf16x8 kf = *(const LAS bf16x8*)(Ks + (16 * t + c) * KSTR + ks * 32 + 8 * i); s[t] = mfma16(kf, qf[ks], s[t]); }
;     }
;     float v[16];
; #pragma unroll
;     for (int t = 0; t < 4; ++t)
; #pragma unroll
;         for (int r = 0; r < 4; ++r) v[4 * t + r] = sf(16 * t + 4 * i + r, s[t][r]);
;     float mx = fmaxf(fmaxf(fmaxf(v[0], v[1]), fmaxf(v[2], v[3])), fmaxf(fmaxf(v[4], v[5]), fmaxf(v[6], v[7])));
;     mx = fmaxf(mx, fmaxf(fmaxf(fmaxf(v[8], v[9]), fmaxf(v[10], v[11])), fmaxf(fmaxf(v[12], v[13]), fmaxf(v[14], v[15]))));
;     mx = rows_max(mx);
;     const float mnew = fmaxf(m, mx);
;     const float mc = fmaxf(mnew, -1e20f);
;     const float alpha = __builtin_amdgcn_exp2f(fmaxf(m, -1e20f) - mc);
;     float p[16], rs = 0.f;
; #pragma unroll
;     for (int r = 0; r < 16; ++r) { p[r] = __builtin_amdgcn_exp2f(v[r] - mc); rs += p[r]; }
;     rs = rows_sum(rs);
;     lsum = lsum * alpha + rs; m = mnew;
;     union { u32x4 u; bf16x8 b; } pk0, pk1;
;     pk0.u.x = cvt_pk_bf16(p[0], p[1]); pk0.u.y = cvt_pk_bf16(p[2], p[3]); pk0.u.z = cvt_pk_bf16(p[4], p[5]); pk0.u.w = cvt_pk_bf16(p[6], p[7]);
;     pk1.u.x = cvt_pk_bf16(p[8], p[9]); pk1.u.y = cvt_pk_bf16(p[10], p[11]); pk1.u.z = cvt_pk_bf16(p[12], p[13]); pk1.u.w = cvt_pk_bf16(p[14], p[15]);
;     if (__builtin_amdgcn_ballot_w64(alpha != 1.0f) != 0ull) {
; #pragma unroll
;         for (int dt = 0; dt < D / 16; ++dt) o[dt] *= alpha;
;     }
; #pragma unroll
;     for (int dt = 0; dt < D / 16; ++dt) {
;         const LAS bf16_t* vp = Vt + (16 * dt + c) * 72 + 4 * i;
;         union { u32x4 u; bf16x8 b; } vf0, vf1; const u32x2 a0 = *(const LAS u32x2*)vp, a1 = *(const LAS u32x2*)(vp + 16), b0 = *(const LAS u32x2*)(vp + 32), b1 = *(const LAS u32x2*)(vp + 48);
.Lsl2_nonext_3:
	s_mov_b32 s13, 0
.Lsl2_cont_4:
	s_sub_i32 s4, s19, s21
	s_cmp_lt_i32 s4, 0
	s_cbranch_scc1 .Lsl2_diaga_8
	s_cmpk_lt_i32 s4, 0x316
	s_cbranch_scc1 .Lsl2_neara_7
	v_lshrrev_b64 v[78:79], s20, v[18:19]
	v_and_b32_e32 v78, 1, v78
	v_cmp_eq_u32_e64 s[24:25], 1, v78
	s_cmp_eq_u64 s[24:25], 0
	s_cbranch_scc1 .Lsl2_skf_9
	ds_read_b128 v[198:201], v102 offset:16384
	ds_read_b128 v[206:209], v102 offset:18688
	ds_read_b128 v[202:205], v102 offset:16448
	ds_read_b128 v[210:213], v102 offset:18752
	ds_read_b128 v[214:217], v102 offset:20992
	ds_read_b128 v[222:225], v102 offset:23296
	ds_read_b128 v[218:221], v102 offset:21056
	ds_read_b128 v[226:229], v102 offset:23360
	s_waitcnt lgkmcnt(6)
	v_mfma_f32_16x16x32_bf16 v[54:57], v[198:201], v[2:5], 0
	v_mfma_f32_16x16x32_bf16 v[58:61], v[206:209], v[2:5], 0
	s_waitcnt lgkmcnt(4)
	v_mfma_f32_16x16x32_bf16 v[54:57], v[202:205], v[6:9], v[54:57]
	v_mfma_f32_16x16x32_bf16 v[58:61], v[210:213], v[6:9], v[58:61]
	s_waitcnt lgkmcnt(2)
	v_mfma_f32_16x16x32_bf16 v[62:65], v[214:217], v[2:5], 0
	v_mfma_f32_16x16x32_bf16 v[66:69], v[222:225], v[2:5], 0
	s_waitcnt lgkmcnt(0)
	v_mfma_f32_16x16x32_bf16 v[62:65], v[218:221], v[6:9], v[62:65]
	v_mfma_f32_16x16x32_bf16 v[66:69], v[226:229], v[6:9], v[66:69]
	ds_read_b64_tr_b16 v[198:199], v104 offset:25600
	ds_read_b64_tr_b16 v[200:201], v104 offset:27904
	ds_read_b64_tr_b16 v[202:203], v104 offset:30208
	ds_read_b64_tr_b16 v[204:205], v104 offset:32512
	ds_read_b64_tr_b16 v[206:207], v104 offset:25632
	ds_read_b64_tr_b16 v[208:209], v104 offset:27936
	ds_read_b64_tr_b16 v[210:211], v104 offset:30240
	ds_read_b64_tr_b16 v[212:213], v104 offset:32544
	ds_read_b64_tr_b16 v[214:215], v104 offset:25664
	ds_read_b64_tr_b16 v[216:217], v104 offset:27968
	ds_read_b64_tr_b16 v[218:219], v104 offset:30272
	ds_read_b64_tr_b16 v[220:221], v104 offset:32576
	ds_read_b64_tr_b16 v[222:223], v104 offset:25696
	ds_read_b64_tr_b16 v[224:225], v104 offset:28000
	ds_read_b64_tr_b16 v[226:227], v104 offset:30304
	ds_read_b64_tr_b16 v[228:229], v104 offset:32608
	v_max3_f32 v78, v54, v55, v56
	v_max3_f32 v79, v57, v58, v59
	v_max3_f32 v80, v60, v61, v62
	v_max3_f32 v81, v63, v64, v65
	v_max3_f32 v83, v66, v67, v68
	v_max3_f32 v78, v78, v79, v69
	v_max3_f32 v80, v80, v81, v83
	v_max_f32_e32 v78, v78, v80
	v_mov_b32_e32 v79, v78
	s_nop 1
	v_permlane16_swap_b32_e32 v78, v79
	v_max_f32_e32 v78, v78, v79
	v_mov_b32_e32 v79, v78
	s_nop 1
	v_permlane32_swap_b32_e32 v78, v79
	v_max_f32_e32 v78, v78, v79
	v_fmamk_f32 v78, v78, 0x3fb8aa3b, v92
	v_cndmask_b32_e64 v78, v243, v78, s[24:25]
	v_max_f32_e32 v80, v100, v78
	v_max_f32_e32 v82, 0xe0ad78ec, v100
	v_max_f32_e32 v81, 0xe0ad78ec, v80
	v_sub_f32_e32 v82, v82, v81
	v_mov_b32_e32 v100, v80
	v_exp_f32_e32 v82, v82
	v_sub_f32_e32 v83, v92, v81
	v_cndmask_b32_e64 v83, v243, v83, s[24:25]
	v_fmamk_f32 v54, v54, 0x3fb8aa3b, v83
	v_fmamk_f32 v55, v55, 0x3fb8aa3b, v83
	v_fmamk_f32 v56, v56, 0x3fb8aa3b, v83
	v_fmamk_f32 v57, v57, 0x3fb8aa3b, v83
	v_exp_f32_e32 v54, v54
	v_exp_f32_e32 v55, v55
	v_exp_f32_e32 v56, v56
	v_exp_f32_e32 v57, v57
	v_fmamk_f32 v58, v58, 0x3fb8aa3b, v83
	v_fmamk_f32 v59, v59, 0x3fb8aa3b, v83
	v_fmamk_f32 v60, v60, 0x3fb8aa3b, v83
	v_fmamk_f32 v61, v61, 0x3fb8aa3b, v83
	v_exp_f32_e32 v58, v58
	v_exp_f32_e32 v59, v59
	v_exp_f32_e32 v60, v60
	v_exp_f32_e32 v61, v61
	v_fmamk_f32 v62, v62, 0x3fb8aa3b, v83
	v_fmamk_f32 v63, v63, 0x3fb8aa3b, v83
	v_fmamk_f32 v64, v64, 0x3fb8aa3b, v83
	v_fmamk_f32 v65, v65, 0x3fb8aa3b, v83
	v_exp_f32_e32 v62, v62
	v_exp_f32_e32 v63, v63
	v_exp_f32_e32 v64, v64
	v_exp_f32_e32 v65, v65
	v_fmamk_f32 v66, v66, 0x3fb8aa3b, v83
	v_fmamk_f32 v67, v67, 0x3fb8aa3b, v83
	v_fmamk_f32 v68, v68, 0x3fb8aa3b, v83
	v_fmamk_f32 v69, v69, 0x3fb8aa3b, v83
	v_exp_f32_e32 v66, v66
	v_exp_f32_e32 v67, v67
	v_exp_f32_e32 v68, v68
	v_exp_f32_e32 v69, v69
	s_nop 0
	v_add_f32_e32 v78, v54, v55
	v_add_f32_e32 v79, v56, v57
	v_add_f32_e32 v80, v58, v59
	v_add_f32_e32 v81, v60, v61
	v_add_f32_e32 v78, v78, v62
	v_add_f32_e32 v79, v79, v63
	v_add_f32_e32 v80, v80, v64
	v_add_f32_e32 v81, v81, v65
	v_add_f32_e32 v78, v78, v66
	v_add_f32_e32 v79, v79, v67
	v_add_f32_e32 v80, v80, v68
	v_add_f32_e32 v81, v81, v69
	v_add_f32_e32 v78, v78, v79
	v_add_f32_e32 v80, v80, v81
	v_add_f32_e32 v78, v78, v80
	v_cvt_pk_bf16_f32 v70, v54, v55
	v_cvt_pk_bf16_f32 v71, v56, v57
	v_cvt_pk_bf16_f32 v72, v58, v59
	v_cvt_pk_bf16_f32 v73, v60, v61
	v_cvt_pk_bf16_f32 v74, v62, v63
	v_cvt_pk_bf16_f32 v75, v64, v65
	v_cvt_pk_bf16_f32 v76, v66, v67
	v_cvt_pk_bf16_f32 v77, v68, v69
	v_mov_b32_e32 v79, v78
	s_nop 1
	v_permlane16_swap_b32_e32 v78, v79
	v_add_f32_e32 v78, v78, v79
	v_mov_b32_e32 v79, v78
	s_nop 1
	v_permlane32_swap_b32_e32 v78, v79
	v_add_f32_e32 v78, v78, v79
	v_fma_f32 v106, v106, v82, v78
	v_cmp_neq_f32_e64 s[4:5], 1.0, v82
	s_cmp_eq_u64 s[4:5], 0
	s_cbranch_scc1 .Lsl2_nosc_10
	v_pk_mul_f32 v[38:39], v[38:39], v[82:83] op_sel_hi:[1,0]
	v_pk_mul_f32 v[40:41], v[40:41], v[82:83] op_sel_hi:[1,0]
	v_pk_mul_f32 v[42:43], v[42:43], v[82:83] op_sel_hi:[1,0]
	v_pk_mul_f32 v[44:45], v[44:45], v[82:83] op_sel_hi:[1,0]
	v_pk_mul_f32 v[46:47], v[46:47], v[82:83] op_sel_hi:[1,0]
	v_pk_mul_f32 v[48:49], v[48:49], v[82:83] op_sel_hi:[1,0]
	v_pk_mul_f32 v[50:51], v[50:51], v[82:83] op_sel_hi:[1,0]
	v_pk_mul_f32 v[52:53], v[52:53], v[82:83] op_sel_hi:[1,0]

; #define LAS __attribute__((address_space(3)))
; template <int D, class SF>
; __device__ __forceinline__ void attn_step(const bf16x8 (&qf)[D / 32], const LAS bf16_t* Ks, const LAS bf16_t* Vt, f32x4 (&o)[D / 16], float& m, float& lsum, float& alpha_out, bf16x8& pf0_out, bf16x8& pf1_out, const int lane, SF sf) {
;     constexpr int KSTR = D + 8;
;     const int c = lane & 15, i = lane >> 4;
;     f32x4 s[4];
; #pragma unroll
;     for (int t = 0; t < 4; ++t) s[t] = (f32x4){0.f, 0.f, 0.f, 0.f};
; #pragma unroll
;     for (int ks = 0; ks < D / 32; ++ks) {
; #pragma unroll
;         for (int t = 0; t < 4; ++t) { const bf16x8 kf = *(const LAS bf16x8*)(Ks + (16 * t + c) * KSTR + ks * 32 + 8 * i); s[t] = mfma16(kf, qf[ks], s[t]); }
;     }
;     float v[16];
; #pragma unroll
;     for (int t = 0; t < 4; ++t)
; #pragma unroll
;         for (int r = 0; r < 4; ++r) v[4 * t + r] = sf(16 * t + 4 * i + r, s[t][r]);
;     float mx = fmaxf(fmaxf(fmaxf(v[0], v[1]), fmaxf(v[2], v[3])), fmaxf(fmaxf(v[4], v[5]), fmaxf(v[6], v[7])));
;     mx = fmaxf(mx, fmaxf(fmaxf(fmaxf(v[8], v[9]), fmaxf(v[10], v[11])), fmaxf(fmaxf(v[12], v[13]), fmaxf(v[14], v[15]))));
;     mx = rows_max(mx);
;     const float mnew = fmaxf(m, mx);
;     const float mc = fmaxf(mnew, -1e20f);
;     const float alpha = __builtin_amdgcn_exp2f(fmaxf(m, -1e20f) - mc);
;     float p[16], rs = 0.f;
; #pragma unroll
;     for (int r = 0; r < 16; ++r) { p[r] = __builtin_amdgcn_exp2f(v[r] - mc); rs += p[r]; }
;     rs = rows_sum(rs);
;     lsum = lsum * alpha + rs; m = mnew;
;     union { u32x4 u; bf16x8 b; } pk0, pk1;
;     pk0.u.x = cvt_pk_bf16(p[0], p[1]); pk0.u.y = cvt_pk_bf16(p[2], p[3]); pk0.u.z = cvt_pk_bf16(p[4], p[5]); pk0.u.w = cvt_pk_bf16(p[6], p[7]);
;     pk1.u.x = cvt_pk_bf16(p[8], p[9]); pk1.u.y = cvt_pk_bf16(p[10], p[11]); pk1.u.z = cvt_pk_bf16(p[12], p[13]); pk1.u.w = cvt_pk_bf16(p[14], p[15]);
;     if (__builtin_amdgcn_ballot_w64(alpha != 1.0f) != 0ull) {
; #pragma unroll
;         for (int dt = 0; dt < D / 16; ++dt) o[dt] *= alpha;
;     }
; #pragma unroll
;     for (int dt = 0; dt < D / 16; ++dt) {
;         const LAS bf16_t* vp = Vt + (16 * dt + c) * 72 + 4 * i;
;         union { u32x4 u; bf16x8 b; } vf0, vf1; const u32x2 a0 = *(const LAS u32x2*)vp, a1 = *(const LAS u32x2*)(vp + 16), b0 = *(const LAS u32x2*)(vp + 32), b1 = *(const LAS u32x2*)(vp + 48);
.Lsl2_skf_9:
	v_lshrrev_b64 v[78:79], s20, v[20:21]
	v_and_b32_e32 v78, 1, v78
	v_cmp_eq_u32_e64 s[24:25], 1, v78
	s_cmp_eq_u64 s[24:25], 0
	s_cbranch_scc1 .Lsl2_skf_11
	ds_read_b128 v[198:201], v102 offset:16384
	ds_read_b128 v[206:209], v102 offset:18688
	ds_read_b128 v[202:205], v102 offset:16448
	ds_read_b128 v[210:213], v102 offset:18752
	ds_read_b128 v[214:217], v102 offset:20992
	ds_read_b128 v[222:225], v102 offset:23296
	ds_read_b128 v[218:221], v102 offset:21056
	ds_read_b128 v[226:229], v102 offset:23360
	s_waitcnt lgkmcnt(6)
	v_mfma_f32_16x16x32_bf16 v[54:57], v[198:201], v[10:13], 0
	v_mfma_f32_16x16x32_bf16 v[58:61], v[206:209], v[10:13], 0
	s_waitcnt lgkmcnt(4)
	v_mfma_f32_16x16x32_bf16 v[54:57], v[202:205], v[14:17], v[54:57]
	v_mfma_f32_16x16x32_bf16 v[58:61], v[210:213], v[14:17], v[58:61]
	s_waitcnt lgkmcnt(2)
	v_mfma_f32_16x16x32_bf16 v[62:65], v[214:217], v[10:13], 0
	v_mfma_f32_16x16x32_bf16 v[66:69], v[222:225], v[10:13], 0
	s_waitcnt lgkmcnt(0)
	v_mfma_f32_16x16x32_bf16 v[62:65], v[218:221], v[14:17], v[62:65]
	v_mfma_f32_16x16x32_bf16 v[66:69], v[226:229], v[14:17], v[66:69]
	ds_read_b64_tr_b16 v[198:199], v104 offset:25600
	ds_read_b64_tr_b16 v[200:201], v104 offset:27904
	ds_read_b64_tr_b16 v[202:203], v104 offset:30208
	ds_read_b64_tr_b16 v[204:205], v104 offset:32512
	ds_read_b64_tr_b16 v[206:207], v104 offset:25632
	ds_read_b64_tr_b16 v[208:209], v104 offset:27936
	ds_read_b64_tr_b16 v[210:211], v104 offset:30240
	ds_read_b64_tr_b16 v[212:213], v104 offset:32544
	ds_read_b64_tr_b16 v[214:215], v104 offset:25664
	ds_read_b64_tr_b16 v[216:217], v104 offset:27968
	ds_read_b64_tr_b16 v[218:219], v104 offset:30272
	ds_read_b64_tr_b16 v[220:221], v104 offset:32576
	ds_read_b64_tr_b16 v[222:223], v104 offset:25696
	ds_read_b64_tr_b16 v[224:225], v104 offset:28000
	ds_read_b64_tr_b16 v[226:227], v104 offset:30304
	ds_read_b64_tr_b16 v[228:229], v104 offset:32608
	v_max3_f32 v78, v54, v55, v56
	v_max3_f32 v79, v57, v58, v59
	v_max3_f32 v80, v60, v61, v62
	v_max3_f32 v81, v63, v64, v65
	v_max3_f32 v83, v66, v67, v68
	v_max3_f32 v78, v78, v79, v69
	v_max3_f32 v80, v80, v81, v83
	v_max_f32_e32 v78, v78, v80
	v_mov_b32_e32 v79, v78
	s_nop 1
	v_permlane16_swap_b32_e32 v78, v79
	v_max_f32_e32 v78, v78, v79
	v_mov_b32_e32 v79, v78
	s_nop 1
	v_permlane32_swap_b32_e32 v78, v79
	v_max_f32_e32 v78, v78, v79
	v_fmamk_f32 v78, v78, 0x3fb8aa3b, v92
	v_cndmask_b32_e64 v78, v243, v78, s[24:25]
	v_max_f32_e32 v80, v93, v78
	v_max_f32_e32 v82, 0xe0ad78ec, v93
	v_max_f32_e32 v81, 0xe0ad78ec, v80
	v_sub_f32_e32 v82, v82, v81
	v_mov_b32_e32 v93, v80
	v_exp_f32_e32 v82, v82
	v_sub_f32_e32 v83, v92, v81
	v_cndmask_b32_e64 v83, v243, v83, s[24:25]
	v_fmamk_f32 v54, v54, 0x3fb8aa3b, v83
	v_fmamk_f32 v55, v55, 0x3fb8aa3b, v83
	v_fmamk_f32 v56, v56, 0x3fb8aa3b, v83
	v_fmamk_f32 v57, v57, 0x3fb8aa3b, v83
	v_exp_f32_e32 v54, v54
	v_exp_f32_e32 v55, v55
	v_exp_f32_e32 v56, v56
	v_exp_f32_e32 v57, v57
	v_fmamk_f32 v58, v58, 0x3fb8aa3b, v83
	v_fmamk_f32 v59, v59, 0x3fb8aa3b, v83
	v_fmamk_f32 v60, v60, 0x3fb8aa3b, v83
	v_fmamk_f32 v61, v61, 0x3fb8aa3b, v83
	v_exp_f32_e32 v58, v58
	v_exp_f32_e32 v59, v59
	v_exp_f32_e32 v60, v60
	v_exp_f32_e32 v61, v61
	v_fmamk_f32 v62, v62, 0x3fb8aa3b, v83
	v_fmamk_f32 v63, v63, 0x3fb8aa3b, v83
	v_fmamk_f32 v64, v64, 0x3fb8aa3b, v83
	v_fmamk_f32 v65, v65, 0x3fb8aa3b, v83
	v_exp_f32_e32 v62, v62
	v_exp_f32_e32 v63, v63
	v_exp_f32_e32 v64, v64
	v_exp_f32_e32 v65, v65
	v_fmamk_f32 v66, v66, 0x3fb8aa3b, v83
	v_fmamk_f32 v67, v67, 0x3fb8aa3b, v83
	v_fmamk_f32 v68, v68, 0x3fb8aa3b, v83
	v_fmamk_f32 v69, v69, 0x3fb8aa3b, v83
	v_exp_f32_e32 v66, v66
	v_exp_f32_e32 v67, v67
	v_exp_f32_e32 v68, v68
	v_exp_f32_e32 v69, v69
	s_nop 0
	v_add_f32_e32 v78, v54, v55
	v_add_f32_e32 v79, v56, v57
	v_add_f32_e32 v80, v58, v59
	v_add_f32_e32 v81, v60, v61
	v_add_f32_e32 v78, v78, v62
	v_add_f32_e32 v79, v79, v63
	v_add_f32_e32 v80, v80, v64
	v_add_f32_e32 v81, v81, v65
	v_add_f32_e32 v78, v78, v66
	v_add_f32_e32 v79, v79, v67
	v_add_f32_e32 v80, v80, v68
	v_add_f32_e32 v81, v81, v69
	v_add_f32_e32 v78, v78, v79
	v_add_f32_e32 v80, v80, v81
	v_add_f32_e32 v78, v78, v80
	v_cvt_pk_bf16_f32 v70, v54, v55
	v_cvt_pk_bf16_f32 v71, v56, v57
	v_cvt_pk_bf16_f32 v72, v58, v59
	v_cvt_pk_bf16_f32 v73, v60, v61
	v_cvt_pk_bf16_f32 v74, v62, v63
	v_cvt_pk_bf16_f32 v75, v64, v65
	v_cvt_pk_bf16_f32 v76, v66, v67
	v_cvt_pk_bf16_f32 v77, v68, v69
	v_mov_b32_e32 v79, v78
	s_nop 1
	v_permlane16_swap_b32_e32 v78, v79
	v_add_f32_e32 v78, v78, v79
	v_mov_b32_e32 v79, v78
	s_nop 1
	v_permlane32_swap_b32_e32 v78, v79
	v_add_f32_e32 v78, v78, v79
	v_fma_f32 v105, v105, v82, v78
	v_cmp_neq_f32_e64 s[4:5], 1.0, v82
	s_cmp_eq_u64 s[4:5], 0
	s_cbranch_scc1 .Lsl2_nosc_12
	v_pk_mul_f32 v[22:23], v[22:23], v[82:83] op_sel_hi:[1,0]
	v_pk_mul_f32 v[24:25], v[24:25], v[82:83] op_sel_hi:[1,0]
	v_pk_mul_f32 v[26:27], v[26:27], v[82:83] op_sel_hi:[1,0]
	v_pk_mul_f32 v[28:29], v[28:29], v[82:83] op_sel_hi:[1,0]
	v_pk_mul_f32 v[34:35], v[34:35], v[82:83] op_sel_hi:[1,0]
	v_pk_mul_f32 v[36:37], v[36:37], v[82:83] op_sel_hi:[1,0]
	v_pk_mul_f32 v[30:31], v[30:31], v[82:83] op_sel_hi:[1,0]
	v_pk_mul_f32 v[32:33], v[32:33], v[82:83] op_sel_hi:[1,0]

; #define LAS __attribute__((address_space(3)))
; template <int D, class SF>
; __device__ __forceinline__ void attn_step(const bf16x8 (&qf)[D / 32], const LAS bf16_t* Ks, const LAS bf16_t* Vt, f32x4 (&o)[D / 16], float& m, float& lsum, float& alpha_out, bf16x8& pf0_out, bf16x8& pf1_out, const int lane, SF sf) {
;     constexpr int KSTR = D + 8;
;     const int c = lane & 15, i = lane >> 4;
;     f32x4 s[4];
; #pragma unroll
;     for (int t = 0; t < 4; ++t) s[t] = (f32x4){0.f, 0.f, 0.f, 0.f};
; #pragma unroll
;     for (int ks = 0; ks < D / 32; ++ks) {
; #pragma unroll
;         for (int t = 0; t < 4; ++t) { const bf16x8 kf = *(const LAS bf16x8*)(Ks + (16 * t + c) * KSTR + ks * 32 + 8 * i); s[t] = mfma16(kf, qf[ks], s[t]); }
;     }
;     float v[16];
; #pragma unroll
;     for (int t = 0; t < 4; ++t)
; #pragma unroll
;         for (int r = 0; r < 4; ++r) v[4 * t + r] = sf(16 * t + 4 * i + r, s[t][r]);
;     float mx = fmaxf(fmaxf(fmaxf(v[0], v[1]), fmaxf(v[2], v[3])), fmaxf(fmaxf(v[4], v[5]), fmaxf(v[6], v[7])));
;     mx = fmaxf(mx, fmaxf(fmaxf(fmaxf(v[8], v[9]), fmaxf(v[10], v[11])), fmaxf(fmaxf(v[12], v[13]), fmaxf(v[14], v[15]))));
;     mx = rows_max(mx);
;     const float mnew = fmaxf(m, mx);
;     const float mc = fmaxf(mnew, -1e20f);
;     const float alpha = __builtin_amdgcn_exp2f(fmaxf(m, -1e20f) - mc);
;     float p[16], rs = 0.f;
; #pragma unroll
;     for (int r = 0; r < 16; ++r) { p[r] = __builtin_amdgcn_exp2f(v[r] - mc); rs += p[r]; }
;     rs = rows_sum(rs);
;     lsum = lsum * alpha + rs; m = mnew;
;     union { u32x4 u; bf16x8 b; } pk0, pk1;
;     pk0.u.x = cvt_pk_bf16(p[0], p[1]); pk0.u.y = cvt_pk_bf16(p[2], p[3]); pk0.u.z = cvt_pk_bf16(p[4], p[5]); pk0.u.w = cvt_pk_bf16(p[6], p[7]);
;     pk1.u.x = cvt_pk_bf16(p[8], p[9]); pk1.u.y = cvt_pk_bf16(p[10], p[11]); pk1.u.z = cvt_pk_bf16(p[12], p[13]); pk1.u.w = cvt_pk_bf16(p[14], p[15]);
;     if (__builtin_amdgcn_ballot_w64(alpha != 1.0f) != 0ull) {
; #pragma unroll
;         for (int dt = 0; dt < D / 16; ++dt) o[dt] *= alpha;
;     }
; #pragma unroll
;     for (int dt = 0; dt < D / 16; ++dt) {
;         const LAS bf16_t* vp = Vt + (16 * dt + c) * 72 + 4 * i;
;         union { u32x4 u; bf16x8 b; } vf0, vf1; const u32x2 a0 = *(const LAS u32x2*)vp, a1 = *(const LAS u32x2*)(vp + 16), b0 = *(const LAS u32x2*)(vp + 32), b1 = *(const LAS u32x2*)(vp + 48);
.Lsl2_neara_7:
	v_lshrrev_b64 v[78:79], s20, v[18:19]
	v_and_b32_e32 v78, 1, v78
	v_cmp_eq_u32_e64 s[24:25], 1, v78
	s_cmp_eq_u64 s[24:25], 0
	s_cbranch_scc1 .Lsl2_skn_13
	v_sub_u32_e32 v78, v130, v139
	v_subrev_u32_e32 v78, s21, v78
	v_lshl_add_u32 v79, v78, 2, v131
	v_add_u32_e32 v79, 0xffffff34, v79
	ds_read_b32 v107, v79 offset:204
	ds_read_b32 v108, v79 offset:200
	ds_read_b32 v109, v79 offset:196
	ds_read_b32 v110, v79 offset:192
	ds_read_b32 v111, v79 offset:140
	ds_read_b32 v112, v79 offset:136
	ds_read_b32 v113, v79 offset:132
	ds_read_b32 v133, v79 offset:128
	ds_read_b128 v[198:201], v102 offset:16384
	ds_read_b128 v[206:209], v102 offset:18688
	ds_read_b128 v[202:205], v102 offset:16448
	ds_read_b128 v[210:213], v102 offset:18752
	ds_read_b128 v[214:217], v102 offset:20992
	ds_read_b128 v[222:225], v102 offset:23296
	ds_read_b128 v[218:221], v102 offset:21056
	ds_read_b128 v[226:229], v102 offset:23360
	s_waitcnt lgkmcnt(6)
	v_mfma_f32_16x16x32_bf16 v[54:57], v[198:201], v[2:5], 0
	v_mfma_f32_16x16x32_bf16 v[58:61], v[206:209], v[2:5], 0
	s_waitcnt lgkmcnt(4)
	v_mfma_f32_16x16x32_bf16 v[54:57], v[202:205], v[6:9], v[54:57]
	v_mfma_f32_16x16x32_bf16 v[58:61], v[210:213], v[6:9], v[58:61]
	s_waitcnt lgkmcnt(2)
	v_mfma_f32_16x16x32_bf16 v[62:65], v[214:217], v[2:5], 0
	v_mfma_f32_16x16x32_bf16 v[66:69], v[222:225], v[2:5], 0
	s_waitcnt lgkmcnt(0)
	v_mfma_f32_16x16x32_bf16 v[62:65], v[218:221], v[6:9], v[62:65]
	v_mfma_f32_16x16x32_bf16 v[66:69], v[226:229], v[6:9], v[66:69]
	ds_read_b64_tr_b16 v[198:199], v104 offset:25600
	ds_read_b64_tr_b16 v[200:201], v104 offset:27904
	ds_read_b64_tr_b16 v[202:203], v104 offset:30208
	ds_read_b64_tr_b16 v[204:205], v104 offset:32512
	ds_read_b64_tr_b16 v[206:207], v104 offset:25632
	ds_read_b64_tr_b16 v[208:209], v104 offset:27936
	ds_read_b64_tr_b16 v[210:211], v104 offset:30240
	v_fmamk_f32 v54, v54, 0x3fb8aa3b, v107
	v_fmamk_f32 v55, v55, 0x3fb8aa3b, v108
	v_fmamk_f32 v56, v56, 0x3fb8aa3b, v109
	v_fmamk_f32 v57, v57, 0x3fb8aa3b, v110
	v_fmamk_f32 v58, v58, 0x3fb8aa3b, v111
	v_fmamk_f32 v59, v59, 0x3fb8aa3b, v112
	v_fmamk_f32 v60, v60, 0x3fb8aa3b, v113
	v_fmamk_f32 v61, v61, 0x3fb8aa3b, v133
	ds_read_b32 v107, v79 offset:76
	ds_read_b32 v108, v79 offset:72
	ds_read_b32 v109, v79 offset:68
	ds_read_b32 v110, v79 offset:64
	ds_read_b32 v111, v79 offset:12
	ds_read_b32 v112, v79 offset:8
	ds_read_b32 v113, v79 offset:4
	ds_read_b32 v133, v79 offset:0
	ds_read_b64_tr_b16 v[212:213], v104 offset:32544
	ds_read_b64_tr_b16 v[214:215], v104 offset:25664
	ds_read_b64_tr_b16 v[216:217], v104 offset:27968
	ds_read_b64_tr_b16 v[218:219], v104 offset:30272
	ds_read_b64_tr_b16 v[220:221], v104 offset:32576
	ds_read_b64_tr_b16 v[222:223], v104 offset:25696
	ds_read_b64_tr_b16 v[224:225], v104 offset:28000
	ds_read_b64_tr_b16 v[226:227], v104 offset:30304
	ds_read_b64_tr_b16 v[228:229], v104 offset:32608
	s_waitcnt lgkmcnt(9)
	v_fmamk_f32 v62, v62, 0x3fb8aa3b, v107
	v_fmamk_f32 v63, v63, 0x3fb8aa3b, v108
	v_fmamk_f32 v64, v64, 0x3fb8aa3b, v109
	v_fmamk_f32 v65, v65, 0x3fb8aa3b, v110
	v_fmamk_f32 v66, v66, 0x3fb8aa3b, v111
	v_fmamk_f32 v67, v67, 0x3fb8aa3b, v112
	v_fmamk_f32 v68, v68, 0x3fb8aa3b, v113
	v_fmamk_f32 v69, v69, 0x3fb8aa3b, v133
	v_max3_f32 v84, v54, v55, v56
	v_max3_f32 v79, v57, v58, v59
	v_max3_f32 v80, v60, v61, v62
	v_max3_f32 v81, v63, v64, v65
	v_max3_f32 v83, v66, v67, v68
	v_max3_f32 v84, v84, v79, v69
	v_max3_f32 v80, v80, v81, v83
	v_max_f32_e32 v84, v84, v80
	v_mov_b32_e32 v79, v84
	s_nop 1
	v_permlane16_swap_b32_e32 v84, v79
	v_max_f32_e32 v84, v84, v79
	v_mov_b32_e32 v79, v84
	s_nop 1
	v_permlane32_swap_b32_e32 v84, v79
	v_max_f32_e32 v84, v84, v79
	v_cndmask_b32_e64 v84, v243, v84, s[24:25]
	v_max_f32_e32 v80, v100, v84
	v_max_f32_e32 v82, 0xe0ad78ec, v100
	v_max_f32_e32 v81, 0xe0ad78ec, v80
	v_sub_f32_e32 v82, v82, v81
	v_mov_b32_e32 v100, v80
	v_exp_f32_e32 v82, v82
	v_mov_b32_e32 v83, 0x7149f2ca
	v_cndmask_b32_e64 v83, v83, v81, s[24:25]
	v_sub_f32_e32 v54, v54, v83
	v_sub_f32_e32 v55, v55, v83
	v_sub_f32_e32 v56, v56, v83
	v_sub_f32_e32 v57, v57, v83
	v_exp_f32_e32 v54, v54
	v_exp_f32_e32 v55, v55
	v_exp_f32_e32 v56, v56
	v_exp_f32_e32 v57, v57
	v_sub_f32_e32 v58, v58, v83
	v_sub_f32_e32 v59, v59, v83
	v_sub_f32_e32 v60, v60, v83
	v_sub_f32_e32 v61, v61, v83
	v_exp_f32_e32 v58, v58
	v_exp_f32_e32 v59, v59
	v_exp_f32_e32 v60, v60
	v_exp_f32_e32 v61, v61
	v_sub_f32_e32 v62, v62, v83
	v_sub_f32_e32 v63, v63, v83
	v_sub_f32_e32 v64, v64, v83
	v_sub_f32_e32 v65, v65, v83
	v_exp_f32_e32 v62, v62
	v_exp_f32_e32 v63, v63
	v_exp_f32_e32 v64, v64
	v_exp_f32_e32 v65, v65
	v_sub_f32_e32 v66, v66, v83
	v_sub_f32_e32 v67, v67, v83
	v_sub_f32_e32 v68, v68, v83
	v_sub_f32_e32 v69, v69, v83
	v_exp_f32_e32 v66, v66
	v_exp_f32_e32 v67, v67
	v_exp_f32_e32 v68, v68
	v_exp_f32_e32 v69, v69
	s_nop 0
	v_add_f32_e32 v78, v54, v55
	v_add_f32_e32 v79, v56, v57
	v_add_f32_e32 v80, v58, v59
	v_add_f32_e32 v81, v60, v61
	v_add_f32_e32 v78, v78, v62
	v_add_f32_e32 v79, v79, v63
	v_add_f32_e32 v80, v80, v64
	v_add_f32_e32 v81, v81, v65
	v_add_f32_e32 v78, v78, v66
	v_add_f32_e32 v79, v79, v67
	v_add_f32_e32 v80, v80, v68
	v_add_f32_e32 v81, v81, v69
	v_add_f32_e32 v78, v78, v79
	v_add_f32_e32 v80, v80, v81
	v_add_f32_e32 v78, v78, v80
	v_cvt_pk_bf16_f32 v70, v54, v55
	v_cvt_pk_bf16_f32 v71, v56, v57
	v_cvt_pk_bf16_f32 v72, v58, v59
	v_cvt_pk_bf16_f32 v73, v60, v61
	v_cvt_pk_bf16_f32 v74, v62, v63
	v_cvt_pk_bf16_f32 v75, v64, v65
	v_cvt_pk_bf16_f32 v76, v66, v67
	v_cvt_pk_bf16_f32 v77, v68, v69
	v_mov_b32_e32 v79, v78
	s_nop 1
	v_permlane16_swap_b32_e32 v78, v79
	v_add_f32_e32 v78, v78, v79
	v_mov_b32_e32 v79, v78
	s_nop 1
	v_permlane32_swap_b32_e32 v78, v79
	v_add_f32_e32 v78, v78, v79
	v_fma_f32 v106, v106, v82, v78
	v_cmp_neq_f32_e64 s[4:5], 1.0, v82
	s_cmp_eq_u64 s[4:5], 0
	s_cbranch_scc1 .Lsl2_nosc_14
	v_pk_mul_f32 v[38:39], v[38:39], v[82:83] op_sel_hi:[1,0]
	v_pk_mul_f32 v[40:41], v[40:41], v[82:83] op_sel_hi:[1,0]
	v_pk_mul_f32 v[42:43], v[42:43], v[82:83] op_sel_hi:[1,0]
	v_pk_mul_f32 v[44:45], v[44:45], v[82:83] op_sel_hi:[1,0]
	v_pk_mul_f32 v[46:47], v[46:47], v[82:83] op_sel_hi:[1,0]
	v_pk_mul_f32 v[48:49], v[48:49], v[82:83] op_sel_hi:[1,0]
	v_pk_mul_f32 v[50:51], v[50:51], v[82:83] op_sel_hi:[1,0]
	v_pk_mul_f32 v[52:53], v[52:53], v[82:83] op_sel_hi:[1,0]

; #define LAS __attribute__((address_space(3)))
; template <int D, class SF>
; __device__ __forceinline__ void attn_step(const bf16x8 (&qf)[D / 32], const LAS bf16_t* Ks, const LAS bf16_t* Vt, f32x4 (&o)[D / 16], float& m, float& lsum, float& alpha_out, bf16x8& pf0_out, bf16x8& pf1_out, const int lane, SF sf) {
;     constexpr int KSTR = D + 8;
;     const int c = lane & 15, i = lane >> 4;
;     f32x4 s[4];
; #pragma unroll
;     for (int t = 0; t < 4; ++t) s[t] = (f32x4){0.f, 0.f, 0.f, 0.f};
; #pragma unroll
;     for (int ks = 0; ks < D / 32; ++ks) {
; #pragma unroll
;         for (int t = 0; t < 4; ++t) { const bf16x8 kf = *(const LAS bf16x8*)(Ks + (16 * t + c) * KSTR + ks * 32 + 8 * i); s[t] = mfma16(kf, qf[ks], s[t]); }
;     }
;     float v[16];
; #pragma unroll
;     for (int t = 0; t < 4; ++t)
; #pragma unroll
;         for (int r = 0; r < 4; ++r) v[4 * t + r] = sf(16 * t + 4 * i + r, s[t][r]);
;     float mx = fmaxf(fmaxf(fmaxf(v[0], v[1]), fmaxf(v[2], v[3])), fmaxf(fmaxf(v[4], v[5]), fmaxf(v[6], v[7])));
;     mx = fmaxf(mx, fmaxf(fmaxf(fmaxf(v[8], v[9]), fmaxf(v[10], v[11])), fmaxf(fmaxf(v[12], v[13]), fmaxf(v[14], v[15]))));
;     mx = rows_max(mx);
;     const float mnew = fmaxf(m, mx);
;     const float mc = fmaxf(mnew, -1e20f);
;     const float alpha = __builtin_amdgcn_exp2f(fmaxf(m, -1e20f) - mc);
;     float p[16], rs = 0.f;
; #pragma unroll
;     for (int r = 0; r < 16; ++r) { p[r] = __builtin_amdgcn_exp2f(v[r] - mc); rs += p[r]; }
;     rs = rows_sum(rs);
;     lsum = lsum * alpha + rs; m = mnew;
;     union { u32x4 u; bf16x8 b; } pk0, pk1;
;     pk0.u.x = cvt_pk_bf16(p[0], p[1]); pk0.u.y = cvt_pk_bf16(p[2], p[3]); pk0.u.z = cvt_pk_bf16(p[4], p[5]); pk0.u.w = cvt_pk_bf16(p[6], p[7]);
;     pk1.u.x = cvt_pk_bf16(p[8], p[9]); pk1.u.y = cvt_pk_bf16(p[10], p[11]); pk1.u.z = cvt_pk_bf16(p[12], p[13]); pk1.u.w = cvt_pk_bf16(p[14], p[15]);
;     if (__builtin_amdgcn_ballot_w64(alpha != 1.0f) != 0ull) {
; #pragma unroll
;         for (int dt = 0; dt < D / 16; ++dt) o[dt] *= alpha;
;     }
; #pragma unroll
;     for (int dt = 0; dt < D / 16; ++dt) {
;         const LAS bf16_t* vp = Vt + (16 * dt + c) * 72 + 4 * i;
;         union { u32x4 u; bf16x8 b; } vf0, vf1; const u32x2 a0 = *(const LAS u32x2*)vp, a1 = *(const LAS u32x2*)(vp + 16), b0 = *(const LAS u32x2*)(vp + 32), b1 = *(const LAS u32x2*)(vp + 48);
.Lsl2_skn_13:
	v_lshrrev_b64 v[78:79], s20, v[20:21]
	v_and_b32_e32 v78, 1, v78
	v_cmp_eq_u32_e64 s[24:25], 1, v78
	s_cmp_eq_u64 s[24:25], 0
	s_cbranch_scc1 .Lsl2_skn_15
	v_sub_u32_e32 v78, v98, v139
	v_subrev_u32_e32 v78, s21, v78
	v_lshl_add_u32 v79, v78, 2, v131
	v_add_u32_e32 v79, 0xffffff34, v79
	ds_read_b32 v107, v79 offset:204
	ds_read_b32 v108, v79 offset:200
	ds_read_b32 v109, v79 offset:196
	ds_read_b32 v110, v79 offset:192
	ds_read_b32 v111, v79 offset:140
	ds_read_b32 v112, v79 offset:136
	ds_read_b32 v113, v79 offset:132
	ds_read_b32 v133, v79 offset:128
	ds_read_b128 v[198:201], v102 offset:16384
	ds_read_b128 v[206:209], v102 offset:18688
	ds_read_b128 v[202:205], v102 offset:16448
	ds_read_b128 v[210:213], v102 offset:18752
	ds_read_b128 v[214:217], v102 offset:20992
	ds_read_b128 v[222:225], v102 offset:23296
	ds_read_b128 v[218:221], v102 offset:21056
	ds_read_b128 v[226:229], v102 offset:23360
	s_waitcnt lgkmcnt(6)
	v_mfma_f32_16x16x32_bf16 v[54:57], v[198:201], v[10:13], 0
	v_mfma_f32_16x16x32_bf16 v[58:61], v[206:209], v[10:13], 0
	s_waitcnt lgkmcnt(4)
	v_mfma_f32_16x16x32_bf16 v[54:57], v[202:205], v[14:17], v[54:57]
	v_mfma_f32_16x16x32_bf16 v[58:61], v[210:213], v[14:17], v[58:61]
	s_waitcnt lgkmcnt(2)
	v_mfma_f32_16x16x32_bf16 v[62:65], v[214:217], v[10:13], 0
	v_mfma_f32_16x16x32_bf16 v[66:69], v[222:225], v[10:13], 0
	s_waitcnt lgkmcnt(0)
	v_mfma_f32_16x16x32_bf16 v[62:65], v[218:221], v[14:17], v[62:65]
	v_mfma_f32_16x16x32_bf16 v[66:69], v[226:229], v[14:17], v[66:69]
	ds_read_b64_tr_b16 v[198:199], v104 offset:25600
	ds_read_b64_tr_b16 v[200:201], v104 offset:27904
	ds_read_b64_tr_b16 v[202:203], v104 offset:30208
	ds_read_b64_tr_b16 v[204:205], v104 offset:32512
	ds_read_b64_tr_b16 v[206:207], v104 offset:25632
	ds_read_b64_tr_b16 v[208:209], v104 offset:27936
	ds_read_b64_tr_b16 v[210:211], v104 offset:30240
	v_fmamk_f32 v54, v54, 0x3fb8aa3b, v107
	v_fmamk_f32 v55, v55, 0x3fb8aa3b, v108
	v_fmamk_f32 v56, v56, 0x3fb8aa3b, v109
	v_fmamk_f32 v57, v57, 0x3fb8aa3b, v110
	v_fmamk_f32 v58, v58, 0x3fb8aa3b, v111
	v_fmamk_f32 v59, v59, 0x3fb8aa3b, v112
	v_fmamk_f32 v60, v60, 0x3fb8aa3b, v113
	v_fmamk_f32 v61, v61, 0x3fb8aa3b, v133
	ds_read_b32 v107, v79 offset:76
	ds_read_b32 v108, v79 offset:72
	ds_read_b32 v109, v79 offset:68
	ds_read_b32 v110, v79 offset:64
	ds_read_b32 v111, v79 offset:12
	ds_read_b32 v112, v79 offset:8
	ds_read_b32 v113, v79 offset:4
	ds_read_b32 v133, v79 offset:0
	ds_read_b64_tr_b16 v[212:213], v104 offset:32544
	ds_read_b64_tr_b16 v[214:215], v104 offset:25664
	ds_read_b64_tr_b16 v[216:217], v104 offset:27968
	ds_read_b64_tr_b16 v[218:219], v104 offset:30272
	ds_read_b64_tr_b16 v[220:221], v104 offset:32576
	ds_read_b64_tr_b16 v[222:223], v104 offset:25696
	ds_read_b64_tr_b16 v[224:225], v104 offset:28000
	ds_read_b64_tr_b16 v[226:227], v104 offset:30304
	ds_read_b64_tr_b16 v[228:229], v104 offset:32608
	s_waitcnt lgkmcnt(9)
	v_fmamk_f32 v62, v62, 0x3fb8aa3b, v107
	v_fmamk_f32 v63, v63, 0x3fb8aa3b, v108
	v_fmamk_f32 v64, v64, 0x3fb8aa3b, v109
	v_fmamk_f32 v65, v65, 0x3fb8aa3b, v110
	v_fmamk_f32 v66, v66, 0x3fb8aa3b, v111
	v_fmamk_f32 v67, v67, 0x3fb8aa3b, v112
	v_fmamk_f32 v68, v68, 0x3fb8aa3b, v113
	v_fmamk_f32 v69, v69, 0x3fb8aa3b, v133
	v_max3_f32 v84, v54, v55, v56
	v_max3_f32 v79, v57, v58, v59
	v_max3_f32 v80, v60, v61, v62
	v_max3_f32 v81, v63, v64, v65
	v_max3_f32 v83, v66, v67, v68
	v_max3_f32 v84, v84, v79, v69
	v_max3_f32 v80, v80, v81, v83
	v_max_f32_e32 v84, v84, v80
	v_mov_b32_e32 v79, v84
	s_nop 1
	v_permlane16_swap_b32_e32 v84, v79
	v_max_f32_e32 v84, v84, v79
	v_mov_b32_e32 v79, v84
	s_nop 1
	v_permlane32_swap_b32_e32 v84, v79
	v_max_f32_e32 v84, v84, v79
	v_cndmask_b32_e64 v84, v243, v84, s[24:25]
	v_max_f32_e32 v80, v93, v84
	v_max_f32_e32 v82, 0xe0ad78ec, v93
	v_max_f32_e32 v81, 0xe0ad78ec, v80
	v_sub_f32_e32 v82, v82, v81
	v_mov_b32_e32 v93, v80
	v_exp_f32_e32 v82, v82
	v_mov_b32_e32 v83, 0x7149f2ca
	v_cndmask_b32_e64 v83, v83, v81, s[24:25]
	v_sub_f32_e32 v54, v54, v83
	v_sub_f32_e32 v55, v55, v83
	v_sub_f32_e32 v56, v56, v83
	v_sub_f32_e32 v57, v57, v83
	v_exp_f32_e32 v54, v54
	v_exp_f32_e32 v55, v55
	v_exp_f32_e32 v56, v56
	v_exp_f32_e32 v57, v57
	v_sub_f32_e32 v58, v58, v83
	v_sub_f32_e32 v59, v59, v83
	v_sub_f32_e32 v60, v60, v83
	v_sub_f32_e32 v61, v61, v83
	v_exp_f32_e32 v58, v58
	v_exp_f32_e32 v59, v59
	v_exp_f32_e32 v60, v60
	v_exp_f32_e32 v61, v61
	v_sub_f32_e32 v62, v62, v83
	v_sub_f32_e32 v63, v63, v83
	v_sub_f32_e32 v64, v64, v83
	v_sub_f32_e32 v65, v65, v83
	v_exp_f32_e32 v62, v62
	v_exp_f32_e32 v63, v63
	v_exp_f32_e32 v64, v64
	v_exp_f32_e32 v65, v65
	v_sub_f32_e32 v66, v66, v83
	v_sub_f32_e32 v67, v67, v83
	v_sub_f32_e32 v68, v68, v83
	v_sub_f32_e32 v69, v69, v83
	v_exp_f32_e32 v66, v66
	v_exp_f32_e32 v67, v67
	v_exp_f32_e32 v68, v68
	v_exp_f32_e32 v69, v69
	s_nop 0
	v_add_f32_e32 v78, v54, v55
	v_add_f32_e32 v79, v56, v57
	v_add_f32_e32 v80, v58, v59
	v_add_f32_e32 v81, v60, v61
	v_add_f32_e32 v78, v78, v62
	v_add_f32_e32 v79, v79, v63
	v_add_f32_e32 v80, v80, v64
	v_add_f32_e32 v81, v81, v65
	v_add_f32_e32 v78, v78, v66
	v_add_f32_e32 v79, v79, v67
	v_add_f32_e32 v80, v80, v68
	v_add_f32_e32 v81, v81, v69
	v_add_f32_e32 v78, v78, v79
	v_add_f32_e32 v80, v80, v81
	v_add_f32_e32 v78, v78, v80
	v_cvt_pk_bf16_f32 v70, v54, v55
	v_cvt_pk_bf16_f32 v71, v56, v57
	v_cvt_pk_bf16_f32 v72, v58, v59
	v_cvt_pk_bf16_f32 v73, v60, v61
	v_cvt_pk_bf16_f32 v74, v62, v63
	v_cvt_pk_bf16_f32 v75, v64, v65
	v_cvt_pk_bf16_f32 v76, v66, v67
	v_cvt_pk_bf16_f32 v77, v68, v69
	v_mov_b32_e32 v79, v78
	s_nop 1
	v_permlane16_swap_b32_e32 v78, v79
	v_add_f32_e32 v78, v78, v79
	v_mov_b32_e32 v79, v78
	s_nop 1
	v_permlane32_swap_b32_e32 v78, v79
	v_add_f32_e32 v78, v78, v79
	v_fma_f32 v105, v105, v82, v78
	v_cmp_neq_f32_e64 s[4:5], 1.0, v82
	s_cmp_eq_u64 s[4:5], 0
	s_cbranch_scc1 .Lsl2_nosc_16
	v_pk_mul_f32 v[22:23], v[22:23], v[82:83] op_sel_hi:[1,0]
	v_pk_mul_f32 v[24:25], v[24:25], v[82:83] op_sel_hi:[1,0]
	v_pk_mul_f32 v[26:27], v[26:27], v[82:83] op_sel_hi:[1,0]
	v_pk_mul_f32 v[28:29], v[28:29], v[82:83] op_sel_hi:[1,0]
	v_pk_mul_f32 v[34:35], v[34:35], v[82:83] op_sel_hi:[1,0]
	v_pk_mul_f32 v[36:37], v[36:37], v[82:83] op_sel_hi:[1,0]
	v_pk_mul_f32 v[30:31], v[30:31], v[82:83] op_sel_hi:[1,0]
	v_pk_mul_f32 v[32:33], v[32:33], v[82:83] op_sel_hi:[1,0]

; #define LAS __attribute__((address_space(3)))
; template <int D, class SF>
; __device__ __forceinline__ void attn_step(const bf16x8 (&qf)[D / 32], const LAS bf16_t* Ks, const LAS bf16_t* Vt, f32x4 (&o)[D / 16], float& m, float& lsum, float& alpha_out, bf16x8& pf0_out, bf16x8& pf1_out, const int lane, SF sf) {
;     constexpr int KSTR = D + 8;
;     const int c = lane & 15, i = lane >> 4;
;     f32x4 s[4];
; #pragma unroll
;     for (int t = 0; t < 4; ++t) s[t] = (f32x4){0.f, 0.f, 0.f, 0.f};
; #pragma unroll
;     for (int ks = 0; ks < D / 32; ++ks) {
; #pragma unroll
;         for (int t = 0; t < 4; ++t) { const bf16x8 kf = *(const LAS bf16x8*)(Ks + (16 * t + c) * KSTR + ks * 32 + 8 * i); s[t] = mfma16(kf, qf[ks], s[t]); }
;     }
;     float v[16];
; #pragma unroll
;     for (int t = 0; t < 4; ++t)
; #pragma unroll
;         for (int r = 0; r < 4; ++r) v[4 * t + r] = sf(16 * t + 4 * i + r, s[t][r]);
;     float mx = fmaxf(fmaxf(fmaxf(v[0], v[1]), fmaxf(v[2], v[3])), fmaxf(fmaxf(v[4], v[5]), fmaxf(v[6], v[7])));
;     mx = fmaxf(mx, fmaxf(fmaxf(fmaxf(v[8], v[9]), fmaxf(v[10], v[11])), fmaxf(fmaxf(v[12], v[13]), fmaxf(v[14], v[15]))));
;     mx = rows_max(mx);
;     const float mnew = fmaxf(m, mx);
;     const float mc = fmaxf(mnew, -1e20f);
;     const float alpha = __builtin_amdgcn_exp2f(fmaxf(m, -1e20f) - mc);
;     float p[16], rs = 0.f;
; #pragma unroll
;     for (int r = 0; r < 16; ++r) { p[r] = __builtin_amdgcn_exp2f(v[r] - mc); rs += p[r]; }
;     rs = rows_sum(rs);
;     lsum = lsum * alpha + rs; m = mnew;
;     union { u32x4 u; bf16x8 b; } pk0, pk1;
;     pk0.u.x = cvt_pk_bf16(p[0], p[1]); pk0.u.y = cvt_pk_bf16(p[2], p[3]); pk0.u.z = cvt_pk_bf16(p[4], p[5]); pk0.u.w = cvt_pk_bf16(p[6], p[7]);
;     pk1.u.x = cvt_pk_bf16(p[8], p[9]); pk1.u.y = cvt_pk_bf16(p[10], p[11]); pk1.u.z = cvt_pk_bf16(p[12], p[13]); pk1.u.w = cvt_pk_bf16(p[14], p[15]);
;     if (__builtin_amdgcn_ballot_w64(alpha != 1.0f) != 0ull) {
; #pragma unroll
;         for (int dt = 0; dt < D / 16; ++dt) o[dt] *= alpha;
;     }
; #pragma unroll
;     for (int dt = 0; dt < D / 16; ++dt) {
;         const LAS bf16_t* vp = Vt + (16 * dt + c) * 72 + 4 * i;
;         union { u32x4 u; bf16x8 b; } vf0, vf1; const u32x2 a0 = *(const LAS u32x2*)vp, a1 = *(const LAS u32x2*)(vp + 16), b0 = *(const LAS u32x2*)(vp + 32), b1 = *(const LAS u32x2*)(vp + 48);
.Lsl2_diaga_8:
	v_lshrrev_b64 v[78:79], s20, v[18:19]
	v_and_b32_e32 v78, 1, v78
	v_cmp_eq_u32_e64 s[24:25], 1, v78
	s_cmp_eq_u64 s[24:25], 0
	s_cbranch_scc1 .Lsl2_skd_17
	v_sub_u32_e32 v78, v130, v139
	v_subrev_u32_e32 v78, s21, v78
	v_subrev_u32_e32 v107, 0, v78
	v_min_u32_e32 v107, 0x3ff, v107
	v_lshl_add_u32 v107, v107, 2, v131
	ds_read_b32 v107, v107
	v_subrev_u32_e32 v108, 1, v78
	v_min_u32_e32 v108, 0x3ff, v108
	v_lshl_add_u32 v108, v108, 2, v131
	ds_read_b32 v108, v108
	v_subrev_u32_e32 v109, 2, v78
	v_min_u32_e32 v109, 0x3ff, v109
	v_lshl_add_u32 v109, v109, 2, v131
	ds_read_b32 v109, v109
	v_subrev_u32_e32 v110, 3, v78
	v_min_u32_e32 v110, 0x3ff, v110
	v_lshl_add_u32 v110, v110, 2, v131
	ds_read_b32 v110, v110
	v_subrev_u32_e32 v111, 16, v78
	v_min_u32_e32 v111, 0x3ff, v111
	v_lshl_add_u32 v111, v111, 2, v131
	ds_read_b32 v111, v111
	v_subrev_u32_e32 v112, 17, v78
	v_min_u32_e32 v112, 0x3ff, v112
	v_lshl_add_u32 v112, v112, 2, v131
	ds_read_b32 v112, v112
	v_subrev_u32_e32 v113, 18, v78
	v_min_u32_e32 v113, 0x3ff, v113
	v_lshl_add_u32 v113, v113, 2, v131
	ds_read_b32 v113, v113
	v_subrev_u32_e32 v133, 19, v78
	v_min_u32_e32 v133, 0x3ff, v133
	v_lshl_add_u32 v133, v133, 2, v131
	ds_read_b32 v133, v133
	ds_read_b128 v[198:201], v102 offset:16384
	ds_read_b128 v[206:209], v102 offset:18688
	ds_read_b128 v[202:205], v102 offset:16448
	ds_read_b128 v[210:213], v102 offset:18752
	ds_read_b128 v[214:217], v102 offset:20992
	ds_read_b128 v[222:225], v102 offset:23296
	ds_read_b128 v[218:221], v102 offset:21056
	ds_read_b128 v[226:229], v102 offset:23360
	s_waitcnt lgkmcnt(6)
	v_mfma_f32_16x16x32_bf16 v[54:57], v[198:201], v[2:5], 0
	v_mfma_f32_16x16x32_bf16 v[58:61], v[206:209], v[2:5], 0
	s_waitcnt lgkmcnt(4)
	v_mfma_f32_16x16x32_bf16 v[54:57], v[202:205], v[6:9], v[54:57]
	v_mfma_f32_16x16x32_bf16 v[58:61], v[210:213], v[6:9], v[58:61]
	s_waitcnt lgkmcnt(2)
	v_mfma_f32_16x16x32_bf16 v[62:65], v[214:217], v[2:5], 0
	v_mfma_f32_16x16x32_bf16 v[66:69], v[222:225], v[2:5], 0
	s_waitcnt lgkmcnt(0)
	v_mfma_f32_16x16x32_bf16 v[62:65], v[218:221], v[6:9], v[62:65]
	v_mfma_f32_16x16x32_bf16 v[66:69], v[226:229], v[6:9], v[66:69]
	ds_read_b64_tr_b16 v[198:199], v104 offset:25600
	ds_read_b64_tr_b16 v[200:201], v104 offset:27904
	ds_read_b64_tr_b16 v[202:203], v104 offset:30208
	ds_read_b64_tr_b16 v[204:205], v104 offset:32512
	ds_read_b64_tr_b16 v[206:207], v104 offset:25632
	ds_read_b64_tr_b16 v[208:209], v104 offset:27936
	ds_read_b64_tr_b16 v[210:211], v104 offset:30240
	v_fmamk_f32 v54, v54, 0x3fb8aa3b, v107
	v_fmamk_f32 v55, v55, 0x3fb8aa3b, v108
	v_fmamk_f32 v56, v56, 0x3fb8aa3b, v109
	v_fmamk_f32 v57, v57, 0x3fb8aa3b, v110
	v_fmamk_f32 v58, v58, 0x3fb8aa3b, v111
	v_fmamk_f32 v59, v59, 0x3fb8aa3b, v112
	v_fmamk_f32 v60, v60, 0x3fb8aa3b, v113
	v_fmamk_f32 v61, v61, 0x3fb8aa3b, v133
	v_cmp_le_i32_e32 vcc, 0, v78
	s_nop 1
	v_cndmask_b32_e32 v54, v243, v54, vcc
	v_cmp_le_i32_e32 vcc, 1, v78
	s_nop 1
	v_cndmask_b32_e32 v55, v243, v55, vcc
	v_cmp_le_i32_e32 vcc, 2, v78
	s_nop 1
	v_cndmask_b32_e32 v56, v243, v56, vcc
	v_cmp_le_i32_e32 vcc, 3, v78
	s_nop 1
	v_cndmask_b32_e32 v57, v243, v57, vcc
	v_cmp_le_i32_e32 vcc, 16, v78
	s_nop 1
	v_cndmask_b32_e32 v58, v243, v58, vcc
	v_cmp_le_i32_e32 vcc, 17, v78
	s_nop 1
	v_cndmask_b32_e32 v59, v243, v59, vcc
	v_cmp_le_i32_e32 vcc, 18, v78
	s_nop 1
	v_cndmask_b32_e32 v60, v243, v60, vcc
	v_cmp_le_i32_e32 vcc, 19, v78
	s_nop 1
	v_cndmask_b32_e32 v61, v243, v61, vcc
	v_subrev_u32_e32 v107, 32, v78
	v_min_u32_e32 v107, 0x3ff, v107
	v_lshl_add_u32 v107, v107, 2, v131
	ds_read_b32 v107, v107
	v_subrev_u32_e32 v108, 33, v78
	v_min_u32_e32 v108, 0x3ff, v108
	v_lshl_add_u32 v108, v108, 2, v131
	ds_read_b32 v108, v108
	v_subrev_u32_e32 v109, 34, v78
	v_min_u32_e32 v109, 0x3ff, v109
	v_lshl_add_u32 v109, v109, 2, v131
	ds_read_b32 v109, v109
	v_subrev_u32_e32 v110, 35, v78
	v_min_u32_e32 v110, 0x3ff, v110
	v_lshl_add_u32 v110, v110, 2, v131
	ds_read_b32 v110, v110
	v_subrev_u32_e32 v111, 48, v78
	v_min_u32_e32 v111, 0x3ff, v111
	v_lshl_add_u32 v111, v111, 2, v131
	ds_read_b32 v111, v111
	v_subrev_u32_e32 v112, 49, v78
	v_min_u32_e32 v112, 0x3ff, v112
	v_lshl_add_u32 v112, v112, 2, v131
	ds_read_b32 v112, v112
	v_subrev_u32_e32 v113, 50, v78
	v_min_u32_e32 v113, 0x3ff, v113
	v_lshl_add_u32 v113, v113, 2, v131
	ds_read_b32 v113, v113
	v_subrev_u32_e32 v133, 51, v78
	v_min_u32_e32 v133, 0x3ff, v133
	v_lshl_add_u32 v133, v133, 2, v131
	ds_read_b32 v133, v133
	ds_read_b64_tr_b16 v[212:213], v104 offset:32544
	ds_read_b64_tr_b16 v[214:215], v104 offset:25664
	ds_read_b64_tr_b16 v[216:217], v104 offset:27968
	ds_read_b64_tr_b16 v[218:219], v104 offset:30272
	ds_read_b64_tr_b16 v[220:221], v104 offset:32576
	ds_read_b64_tr_b16 v[222:223], v104 offset:25696
	ds_read_b64_tr_b16 v[224:225], v104 offset:28000
	ds_read_b64_tr_b16 v[226:227], v104 offset:30304
	ds_read_b64_tr_b16 v[228:229], v104 offset:32608
	s_waitcnt lgkmcnt(9)
; #define LAS __attribute__((address_space(3)))
; template <int D, class SF>
; __device__ __forceinline__ void attn_step(const bf16x8 (&qf)[D / 32], const LAS bf16_t* Ks, const LAS bf16_t* Vt, f32x4 (&o)[D / 16], float& m, float& lsum, float& alpha_out, bf16x8& pf0_out, bf16x8& pf1_out, const int lane, SF sf) {
;     ...
;     for (int t = 0; t < 4; ++t)
; #pragma unroll
;         for (int r = 0; r < 4; ++r) v[4 * t + r] = sf(16 * t + 4 * i + r, s[t][r]);
;     float mx = fmaxf(fmaxf(fmaxf(v[0], v[1]), fmaxf(v[2], v[3])), fmaxf(fmaxf(v[4], v[5]), fmaxf(v[6], v[7])));
;     mx = fmaxf(mx, fmaxf(fmaxf(fmaxf(v[8], v[9]), fmaxf(v[10], v[11])), fmaxf(fmaxf(v[12], v[13]), fmaxf(v[14], v[15]))));
;     mx = rows_max(mx);
;     const float mnew = fmaxf(m, mx);
;     const float mc = fmaxf(mnew, -1e20f);
;     const float alpha = __builtin_amdgcn_exp2f(fmaxf(m, -1e20f) - mc);
;     float p[16], rs = 0.f;
; #pragma unroll
;     for (int r = 0; r < 16; ++r) { p[r] = __builtin_amdgcn_exp2f(v[r] - mc); rs += p[r]; }
;     rs = rows_sum(rs);
;     lsum = lsum * alpha + rs; m = mnew;
;     union { u32x4 u; bf16x8 b; } pk0, pk1;
;     pk0.u.x = cvt_pk_bf16(p[0], p[1]); pk0.u.y = cvt_pk_bf16(p[2], p[3]); pk0.u.z = cvt_pk_bf16(p[4], p[5]); pk0.u.w = cvt_pk_bf16(p[6], p[7]);
;     pk1.u.x = cvt_pk_bf16(p[8], p[9]); pk1.u.y = cvt_pk_bf16(p[10], p[11]); pk1.u.z = cvt_pk_bf16(p[12], p[13]); pk1.u.w = cvt_pk_bf16(p[14], p[15]);
;     if (__builtin_amdgcn_ballot_w64(alpha != 1.0f) != 0ull) {
; #pragma unroll
;         for (int dt = 0; dt < D / 16; ++dt) o[dt] *= alpha;
;     }
; #pragma unroll
;     for (int dt = 0; dt < D / 16; ++dt) {
;         const LAS bf16_t* vp = Vt + (16 * dt + c) * 72 + 4 * i;
;         union { u32x4 u; bf16x8 b; } vf0, vf1; const u32x2 a0 = *(const LAS u32x2*)vp, a1 = *(const LAS u32x2*)(vp + 16), b0 = *(const LAS u32x2*)(vp + 32), b1 = *(const LAS u32x2*)(vp + 48);
;         vf0.u.x = a0.x; vf0.u.y = a0.y; vf0.u.z = a1.x; vf0.u.w = a1.y; vf1.u.x = b0.x; vf1.u.y = b0.y; vf1.u.z = b1.x; vf1.u.w = b1.y;
;         o[dt] = mfma16(vf0.b, pk0.b, o[dt]); o[dt] = mfma16(vf1.b, pk1.b, o[dt]);
;     }
; __device__ __forceinline__ void nsa_unit(LAS unsigned char* lds, const Ctx& P, int l, int b, int hkv, int tb) {
;     ...
;                     } else { const int kp0 = j * 64;
;                         attn_step<64>(qf[sb], Ks, Vt, o[sb], m[sb], lsum[sb], alpha, pf, pf1, lane,
	v_fmamk_f32 v62, v62, 0x3fb8aa3b, v107
	v_fmamk_f32 v63, v63, 0x3fb8aa3b, v108
	v_fmamk_f32 v64, v64, 0x3fb8aa3b, v109
	v_fmamk_f32 v65, v65, 0x3fb8aa3b, v110
	v_fmamk_f32 v66, v66, 0x3fb8aa3b, v111
	v_fmamk_f32 v67, v67, 0x3fb8aa3b, v112
	v_fmamk_f32 v68, v68, 0x3fb8aa3b, v113
	v_fmamk_f32 v69, v69, 0x3fb8aa3b, v133
	v_cmp_le_i32_e32 vcc, 32, v78
	s_nop 1
	v_cndmask_b32_e32 v62, v243, v62, vcc
	v_cmp_le_i32_e32 vcc, 33, v78
	s_nop 1
	v_cndmask_b32_e32 v63, v243, v63, vcc
	v_cmp_le_i32_e32 vcc, 34, v78
	s_nop 1
	v_cndmask_b32_e32 v64, v243, v64, vcc
	v_cmp_le_i32_e32 vcc, 35, v78
	s_nop 1
	v_cndmask_b32_e32 v65, v243, v65, vcc
	v_cmp_le_i32_e32 vcc, 48, v78
	s_nop 1
	v_cndmask_b32_e32 v66, v243, v66, vcc
	v_cmp_le_i32_e32 vcc, 49, v78
	s_nop 1
	v_cndmask_b32_e32 v67, v243, v67, vcc
	v_cmp_le_i32_e32 vcc, 50, v78
	s_nop 1
	v_cndmask_b32_e32 v68, v243, v68, vcc
	v_cmp_le_i32_e32 vcc, 51, v78
	s_nop 1
	v_cndmask_b32_e32 v69, v243, v69, vcc
	v_max3_f32 v84, v54, v55, v56
	v_max3_f32 v79, v57, v58, v59
	v_max3_f32 v80, v60, v61, v62
	v_max3_f32 v81, v63, v64, v65
	v_max3_f32 v83, v66, v67, v68
	v_max3_f32 v84, v84, v79, v69
	v_max3_f32 v80, v80, v81, v83
	v_max_f32_e32 v84, v84, v80
	v_mov_b32_e32 v79, v84
	s_nop 1
	v_permlane16_swap_b32_e32 v84, v79
	v_max_f32_e32 v84, v84, v79
	v_mov_b32_e32 v79, v84
	s_nop 1
	v_permlane32_swap_b32_e32 v84, v79
	v_max_f32_e32 v84, v84, v79
	v_cndmask_b32_e64 v84, v243, v84, s[24:25]
	v_max_f32_e32 v80, v100, v84
	v_max_f32_e32 v82, 0xe0ad78ec, v100
	v_max_f32_e32 v81, 0xe0ad78ec, v80
	v_sub_f32_e32 v82, v82, v81
	v_mov_b32_e32 v100, v80
	v_exp_f32_e32 v82, v82
	v_mov_b32_e32 v83, 0x7149f2ca
	v_cndmask_b32_e64 v83, v83, v81, s[24:25]
	v_sub_f32_e32 v54, v54, v83
	v_sub_f32_e32 v55, v55, v83
	v_sub_f32_e32 v56, v56, v83
	v_sub_f32_e32 v57, v57, v83
	v_exp_f32_e32 v54, v54
	v_exp_f32_e32 v55, v55
	v_exp_f32_e32 v56, v56
	v_exp_f32_e32 v57, v57
	v_sub_f32_e32 v58, v58, v83
	v_sub_f32_e32 v59, v59, v83
	v_sub_f32_e32 v60, v60, v83
	v_sub_f32_e32 v61, v61, v83
	v_exp_f32_e32 v58, v58
	v_exp_f32_e32 v59, v59
	v_exp_f32_e32 v60, v60
	v_exp_f32_e32 v61, v61
	v_sub_f32_e32 v62, v62, v83
	v_sub_f32_e32 v63, v63, v83
	v_sub_f32_e32 v64, v64, v83
	v_sub_f32_e32 v65, v65, v83
	v_exp_f32_e32 v62, v62
	v_exp_f32_e32 v63, v63
	v_exp_f32_e32 v64, v64
	v_exp_f32_e32 v65, v65
	v_sub_f32_e32 v66, v66, v83
	v_sub_f32_e32 v67, v67, v83
	v_sub_f32_e32 v68, v68, v83
	v_sub_f32_e32 v69, v69, v83
	v_exp_f32_e32 v66, v66
	v_exp_f32_e32 v67, v67
	v_exp_f32_e32 v68, v68
	v_exp_f32_e32 v69, v69
	s_nop 0
	v_add_f32_e32 v78, v54, v55
	v_add_f32_e32 v79, v56, v57
	v_add_f32_e32 v80, v58, v59
	v_add_f32_e32 v81, v60, v61
	v_add_f32_e32 v78, v78, v62
	v_add_f32_e32 v79, v79, v63
	v_add_f32_e32 v80, v80, v64
	v_add_f32_e32 v81, v81, v65
	v_add_f32_e32 v78, v78, v66
	v_add_f32_e32 v79, v79, v67
	v_add_f32_e32 v80, v80, v68
	v_add_f32_e32 v81, v81, v69
	v_add_f32_e32 v78, v78, v79
	v_add_f32_e32 v80, v80, v81
	v_add_f32_e32 v78, v78, v80
	v_cvt_pk_bf16_f32 v70, v54, v55
	v_cvt_pk_bf16_f32 v71, v56, v57
	v_cvt_pk_bf16_f32 v72, v58, v59
	v_cvt_pk_bf16_f32 v73, v60, v61
	v_cvt_pk_bf16_f32 v74, v62, v63
	v_cvt_pk_bf16_f32 v75, v64, v65
	v_cvt_pk_bf16_f32 v76, v66, v67
	v_cvt_pk_bf16_f32 v77, v68, v69
	v_mov_b32_e32 v79, v78
	s_nop 1
	v_permlane16_swap_b32_e32 v78, v79
	v_add_f32_e32 v78, v78, v79
	v_mov_b32_e32 v79, v78
	s_nop 1
	v_permlane32_swap_b32_e32 v78, v79
	v_add_f32_e32 v78, v78, v79
	v_fma_f32 v106, v106, v82, v78
	v_cmp_neq_f32_e64 s[4:5], 1.0, v82
	s_cmp_eq_u64 s[4:5], 0
	s_cbranch_scc1 .Lsl2_nosc_18
	v_pk_mul_f32 v[38:39], v[38:39], v[82:83] op_sel_hi:[1,0]
	v_pk_mul_f32 v[40:41], v[40:41], v[82:83] op_sel_hi:[1,0]
	v_pk_mul_f32 v[42:43], v[42:43], v[82:83] op_sel_hi:[1,0]
	v_pk_mul_f32 v[44:45], v[44:45], v[82:83] op_sel_hi:[1,0]
	v_pk_mul_f32 v[46:47], v[46:47], v[82:83] op_sel_hi:[1,0]
	v_pk_mul_f32 v[48:49], v[48:49], v[82:83] op_sel_hi:[1,0]
	v_pk_mul_f32 v[50:51], v[50:51], v[82:83] op_sel_hi:[1,0]
	v_pk_mul_f32 v[52:53], v[52:53], v[82:83] op_sel_hi:[1,0]

; #define LAS __attribute__((address_space(3)))
; template <int D, class SF>
; __device__ __forceinline__ void attn_step(const bf16x8 (&qf)[D / 32], const LAS bf16_t* Ks, const LAS bf16_t* Vt, f32x4 (&o)[D / 16], float& m, float& lsum, float& alpha_out, bf16x8& pf0_out, bf16x8& pf1_out, const int lane, SF sf) {
;     constexpr int KSTR = D + 8;
;     const int c = lane & 15, i = lane >> 4;
;     f32x4 s[4];
; #pragma unroll
;     for (int t = 0; t < 4; ++t) s[t] = (f32x4){0.f, 0.f, 0.f, 0.f};
; #pragma unroll
;     for (int ks = 0; ks < D / 32; ++ks) {
; #pragma unroll
;         for (int t = 0; t < 4; ++t) { const bf16x8 kf = *(const LAS bf16x8*)(Ks + (16 * t + c) * KSTR + ks * 32 + 8 * i); s[t] = mfma16(kf, qf[ks], s[t]); }
;     }
;     float v[16];
; #pragma unroll
;     for (int t = 0; t < 4; ++t)
; #pragma unroll
;         for (int r = 0; r < 4; ++r) v[4 * t + r] = sf(16 * t + 4 * i + r, s[t][r]);
;     float mx = fmaxf(fmaxf(fmaxf(v[0], v[1]), fmaxf(v[2], v[3])), fmaxf(fmaxf(v[4], v[5]), fmaxf(v[6], v[7])));
;     mx = fmaxf(mx, fmaxf(fmaxf(fmaxf(v[8], v[9]), fmaxf(v[10], v[11])), fmaxf(fmaxf(v[12], v[13]), fmaxf(v[14], v[15]))));
;     mx = rows_max(mx);
;     const float mnew = fmaxf(m, mx);
;     const float mc = fmaxf(mnew, -1e20f);
;     const float alpha = __builtin_amdgcn_exp2f(fmaxf(m, -1e20f) - mc);
;     float p[16], rs = 0.f;
; #pragma unroll
;     for (int r = 0; r < 16; ++r) { p[r] = __builtin_amdgcn_exp2f(v[r] - mc); rs += p[r]; }
;     rs = rows_sum(rs);
;     lsum = lsum * alpha + rs; m = mnew;
;     union { u32x4 u; bf16x8 b; } pk0, pk1;
;     pk0.u.x = cvt_pk_bf16(p[0], p[1]); pk0.u.y = cvt_pk_bf16(p[2], p[3]); pk0.u.z = cvt_pk_bf16(p[4], p[5]); pk0.u.w = cvt_pk_bf16(p[6], p[7]);
;     pk1.u.x = cvt_pk_bf16(p[8], p[9]); pk1.u.y = cvt_pk_bf16(p[10], p[11]); pk1.u.z = cvt_pk_bf16(p[12], p[13]); pk1.u.w = cvt_pk_bf16(p[14], p[15]);
;     if (__builtin_amdgcn_ballot_w64(alpha != 1.0f) != 0ull) {
; #pragma unroll
;         for (int dt = 0; dt < D / 16; ++dt) o[dt] *= alpha;
;     }
; #pragma unroll
;     for (int dt = 0; dt < D / 16; ++dt) {
;         const LAS bf16_t* vp = Vt + (16 * dt + c) * 72 + 4 * i;
;         union { u32x4 u; bf16x8 b; } vf0, vf1; const u32x2 a0 = *(const LAS u32x2*)vp, a1 = *(const LAS u32x2*)(vp + 16), b0 = *(const LAS u32x2*)(vp + 32), b1 = *(const LAS u32x2*)(vp + 48);
.Lsl2_skd_17:
	v_lshrrev_b64 v[78:79], s20, v[20:21]
	v_and_b32_e32 v78, 1, v78
	v_cmp_eq_u32_e64 s[24:25], 1, v78
	s_cmp_eq_u64 s[24:25], 0
	s_cbranch_scc1 .Lsl2_skd_19
	v_sub_u32_e32 v78, v98, v139
	v_subrev_u32_e32 v78, s21, v78
	v_subrev_u32_e32 v107, 0, v78
	v_min_u32_e32 v107, 0x3ff, v107
	v_lshl_add_u32 v107, v107, 2, v131
	ds_read_b32 v107, v107
	v_subrev_u32_e32 v108, 1, v78
	v_min_u32_e32 v108, 0x3ff, v108
	v_lshl_add_u32 v108, v108, 2, v131
	ds_read_b32 v108, v108
	v_subrev_u32_e32 v109, 2, v78
	v_min_u32_e32 v109, 0x3ff, v109
	v_lshl_add_u32 v109, v109, 2, v131
	ds_read_b32 v109, v109
	v_subrev_u32_e32 v110, 3, v78
	v_min_u32_e32 v110, 0x3ff, v110
	v_lshl_add_u32 v110, v110, 2, v131
	ds_read_b32 v110, v110
	v_subrev_u32_e32 v111, 16, v78
	v_min_u32_e32 v111, 0x3ff, v111
	v_lshl_add_u32 v111, v111, 2, v131
	ds_read_b32 v111, v111
	v_subrev_u32_e32 v112, 17, v78
	v_min_u32_e32 v112, 0x3ff, v112
	v_lshl_add_u32 v112, v112, 2, v131
	ds_read_b32 v112, v112
	v_subrev_u32_e32 v113, 18, v78
	v_min_u32_e32 v113, 0x3ff, v113
	v_lshl_add_u32 v113, v113, 2, v131
	ds_read_b32 v113, v113
	v_subrev_u32_e32 v133, 19, v78
	v_min_u32_e32 v133, 0x3ff, v133
	v_lshl_add_u32 v133, v133, 2, v131
	ds_read_b32 v133, v133
	ds_read_b128 v[198:201], v102 offset:16384
	ds_read_b128 v[206:209], v102 offset:18688
	ds_read_b128 v[202:205], v102 offset:16448
	ds_read_b128 v[210:213], v102 offset:18752
	ds_read_b128 v[214:217], v102 offset:20992
	ds_read_b128 v[222:225], v102 offset:23296
	ds_read_b128 v[218:221], v102 offset:21056
	ds_read_b128 v[226:229], v102 offset:23360
	s_waitcnt lgkmcnt(6)
	v_mfma_f32_16x16x32_bf16 v[54:57], v[198:201], v[10:13], 0
	v_mfma_f32_16x16x32_bf16 v[58:61], v[206:209], v[10:13], 0
	s_waitcnt lgkmcnt(4)
	v_mfma_f32_16x16x32_bf16 v[54:57], v[202:205], v[14:17], v[54:57]
	v_mfma_f32_16x16x32_bf16 v[58:61], v[210:213], v[14:17], v[58:61]
	s_waitcnt lgkmcnt(2)
	v_mfma_f32_16x16x32_bf16 v[62:65], v[214:217], v[10:13], 0
	v_mfma_f32_16x16x32_bf16 v[66:69], v[222:225], v[10:13], 0
	s_waitcnt lgkmcnt(0)
	v_mfma_f32_16x16x32_bf16 v[62:65], v[218:221], v[14:17], v[62:65]
	v_mfma_f32_16x16x32_bf16 v[66:69], v[226:229], v[14:17], v[66:69]
	ds_read_b64_tr_b16 v[198:199], v104 offset:25600
	ds_read_b64_tr_b16 v[200:201], v104 offset:27904
	ds_read_b64_tr_b16 v[202:203], v104 offset:30208
	ds_read_b64_tr_b16 v[204:205], v104 offset:32512
	ds_read_b64_tr_b16 v[206:207], v104 offset:25632
	ds_read_b64_tr_b16 v[208:209], v104 offset:27936
	ds_read_b64_tr_b16 v[210:211], v104 offset:30240
	v_fmamk_f32 v54, v54, 0x3fb8aa3b, v107
	v_fmamk_f32 v55, v55, 0x3fb8aa3b, v108
	v_fmamk_f32 v56, v56, 0x3fb8aa3b, v109
	v_fmamk_f32 v57, v57, 0x3fb8aa3b, v110
	v_fmamk_f32 v58, v58, 0x3fb8aa3b, v111
	v_fmamk_f32 v59, v59, 0x3fb8aa3b, v112
	v_fmamk_f32 v60, v60, 0x3fb8aa3b, v113
	v_fmamk_f32 v61, v61, 0x3fb8aa3b, v133
	v_cmp_le_i32_e32 vcc, 0, v78
	s_nop 1
	v_cndmask_b32_e32 v54, v243, v54, vcc
	v_cmp_le_i32_e32 vcc, 1, v78
	s_nop 1
	v_cndmask_b32_e32 v55, v243, v55, vcc
	v_cmp_le_i32_e32 vcc, 2, v78
	s_nop 1
	v_cndmask_b32_e32 v56, v243, v56, vcc
	v_cmp_le_i32_e32 vcc, 3, v78
	s_nop 1
	v_cndmask_b32_e32 v57, v243, v57, vcc
	v_cmp_le_i32_e32 vcc, 16, v78
	s_nop 1
	v_cndmask_b32_e32 v58, v243, v58, vcc
	v_cmp_le_i32_e32 vcc, 17, v78
	s_nop 1
	v_cndmask_b32_e32 v59, v243, v59, vcc
	v_cmp_le_i32_e32 vcc, 18, v78
	s_nop 1
	v_cndmask_b32_e32 v60, v243, v60, vcc
	v_cmp_le_i32_e32 vcc, 19, v78
	s_nop 1
	v_cndmask_b32_e32 v61, v243, v61, vcc
	v_subrev_u32_e32 v107, 32, v78
	v_min_u32_e32 v107, 0x3ff, v107
	v_lshl_add_u32 v107, v107, 2, v131
	ds_read_b32 v107, v107
	v_subrev_u32_e32 v108, 33, v78
	v_min_u32_e32 v108, 0x3ff, v108
	v_lshl_add_u32 v108, v108, 2, v131
	ds_read_b32 v108, v108
	v_subrev_u32_e32 v109, 34, v78
	v_min_u32_e32 v109, 0x3ff, v109
	v_lshl_add_u32 v109, v109, 2, v131
	ds_read_b32 v109, v109
	v_subrev_u32_e32 v110, 35, v78
	v_min_u32_e32 v110, 0x3ff, v110
	v_lshl_add_u32 v110, v110, 2, v131
	ds_read_b32 v110, v110
	v_subrev_u32_e32 v111, 48, v78
	v_min_u32_e32 v111, 0x3ff, v111
	v_lshl_add_u32 v111, v111, 2, v131
	ds_read_b32 v111, v111
	v_subrev_u32_e32 v112, 49, v78
	v_min_u32_e32 v112, 0x3ff, v112
	v_lshl_add_u32 v112, v112, 2, v131
	ds_read_b32 v112, v112
	v_subrev_u32_e32 v113, 50, v78
	v_min_u32_e32 v113, 0x3ff, v113
	v_lshl_add_u32 v113, v113, 2, v131
	ds_read_b32 v113, v113
	v_subrev_u32_e32 v133, 51, v78
	v_min_u32_e32 v133, 0x3ff, v133
	v_lshl_add_u32 v133, v133, 2, v131
	ds_read_b32 v133, v133
	ds_read_b64_tr_b16 v[212:213], v104 offset:32544
	ds_read_b64_tr_b16 v[214:215], v104 offset:25664
	ds_read_b64_tr_b16 v[216:217], v104 offset:27968
	ds_read_b64_tr_b16 v[218:219], v104 offset:30272
	ds_read_b64_tr_b16 v[220:221], v104 offset:32576
	ds_read_b64_tr_b16 v[222:223], v104 offset:25696
	ds_read_b64_tr_b16 v[224:225], v104 offset:28000
	ds_read_b64_tr_b16 v[226:227], v104 offset:30304
	ds_read_b64_tr_b16 v[228:229], v104 offset:32608
	s_waitcnt lgkmcnt(9)
; #define LAS __attribute__((address_space(3)))
; template <int D, class SF>
; __device__ __forceinline__ void attn_step(const bf16x8 (&qf)[D / 32], const LAS bf16_t* Ks, const LAS bf16_t* Vt, f32x4 (&o)[D / 16], float& m, float& lsum, float& alpha_out, bf16x8& pf0_out, bf16x8& pf1_out, const int lane, SF sf) {
;     ...
;     for (int t = 0; t < 4; ++t)
; #pragma unroll
;         for (int r = 0; r < 4; ++r) v[4 * t + r] = sf(16 * t + 4 * i + r, s[t][r]);
;     float mx = fmaxf(fmaxf(fmaxf(v[0], v[1]), fmaxf(v[2], v[3])), fmaxf(fmaxf(v[4], v[5]), fmaxf(v[6], v[7])));
;     mx = fmaxf(mx, fmaxf(fmaxf(fmaxf(v[8], v[9]), fmaxf(v[10], v[11])), fmaxf(fmaxf(v[12], v[13]), fmaxf(v[14], v[15]))));
;     mx = rows_max(mx);
;     const float mnew = fmaxf(m, mx);
;     const float mc = fmaxf(mnew, -1e20f);
;     const float alpha = __builtin_amdgcn_exp2f(fmaxf(m, -1e20f) - mc);
;     float p[16], rs = 0.f;
; #pragma unroll
;     for (int r = 0; r < 16; ++r) { p[r] = __builtin_amdgcn_exp2f(v[r] - mc); rs += p[r]; }
;     rs = rows_sum(rs);
;     lsum = lsum * alpha + rs; m = mnew;
;     union { u32x4 u; bf16x8 b; } pk0, pk1;
;     pk0.u.x = cvt_pk_bf16(p[0], p[1]); pk0.u.y = cvt_pk_bf16(p[2], p[3]); pk0.u.z = cvt_pk_bf16(p[4], p[5]); pk0.u.w = cvt_pk_bf16(p[6], p[7]);
;     pk1.u.x = cvt_pk_bf16(p[8], p[9]); pk1.u.y = cvt_pk_bf16(p[10], p[11]); pk1.u.z = cvt_pk_bf16(p[12], p[13]); pk1.u.w = cvt_pk_bf16(p[14], p[15]);
;     if (__builtin_amdgcn_ballot_w64(alpha != 1.0f) != 0ull) {
; #pragma unroll
;         for (int dt = 0; dt < D / 16; ++dt) o[dt] *= alpha;
;     }
; #pragma unroll
;     for (int dt = 0; dt < D / 16; ++dt) {
;         const LAS bf16_t* vp = Vt + (16 * dt + c) * 72 + 4 * i;
;         union { u32x4 u; bf16x8 b; } vf0, vf1; const u32x2 a0 = *(const LAS u32x2*)vp, a1 = *(const LAS u32x2*)(vp + 16), b0 = *(const LAS u32x2*)(vp + 32), b1 = *(const LAS u32x2*)(vp + 48);
;         vf0.u.x = a0.x; vf0.u.y = a0.y; vf0.u.z = a1.x; vf0.u.w = a1.y; vf1.u.x = b0.x; vf1.u.y = b0.y; vf1.u.z = b1.x; vf1.u.w = b1.y;
;         o[dt] = mfma16(vf0.b, pk0.b, o[dt]); o[dt] = mfma16(vf1.b, pk1.b, o[dt]);
;     }
; __device__ __forceinline__ void nsa_unit(LAS unsigned char* lds, const Ctx& P, int l, int b, int hkv, int tb) {
;     ...
;                     } else { const int kp0 = j * 64;
;                         attn_step<64>(qf[sb], Ks, Vt, o[sb], m[sb], lsum[sb], alpha, pf, pf1, lane,
	v_fmamk_f32 v62, v62, 0x3fb8aa3b, v107
	v_fmamk_f32 v63, v63, 0x3fb8aa3b, v108
	v_fmamk_f32 v64, v64, 0x3fb8aa3b, v109
	v_fmamk_f32 v65, v65, 0x3fb8aa3b, v110
	v_fmamk_f32 v66, v66, 0x3fb8aa3b, v111
	v_fmamk_f32 v67, v67, 0x3fb8aa3b, v112
	v_fmamk_f32 v68, v68, 0x3fb8aa3b, v113
	v_fmamk_f32 v69, v69, 0x3fb8aa3b, v133
	v_cmp_le_i32_e32 vcc, 32, v78
	s_nop 1
	v_cndmask_b32_e32 v62, v243, v62, vcc
	v_cmp_le_i32_e32 vcc, 33, v78
	s_nop 1
	v_cndmask_b32_e32 v63, v243, v63, vcc
	v_cmp_le_i32_e32 vcc, 34, v78
	s_nop 1
	v_cndmask_b32_e32 v64, v243, v64, vcc
	v_cmp_le_i32_e32 vcc, 35, v78
	s_nop 1
	v_cndmask_b32_e32 v65, v243, v65, vcc
	v_cmp_le_i32_e32 vcc, 48, v78
	s_nop 1
	v_cndmask_b32_e32 v66, v243, v66, vcc
	v_cmp_le_i32_e32 vcc, 49, v78
	s_nop 1
	v_cndmask_b32_e32 v67, v243, v67, vcc
	v_cmp_le_i32_e32 vcc, 50, v78
	s_nop 1
	v_cndmask_b32_e32 v68, v243, v68, vcc
	v_cmp_le_i32_e32 vcc, 51, v78
	s_nop 1
	v_cndmask_b32_e32 v69, v243, v69, vcc
	v_max3_f32 v84, v54, v55, v56
	v_max3_f32 v79, v57, v58, v59
	v_max3_f32 v80, v60, v61, v62
	v_max3_f32 v81, v63, v64, v65
	v_max3_f32 v83, v66, v67, v68
	v_max3_f32 v84, v84, v79, v69
	v_max3_f32 v80, v80, v81, v83
	v_max_f32_e32 v84, v84, v80
	v_mov_b32_e32 v79, v84
	s_nop 1
	v_permlane16_swap_b32_e32 v84, v79
	v_max_f32_e32 v84, v84, v79
	v_mov_b32_e32 v79, v84
	s_nop 1
	v_permlane32_swap_b32_e32 v84, v79
	v_max_f32_e32 v84, v84, v79
	v_cndmask_b32_e64 v84, v243, v84, s[24:25]
	v_max_f32_e32 v80, v93, v84
	v_max_f32_e32 v82, 0xe0ad78ec, v93
	v_max_f32_e32 v81, 0xe0ad78ec, v80
	v_sub_f32_e32 v82, v82, v81
	v_mov_b32_e32 v93, v80
	v_exp_f32_e32 v82, v82
	v_mov_b32_e32 v83, 0x7149f2ca
	v_cndmask_b32_e64 v83, v83, v81, s[24:25]
	v_sub_f32_e32 v54, v54, v83
	v_sub_f32_e32 v55, v55, v83
	v_sub_f32_e32 v56, v56, v83
	v_sub_f32_e32 v57, v57, v83
	v_exp_f32_e32 v54, v54
	v_exp_f32_e32 v55, v55
	v_exp_f32_e32 v56, v56
	v_exp_f32_e32 v57, v57
	v_sub_f32_e32 v58, v58, v83
	v_sub_f32_e32 v59, v59, v83
	v_sub_f32_e32 v60, v60, v83
	v_sub_f32_e32 v61, v61, v83
	v_exp_f32_e32 v58, v58
	v_exp_f32_e32 v59, v59
	v_exp_f32_e32 v60, v60
	v_exp_f32_e32 v61, v61
	v_sub_f32_e32 v62, v62, v83
	v_sub_f32_e32 v63, v63, v83
	v_sub_f32_e32 v64, v64, v83
	v_sub_f32_e32 v65, v65, v83
	v_exp_f32_e32 v62, v62
	v_exp_f32_e32 v63, v63
	v_exp_f32_e32 v64, v64
	v_exp_f32_e32 v65, v65
	v_sub_f32_e32 v66, v66, v83
	v_sub_f32_e32 v67, v67, v83
	v_sub_f32_e32 v68, v68, v83
	v_sub_f32_e32 v69, v69, v83
	v_exp_f32_e32 v66, v66
	v_exp_f32_e32 v67, v67
	v_exp_f32_e32 v68, v68
	v_exp_f32_e32 v69, v69
	s_nop 0
	v_add_f32_e32 v78, v54, v55
	v_add_f32_e32 v79, v56, v57
	v_add_f32_e32 v80, v58, v59
	v_add_f32_e32 v81, v60, v61
	v_add_f32_e32 v78, v78, v62
	v_add_f32_e32 v79, v79, v63
	v_add_f32_e32 v80, v80, v64
	v_add_f32_e32 v81, v81, v65
	v_add_f32_e32 v78, v78, v66
	v_add_f32_e32 v79, v79, v67
	v_add_f32_e32 v80, v80, v68
	v_add_f32_e32 v81, v81, v69
	v_add_f32_e32 v78, v78, v79
	v_add_f32_e32 v80, v80, v81
	v_add_f32_e32 v78, v78, v80
	v_cvt_pk_bf16_f32 v70, v54, v55
	v_cvt_pk_bf16_f32 v71, v56, v57
	v_cvt_pk_bf16_f32 v72, v58, v59
	v_cvt_pk_bf16_f32 v73, v60, v61
	v_cvt_pk_bf16_f32 v74, v62, v63
	v_cvt_pk_bf16_f32 v75, v64, v65
	v_cvt_pk_bf16_f32 v76, v66, v67
	v_cvt_pk_bf16_f32 v77, v68, v69
	v_mov_b32_e32 v79, v78
	s_nop 1
	v_permlane16_swap_b32_e32 v78, v79
	v_add_f32_e32 v78, v78, v79
	v_mov_b32_e32 v79, v78
	s_nop 1
	v_permlane32_swap_b32_e32 v78, v79
	v_add_f32_e32 v78, v78, v79
	v_fma_f32 v105, v105, v82, v78
	v_cmp_neq_f32_e64 s[4:5], 1.0, v82
	s_cmp_eq_u64 s[4:5], 0
	s_cbranch_scc1 .Lsl2_nosc_20
	v_pk_mul_f32 v[22:23], v[22:23], v[82:83] op_sel_hi:[1,0]
	v_pk_mul_f32 v[24:25], v[24:25], v[82:83] op_sel_hi:[1,0]
	v_pk_mul_f32 v[26:27], v[26:27], v[82:83] op_sel_hi:[1,0]
	v_pk_mul_f32 v[28:29], v[28:29], v[82:83] op_sel_hi:[1,0]
	v_pk_mul_f32 v[34:35], v[34:35], v[82:83] op_sel_hi:[1,0]
	v_pk_mul_f32 v[36:37], v[36:37], v[82:83] op_sel_hi:[1,0]
	v_pk_mul_f32 v[30:31], v[30:31], v[82:83] op_sel_hi:[1,0]
	v_pk_mul_f32 v[32:33], v[32:33], v[82:83] op_sel_hi:[1,0]

; #define LAS __attribute__((address_space(3)))
; template <int D, class SF>
; __device__ __forceinline__ void attn_step(const bf16x8 (&qf)[D / 32], const LAS bf16_t* Ks, const LAS bf16_t* Vt, f32x4 (&o)[D / 16], float& m, float& lsum, float& alpha_out, bf16x8& pf0_out, bf16x8& pf1_out, const int lane, SF sf) {
;     constexpr int KSTR = D + 8;
;     const int c = lane & 15, i = lane >> 4;
;     f32x4 s[4];
; #pragma unroll
;     for (int t = 0; t < 4; ++t) s[t] = (f32x4){0.f, 0.f, 0.f, 0.f};
; #pragma unroll
;     for (int ks = 0; ks < D / 32; ++ks) {
; #pragma unroll
;         for (int t = 0; t < 4; ++t) { const bf16x8 kf = *(const LAS bf16x8*)(Ks + (16 * t + c) * KSTR + ks * 32 + 8 * i); s[t] = mfma16(kf, qf[ks], s[t]); }
;     }
;     float v[16];
; #pragma unroll
;     for (int t = 0; t < 4; ++t)
; #pragma unroll
;         for (int r = 0; r < 4; ++r) v[4 * t + r] = sf(16 * t + 4 * i + r, s[t][r]);
;     float mx = fmaxf(fmaxf(fmaxf(v[0], v[1]), fmaxf(v[2], v[3])), fmaxf(fmaxf(v[4], v[5]), fmaxf(v[6], v[7])));
;     mx = fmaxf(mx, fmaxf(fmaxf(fmaxf(v[8], v[9]), fmaxf(v[10], v[11])), fmaxf(fmaxf(v[12], v[13]), fmaxf(v[14], v[15]))));
;     mx = rows_max(mx);
;     const float mnew = fmaxf(m, mx);
;     const float mc = fmaxf(mnew, -1e20f);
;     const float alpha = __builtin_amdgcn_exp2f(fmaxf(m, -1e20f) - mc);
;     float p[16], rs = 0.f;
; #pragma unroll
;     for (int r = 0; r < 16; ++r) { p[r] = __builtin_amdgcn_exp2f(v[r] - mc); rs += p[r]; }
;     rs = rows_sum(rs);
;     lsum = lsum * alpha + rs; m = mnew;
;     union { u32x4 u; bf16x8 b; } pk0, pk1;
;     pk0.u.x = cvt_pk_bf16(p[0], p[1]); pk0.u.y = cvt_pk_bf16(p[2], p[3]); pk0.u.z = cvt_pk_bf16(p[4], p[5]); pk0.u.w = cvt_pk_bf16(p[6], p[7]);
;     pk1.u.x = cvt_pk_bf16(p[8], p[9]); pk1.u.y = cvt_pk_bf16(p[10], p[11]); pk1.u.z = cvt_pk_bf16(p[12], p[13]); pk1.u.w = cvt_pk_bf16(p[14], p[15]);
;     if (__builtin_amdgcn_ballot_w64(alpha != 1.0f) != 0ull) {
; #pragma unroll
;         for (int dt = 0; dt < D / 16; ++dt) o[dt] *= alpha;
;     }
; #pragma unroll
;     for (int dt = 0; dt < D / 16; ++dt) {
;         const LAS bf16_t* vp = Vt + (16 * dt + c) * 72 + 4 * i;
;         union { u32x4 u; bf16x8 b; } vf0, vf1; const u32x2 a0 = *(const LAS u32x2*)vp, a1 = *(const LAS u32x2*)(vp + 16), b0 = *(const LAS u32x2*)(vp + 32), b1 = *(const LAS u32x2*)(vp + 48);
.Lsl2_skd_19:
.Lsl2_donea_6:
	s_cmp_eq_u32 s12, 0
	s_cbranch_scc1 .Lsl2_skipb_21
	s_sub_i32 s4, s19, s9
	s_cmp_lt_i32 s4, 0
	s_cbranch_scc1 .Lsl2_diagb_24
	s_cmpk_lt_i32 s4, 0x316
	s_cbranch_scc1 .Lsl2_nearb_23
	v_lshrrev_b64 v[78:79], s8, v[18:19]
	v_and_b32_e32 v78, 1, v78
	v_cmp_eq_u32_e64 s[24:25], 1, v78
	s_cmp_eq_u64 s[24:25], 0
	s_cbranch_scc1 .Lsl2_skf_25
	ds_read_b128 v[198:201], v102 offset:34816
	ds_read_b128 v[206:209], v102 offset:37120
	ds_read_b128 v[202:205], v102 offset:34880
	ds_read_b128 v[210:213], v102 offset:37184
	ds_read_b128 v[214:217], v102 offset:39424
	ds_read_b128 v[222:225], v102 offset:41728
	ds_read_b128 v[218:221], v102 offset:39488
	ds_read_b128 v[226:229], v102 offset:41792
	s_waitcnt lgkmcnt(6)
	v_mfma_f32_16x16x32_bf16 v[54:57], v[198:201], v[2:5], 0
	v_mfma_f32_16x16x32_bf16 v[58:61], v[206:209], v[2:5], 0
	s_waitcnt lgkmcnt(4)
	v_mfma_f32_16x16x32_bf16 v[54:57], v[202:205], v[6:9], v[54:57]
	v_mfma_f32_16x16x32_bf16 v[58:61], v[210:213], v[6:9], v[58:61]
	s_waitcnt lgkmcnt(2)
	v_mfma_f32_16x16x32_bf16 v[62:65], v[214:217], v[2:5], 0
	v_mfma_f32_16x16x32_bf16 v[66:69], v[222:225], v[2:5], 0
	s_waitcnt lgkmcnt(0)
	v_mfma_f32_16x16x32_bf16 v[62:65], v[218:221], v[6:9], v[62:65]
	v_mfma_f32_16x16x32_bf16 v[66:69], v[226:229], v[6:9], v[66:69]
	ds_read_b64_tr_b16 v[198:199], v104 offset:44032
	ds_read_b64_tr_b16 v[200:201], v104 offset:46336
	ds_read_b64_tr_b16 v[202:203], v104 offset:48640
	ds_read_b64_tr_b16 v[204:205], v104 offset:50944
	ds_read_b64_tr_b16 v[206:207], v104 offset:44064
	ds_read_b64_tr_b16 v[208:209], v104 offset:46368
	ds_read_b64_tr_b16 v[210:211], v104 offset:48672
	ds_read_b64_tr_b16 v[212:213], v104 offset:50976
	ds_read_b64_tr_b16 v[214:215], v104 offset:44096
	ds_read_b64_tr_b16 v[216:217], v104 offset:46400
	ds_read_b64_tr_b16 v[218:219], v104 offset:48704
	ds_read_b64_tr_b16 v[220:221], v104 offset:51008
	ds_read_b64_tr_b16 v[222:223], v104 offset:44128
	ds_read_b64_tr_b16 v[224:225], v104 offset:46432
	ds_read_b64_tr_b16 v[226:227], v104 offset:48736
	ds_read_b64_tr_b16 v[228:229], v104 offset:51040
	v_max3_f32 v78, v54, v55, v56
	v_max3_f32 v79, v57, v58, v59
	v_max3_f32 v80, v60, v61, v62
	v_max3_f32 v81, v63, v64, v65
	v_max3_f32 v83, v66, v67, v68
	v_max3_f32 v78, v78, v79, v69
	v_max3_f32 v80, v80, v81, v83
	v_max_f32_e32 v78, v78, v80
	v_mov_b32_e32 v79, v78
	s_nop 1
	v_permlane16_swap_b32_e32 v78, v79
	v_max_f32_e32 v78, v78, v79
	v_mov_b32_e32 v79, v78
	s_nop 1
	v_permlane32_swap_b32_e32 v78, v79
	v_max_f32_e32 v78, v78, v79
	v_fmamk_f32 v78, v78, 0x3fb8aa3b, v92
	v_cndmask_b32_e64 v78, v243, v78, s[24:25]
	v_max_f32_e32 v80, v100, v78
	v_max_f32_e32 v82, 0xe0ad78ec, v100
	v_max_f32_e32 v81, 0xe0ad78ec, v80
	v_sub_f32_e32 v82, v82, v81
	v_mov_b32_e32 v100, v80
	v_exp_f32_e32 v82, v82
	v_sub_f32_e32 v83, v92, v81
	v_cndmask_b32_e64 v83, v243, v83, s[24:25]
	v_fmamk_f32 v54, v54, 0x3fb8aa3b, v83
	v_fmamk_f32 v55, v55, 0x3fb8aa3b, v83
	v_fmamk_f32 v56, v56, 0x3fb8aa3b, v83
	v_fmamk_f32 v57, v57, 0x3fb8aa3b, v83
	v_exp_f32_e32 v54, v54
	v_exp_f32_e32 v55, v55
	v_exp_f32_e32 v56, v56
	v_exp_f32_e32 v57, v57
	v_fmamk_f32 v58, v58, 0x3fb8aa3b, v83
	v_fmamk_f32 v59, v59, 0x3fb8aa3b, v83
	v_fmamk_f32 v60, v60, 0x3fb8aa3b, v83
	v_fmamk_f32 v61, v61, 0x3fb8aa3b, v83
	v_exp_f32_e32 v58, v58
	v_exp_f32_e32 v59, v59
	v_exp_f32_e32 v60, v60
	v_exp_f32_e32 v61, v61
	v_fmamk_f32 v62, v62, 0x3fb8aa3b, v83
	v_fmamk_f32 v63, v63, 0x3fb8aa3b, v83
	v_fmamk_f32 v64, v64, 0x3fb8aa3b, v83
	v_fmamk_f32 v65, v65, 0x3fb8aa3b, v83
	v_exp_f32_e32 v62, v62
	v_exp_f32_e32 v63, v63
	v_exp_f32_e32 v64, v64
	v_exp_f32_e32 v65, v65
	v_fmamk_f32 v66, v66, 0x3fb8aa3b, v83
	v_fmamk_f32 v67, v67, 0x3fb8aa3b, v83
	v_fmamk_f32 v68, v68, 0x3fb8aa3b, v83
	v_fmamk_f32 v69, v69, 0x3fb8aa3b, v83
	v_exp_f32_e32 v66, v66
	v_exp_f32_e32 v67, v67
	v_exp_f32_e32 v68, v68
	v_exp_f32_e32 v69, v69
	s_nop 0
	v_add_f32_e32 v78, v54, v55
	v_add_f32_e32 v79, v56, v57
	v_add_f32_e32 v80, v58, v59
	v_add_f32_e32 v81, v60, v61
	v_add_f32_e32 v78, v78, v62
	v_add_f32_e32 v79, v79, v63
	v_add_f32_e32 v80, v80, v64
	v_add_f32_e32 v81, v81, v65
	v_add_f32_e32 v78, v78, v66
	v_add_f32_e32 v79, v79, v67
	v_add_f32_e32 v80, v80, v68
	v_add_f32_e32 v81, v81, v69
	v_add_f32_e32 v78, v78, v79
	v_add_f32_e32 v80, v80, v81
	v_add_f32_e32 v78, v78, v80
	v_cvt_pk_bf16_f32 v70, v54, v55
	v_cvt_pk_bf16_f32 v71, v56, v57
	v_cvt_pk_bf16_f32 v72, v58, v59
	v_cvt_pk_bf16_f32 v73, v60, v61
	v_cvt_pk_bf16_f32 v74, v62, v63
	v_cvt_pk_bf16_f32 v75, v64, v65
	v_cvt_pk_bf16_f32 v76, v66, v67
	v_cvt_pk_bf16_f32 v77, v68, v69
	v_mov_b32_e32 v79, v78
	s_nop 1
	v_permlane16_swap_b32_e32 v78, v79
	v_add_f32_e32 v78, v78, v79
	v_mov_b32_e32 v79, v78
	s_nop 1
	v_permlane32_swap_b32_e32 v78, v79
	v_add_f32_e32 v78, v78, v79
	v_fma_f32 v106, v106, v82, v78
	v_cmp_neq_f32_e64 s[4:5], 1.0, v82
	s_cmp_eq_u64 s[4:5], 0
	s_cbranch_scc1 .Lsl2_nosc_26
	v_pk_mul_f32 v[38:39], v[38:39], v[82:83] op_sel_hi:[1,0]
	v_pk_mul_f32 v[40:41], v[40:41], v[82:83] op_sel_hi:[1,0]
	v_pk_mul_f32 v[42:43], v[42:43], v[82:83] op_sel_hi:[1,0]
	v_pk_mul_f32 v[44:45], v[44:45], v[82:83] op_sel_hi:[1,0]
	v_pk_mul_f32 v[46:47], v[46:47], v[82:83] op_sel_hi:[1,0]
	v_pk_mul_f32 v[48:49], v[48:49], v[82:83] op_sel_hi:[1,0]
	v_pk_mul_f32 v[50:51], v[50:51], v[82:83] op_sel_hi:[1,0]
	v_pk_mul_f32 v[52:53], v[52:53], v[82:83] op_sel_hi:[1,0]

; #define LAS __attribute__((address_space(3)))
; template <int D, class SF>
; __device__ __forceinline__ void attn_step(const bf16x8 (&qf)[D / 32], const LAS bf16_t* Ks, const LAS bf16_t* Vt, f32x4 (&o)[D / 16], float& m, float& lsum, float& alpha_out, bf16x8& pf0_out, bf16x8& pf1_out, const int lane, SF sf) {
;     constexpr int KSTR = D + 8;
;     const int c = lane & 15, i = lane >> 4;
;     f32x4 s[4];
; #pragma unroll
;     for (int t = 0; t < 4; ++t) s[t] = (f32x4){0.f, 0.f, 0.f, 0.f};
; #pragma unroll
;     for (int ks = 0; ks < D / 32; ++ks) {
; #pragma unroll
;         for (int t = 0; t < 4; ++t) { const bf16x8 kf = *(const LAS bf16x8*)(Ks + (16 * t + c) * KSTR + ks * 32 + 8 * i); s[t] = mfma16(kf, qf[ks], s[t]); }
;     }
;     float v[16];
; #pragma unroll
;     for (int t = 0; t < 4; ++t)
; #pragma unroll
;         for (int r = 0; r < 4; ++r) v[4 * t + r] = sf(16 * t + 4 * i + r, s[t][r]);
;     float mx = fmaxf(fmaxf(fmaxf(v[0], v[1]), fmaxf(v[2], v[3])), fmaxf(fmaxf(v[4], v[5]), fmaxf(v[6], v[7])));
;     mx = fmaxf(mx, fmaxf(fmaxf(fmaxf(v[8], v[9]), fmaxf(v[10], v[11])), fmaxf(fmaxf(v[12], v[13]), fmaxf(v[14], v[15]))));
;     mx = rows_max(mx);
;     const float mnew = fmaxf(m, mx);
;     const float mc = fmaxf(mnew, -1e20f);
;     const float alpha = __builtin_amdgcn_exp2f(fmaxf(m, -1e20f) - mc);
;     float p[16], rs = 0.f;
; #pragma unroll
;     for (int r = 0; r < 16; ++r) { p[r] = __builtin_amdgcn_exp2f(v[r] - mc); rs += p[r]; }
;     rs = rows_sum(rs);
;     lsum = lsum * alpha + rs; m = mnew;
;     union { u32x4 u; bf16x8 b; } pk0, pk1;
;     pk0.u.x = cvt_pk_bf16(p[0], p[1]); pk0.u.y = cvt_pk_bf16(p[2], p[3]); pk0.u.z = cvt_pk_bf16(p[4], p[5]); pk0.u.w = cvt_pk_bf16(p[6], p[7]);
;     pk1.u.x = cvt_pk_bf16(p[8], p[9]); pk1.u.y = cvt_pk_bf16(p[10], p[11]); pk1.u.z = cvt_pk_bf16(p[12], p[13]); pk1.u.w = cvt_pk_bf16(p[14], p[15]);
;     if (__builtin_amdgcn_ballot_w64(alpha != 1.0f) != 0ull) {
; #pragma unroll
;         for (int dt = 0; dt < D / 16; ++dt) o[dt] *= alpha;
;     }
; #pragma unroll
;     for (int dt = 0; dt < D / 16; ++dt) {
;         const LAS bf16_t* vp = Vt + (16 * dt + c) * 72 + 4 * i;
;         union { u32x4 u; bf16x8 b; } vf0, vf1; const u32x2 a0 = *(const LAS u32x2*)vp, a1 = *(const LAS u32x2*)(vp + 16), b0 = *(const LAS u32x2*)(vp + 32), b1 = *(const LAS u32x2*)(vp + 48);
.Lsl2_skf_25:
	v_lshrrev_b64 v[78:79], s8, v[20:21]
	v_and_b32_e32 v78, 1, v78
	v_cmp_eq_u32_e64 s[24:25], 1, v78
	s_cmp_eq_u64 s[24:25], 0
	s_cbranch_scc1 .Lsl2_skf_27
	ds_read_b128 v[198:201], v102 offset:34816
	ds_read_b128 v[206:209], v102 offset:37120
	ds_read_b128 v[202:205], v102 offset:34880
	ds_read_b128 v[210:213], v102 offset:37184
	ds_read_b128 v[214:217], v102 offset:39424
	ds_read_b128 v[222:225], v102 offset:41728
	ds_read_b128 v[218:221], v102 offset:39488
	ds_read_b128 v[226:229], v102 offset:41792
	s_waitcnt lgkmcnt(6)
	v_mfma_f32_16x16x32_bf16 v[54:57], v[198:201], v[10:13], 0
	v_mfma_f32_16x16x32_bf16 v[58:61], v[206:209], v[10:13], 0
	s_waitcnt lgkmcnt(4)
	v_mfma_f32_16x16x32_bf16 v[54:57], v[202:205], v[14:17], v[54:57]
	v_mfma_f32_16x16x32_bf16 v[58:61], v[210:213], v[14:17], v[58:61]
	s_waitcnt lgkmcnt(2)
	v_mfma_f32_16x16x32_bf16 v[62:65], v[214:217], v[10:13], 0
	v_mfma_f32_16x16x32_bf16 v[66:69], v[222:225], v[10:13], 0
	s_waitcnt lgkmcnt(0)
	v_mfma_f32_16x16x32_bf16 v[62:65], v[218:221], v[14:17], v[62:65]
	v_mfma_f32_16x16x32_bf16 v[66:69], v[226:229], v[14:17], v[66:69]
	ds_read_b64_tr_b16 v[198:199], v104 offset:44032
	ds_read_b64_tr_b16 v[200:201], v104 offset:46336
	ds_read_b64_tr_b16 v[202:203], v104 offset:48640
	ds_read_b64_tr_b16 v[204:205], v104 offset:50944
	ds_read_b64_tr_b16 v[206:207], v104 offset:44064
	ds_read_b64_tr_b16 v[208:209], v104 offset:46368
	ds_read_b64_tr_b16 v[210:211], v104 offset:48672
	ds_read_b64_tr_b16 v[212:213], v104 offset:50976
	ds_read_b64_tr_b16 v[214:215], v104 offset:44096
	ds_read_b64_tr_b16 v[216:217], v104 offset:46400
	ds_read_b64_tr_b16 v[218:219], v104 offset:48704
	ds_read_b64_tr_b16 v[220:221], v104 offset:51008
	ds_read_b64_tr_b16 v[222:223], v104 offset:44128
	ds_read_b64_tr_b16 v[224:225], v104 offset:46432
	ds_read_b64_tr_b16 v[226:227], v104 offset:48736
	ds_read_b64_tr_b16 v[228:229], v104 offset:51040
	v_max3_f32 v78, v54, v55, v56
	v_max3_f32 v79, v57, v58, v59
	v_max3_f32 v80, v60, v61, v62
	v_max3_f32 v81, v63, v64, v65
	v_max3_f32 v83, v66, v67, v68
	v_max3_f32 v78, v78, v79, v69
	v_max3_f32 v80, v80, v81, v83
	v_max_f32_e32 v78, v78, v80
	v_mov_b32_e32 v79, v78
	s_nop 1
	v_permlane16_swap_b32_e32 v78, v79
	v_max_f32_e32 v78, v78, v79
	v_mov_b32_e32 v79, v78
	s_nop 1
	v_permlane32_swap_b32_e32 v78, v79
	v_max_f32_e32 v78, v78, v79
	v_fmamk_f32 v78, v78, 0x3fb8aa3b, v92
	v_cndmask_b32_e64 v78, v243, v78, s[24:25]
	v_max_f32_e32 v80, v93, v78
	v_max_f32_e32 v82, 0xe0ad78ec, v93
	v_max_f32_e32 v81, 0xe0ad78ec, v80
	v_sub_f32_e32 v82, v82, v81
	v_mov_b32_e32 v93, v80
	v_exp_f32_e32 v82, v82
	v_sub_f32_e32 v83, v92, v81
	v_cndmask_b32_e64 v83, v243, v83, s[24:25]
	v_fmamk_f32 v54, v54, 0x3fb8aa3b, v83
	v_fmamk_f32 v55, v55, 0x3fb8aa3b, v83
	v_fmamk_f32 v56, v56, 0x3fb8aa3b, v83
	v_fmamk_f32 v57, v57, 0x3fb8aa3b, v83
	v_exp_f32_e32 v54, v54
	v_exp_f32_e32 v55, v55
	v_exp_f32_e32 v56, v56
	v_exp_f32_e32 v57, v57
	v_fmamk_f32 v58, v58, 0x3fb8aa3b, v83
	v_fmamk_f32 v59, v59, 0x3fb8aa3b, v83
	v_fmamk_f32 v60, v60, 0x3fb8aa3b, v83
	v_fmamk_f32 v61, v61, 0x3fb8aa3b, v83
	v_exp_f32_e32 v58, v58
	v_exp_f32_e32 v59, v59
	v_exp_f32_e32 v60, v60
	v_exp_f32_e32 v61, v61
	v_fmamk_f32 v62, v62, 0x3fb8aa3b, v83
	v_fmamk_f32 v63, v63, 0x3fb8aa3b, v83
	v_fmamk_f32 v64, v64, 0x3fb8aa3b, v83
	v_fmamk_f32 v65, v65, 0x3fb8aa3b, v83
	v_exp_f32_e32 v62, v62
	v_exp_f32_e32 v63, v63
	v_exp_f32_e32 v64, v64
	v_exp_f32_e32 v65, v65
	v_fmamk_f32 v66, v66, 0x3fb8aa3b, v83
	v_fmamk_f32 v67, v67, 0x3fb8aa3b, v83
	v_fmamk_f32 v68, v68, 0x3fb8aa3b, v83
	v_fmamk_f32 v69, v69, 0x3fb8aa3b, v83
	v_exp_f32_e32 v66, v66
	v_exp_f32_e32 v67, v67
	v_exp_f32_e32 v68, v68
	v_exp_f32_e32 v69, v69
	s_nop 0
	v_add_f32_e32 v78, v54, v55
	v_add_f32_e32 v79, v56, v57
	v_add_f32_e32 v80, v58, v59
	v_add_f32_e32 v81, v60, v61
	v_add_f32_e32 v78, v78, v62
	v_add_f32_e32 v79, v79, v63
	v_add_f32_e32 v80, v80, v64
	v_add_f32_e32 v81, v81, v65
	v_add_f32_e32 v78, v78, v66
	v_add_f32_e32 v79, v79, v67
	v_add_f32_e32 v80, v80, v68
	v_add_f32_e32 v81, v81, v69
	v_add_f32_e32 v78, v78, v79
	v_add_f32_e32 v80, v80, v81
	v_add_f32_e32 v78, v78, v80
	v_cvt_pk_bf16_f32 v70, v54, v55
	v_cvt_pk_bf16_f32 v71, v56, v57
	v_cvt_pk_bf16_f32 v72, v58, v59
	v_cvt_pk_bf16_f32 v73, v60, v61
	v_cvt_pk_bf16_f32 v74, v62, v63
	v_cvt_pk_bf16_f32 v75, v64, v65
	v_cvt_pk_bf16_f32 v76, v66, v67
	v_cvt_pk_bf16_f32 v77, v68, v69
	v_mov_b32_e32 v79, v78
	s_nop 1
	v_permlane16_swap_b32_e32 v78, v79
	v_add_f32_e32 v78, v78, v79
	v_mov_b32_e32 v79, v78
	s_nop 1
	v_permlane32_swap_b32_e32 v78, v79
	v_add_f32_e32 v78, v78, v79
	v_fma_f32 v105, v105, v82, v78
	v_cmp_neq_f32_e64 s[4:5], 1.0, v82
	s_cmp_eq_u64 s[4:5], 0
	s_cbranch_scc1 .Lsl2_nosc_28
	v_pk_mul_f32 v[22:23], v[22:23], v[82:83] op_sel_hi:[1,0]
	v_pk_mul_f32 v[24:25], v[24:25], v[82:83] op_sel_hi:[1,0]
	v_pk_mul_f32 v[26:27], v[26:27], v[82:83] op_sel_hi:[1,0]
	v_pk_mul_f32 v[28:29], v[28:29], v[82:83] op_sel_hi:[1,0]
	v_pk_mul_f32 v[34:35], v[34:35], v[82:83] op_sel_hi:[1,0]
	v_pk_mul_f32 v[36:37], v[36:37], v[82:83] op_sel_hi:[1,0]
	v_pk_mul_f32 v[30:31], v[30:31], v[82:83] op_sel_hi:[1,0]
	v_pk_mul_f32 v[32:33], v[32:33], v[82:83] op_sel_hi:[1,0]

; #define LAS __attribute__((address_space(3)))
; template <int D, class SF>
; __device__ __forceinline__ void attn_step(const bf16x8 (&qf)[D / 32], const LAS bf16_t* Ks, const LAS bf16_t* Vt, f32x4 (&o)[D / 16], float& m, float& lsum, float& alpha_out, bf16x8& pf0_out, bf16x8& pf1_out, const int lane, SF sf) {
;     constexpr int KSTR = D + 8;
;     const int c = lane & 15, i = lane >> 4;
;     f32x4 s[4];
; #pragma unroll
;     for (int t = 0; t < 4; ++t) s[t] = (f32x4){0.f, 0.f, 0.f, 0.f};
; #pragma unroll
;     for (int ks = 0; ks < D / 32; ++ks) {
; #pragma unroll
;         for (int t = 0; t < 4; ++t) { const bf16x8 kf = *(const LAS bf16x8*)(Ks + (16 * t + c) * KSTR + ks * 32 + 8 * i); s[t] = mfma16(kf, qf[ks], s[t]); }
;     }
;     float v[16];
; #pragma unroll
;     for (int t = 0; t < 4; ++t)
; #pragma unroll
;         for (int r = 0; r < 4; ++r) v[4 * t + r] = sf(16 * t + 4 * i + r, s[t][r]);
;     float mx = fmaxf(fmaxf(fmaxf(v[0], v[1]), fmaxf(v[2], v[3])), fmaxf(fmaxf(v[4], v[5]), fmaxf(v[6], v[7])));
;     mx = fmaxf(mx, fmaxf(fmaxf(fmaxf(v[8], v[9]), fmaxf(v[10], v[11])), fmaxf(fmaxf(v[12], v[13]), fmaxf(v[14], v[15]))));
;     mx = rows_max(mx);
;     const float mnew = fmaxf(m, mx);
;     const float mc = fmaxf(mnew, -1e20f);
;     const float alpha = __builtin_amdgcn_exp2f(fmaxf(m, -1e20f) - mc);
;     float p[16], rs = 0.f;
; #pragma unroll
;     for (int r = 0; r < 16; ++r) { p[r] = __builtin_amdgcn_exp2f(v[r] - mc); rs += p[r]; }
;     rs = rows_sum(rs);
;     lsum = lsum * alpha + rs; m = mnew;
;     union { u32x4 u; bf16x8 b; } pk0, pk1;
;     pk0.u.x = cvt_pk_bf16(p[0], p[1]); pk0.u.y = cvt_pk_bf16(p[2], p[3]); pk0.u.z = cvt_pk_bf16(p[4], p[5]); pk0.u.w = cvt_pk_bf16(p[6], p[7]);
;     pk1.u.x = cvt_pk_bf16(p[8], p[9]); pk1.u.y = cvt_pk_bf16(p[10], p[11]); pk1.u.z = cvt_pk_bf16(p[12], p[13]); pk1.u.w = cvt_pk_bf16(p[14], p[15]);
;     if (__builtin_amdgcn_ballot_w64(alpha != 1.0f) != 0ull) {
; #pragma unroll
;         for (int dt = 0; dt < D / 16; ++dt) o[dt] *= alpha;
;     }
; #pragma unroll
;     for (int dt = 0; dt < D / 16; ++dt) {
;         const LAS bf16_t* vp = Vt + (16 * dt + c) * 72 + 4 * i;
;         union { u32x4 u; bf16x8 b; } vf0, vf1; const u32x2 a0 = *(const LAS u32x2*)vp, a1 = *(const LAS u32x2*)(vp + 16), b0 = *(const LAS u32x2*)(vp + 32), b1 = *(const LAS u32x2*)(vp + 48);
.Lsl2_nearb_23:
	v_lshrrev_b64 v[78:79], s8, v[18:19]
	v_and_b32_e32 v78, 1, v78
	v_cmp_eq_u32_e64 s[24:25], 1, v78
	s_cmp_eq_u64 s[24:25], 0
	s_cbranch_scc1 .Lsl2_skn_29
	v_sub_u32_e32 v78, v130, v139
	v_subrev_u32_e32 v78, s9, v78
	v_lshl_add_u32 v79, v78, 2, v131
	v_add_u32_e32 v79, 0xffffff34, v79
	ds_read_b32 v107, v79 offset:204
	ds_read_b32 v108, v79 offset:200
	ds_read_b32 v109, v79 offset:196
	ds_read_b32 v110, v79 offset:192
	ds_read_b32 v111, v79 offset:140
	ds_read_b32 v112, v79 offset:136
	ds_read_b32 v113, v79 offset:132
	ds_read_b32 v133, v79 offset:128
	ds_read_b128 v[198:201], v102 offset:34816
	ds_read_b128 v[206:209], v102 offset:37120
	ds_read_b128 v[202:205], v102 offset:34880
	ds_read_b128 v[210:213], v102 offset:37184
	ds_read_b128 v[214:217], v102 offset:39424
	ds_read_b128 v[222:225], v102 offset:41728
	ds_read_b128 v[218:221], v102 offset:39488
	ds_read_b128 v[226:229], v102 offset:41792
	s_waitcnt lgkmcnt(6)
	v_mfma_f32_16x16x32_bf16 v[54:57], v[198:201], v[2:5], 0
	v_mfma_f32_16x16x32_bf16 v[58:61], v[206:209], v[2:5], 0
	s_waitcnt lgkmcnt(4)
	v_mfma_f32_16x16x32_bf16 v[54:57], v[202:205], v[6:9], v[54:57]
	v_mfma_f32_16x16x32_bf16 v[58:61], v[210:213], v[6:9], v[58:61]
	s_waitcnt lgkmcnt(2)
	v_mfma_f32_16x16x32_bf16 v[62:65], v[214:217], v[2:5], 0
	v_mfma_f32_16x16x32_bf16 v[66:69], v[222:225], v[2:5], 0
	s_waitcnt lgkmcnt(0)
	v_mfma_f32_16x16x32_bf16 v[62:65], v[218:221], v[6:9], v[62:65]
	v_mfma_f32_16x16x32_bf16 v[66:69], v[226:229], v[6:9], v[66:69]
	ds_read_b64_tr_b16 v[198:199], v104 offset:44032
	ds_read_b64_tr_b16 v[200:201], v104 offset:46336
	ds_read_b64_tr_b16 v[202:203], v104 offset:48640
	ds_read_b64_tr_b16 v[204:205], v104 offset:50944
	ds_read_b64_tr_b16 v[206:207], v104 offset:44064
	ds_read_b64_tr_b16 v[208:209], v104 offset:46368
	ds_read_b64_tr_b16 v[210:211], v104 offset:48672
	v_fmamk_f32 v54, v54, 0x3fb8aa3b, v107
	v_fmamk_f32 v55, v55, 0x3fb8aa3b, v108
	v_fmamk_f32 v56, v56, 0x3fb8aa3b, v109
	v_fmamk_f32 v57, v57, 0x3fb8aa3b, v110
	v_fmamk_f32 v58, v58, 0x3fb8aa3b, v111
	v_fmamk_f32 v59, v59, 0x3fb8aa3b, v112
	v_fmamk_f32 v60, v60, 0x3fb8aa3b, v113
	v_fmamk_f32 v61, v61, 0x3fb8aa3b, v133
	ds_read_b32 v107, v79 offset:76
	ds_read_b32 v108, v79 offset:72
	ds_read_b32 v109, v79 offset:68
	ds_read_b32 v110, v79 offset:64
	ds_read_b32 v111, v79 offset:12
	ds_read_b32 v112, v79 offset:8
	ds_read_b32 v113, v79 offset:4
	ds_read_b32 v133, v79 offset:0
	ds_read_b64_tr_b16 v[212:213], v104 offset:50976
	ds_read_b64_tr_b16 v[214:215], v104 offset:44096
	ds_read_b64_tr_b16 v[216:217], v104 offset:46400
	ds_read_b64_tr_b16 v[218:219], v104 offset:48704
	ds_read_b64_tr_b16 v[220:221], v104 offset:51008
	ds_read_b64_tr_b16 v[222:223], v104 offset:44128
	ds_read_b64_tr_b16 v[224:225], v104 offset:46432
	ds_read_b64_tr_b16 v[226:227], v104 offset:48736
	ds_read_b64_tr_b16 v[228:229], v104 offset:51040
	s_waitcnt lgkmcnt(9)
	v_fmamk_f32 v62, v62, 0x3fb8aa3b, v107
	v_fmamk_f32 v63, v63, 0x3fb8aa3b, v108
	v_fmamk_f32 v64, v64, 0x3fb8aa3b, v109
	v_fmamk_f32 v65, v65, 0x3fb8aa3b, v110
	v_fmamk_f32 v66, v66, 0x3fb8aa3b, v111
	v_fmamk_f32 v67, v67, 0x3fb8aa3b, v112
	v_fmamk_f32 v68, v68, 0x3fb8aa3b, v113
	v_fmamk_f32 v69, v69, 0x3fb8aa3b, v133
	v_max3_f32 v84, v54, v55, v56
	v_max3_f32 v79, v57, v58, v59
	v_max3_f32 v80, v60, v61, v62
	v_max3_f32 v81, v63, v64, v65
	v_max3_f32 v83, v66, v67, v68
	v_max3_f32 v84, v84, v79, v69
	v_max3_f32 v80, v80, v81, v83
	v_max_f32_e32 v84, v84, v80
	v_mov_b32_e32 v79, v84
	s_nop 1
	v_permlane16_swap_b32_e32 v84, v79
	v_max_f32_e32 v84, v84, v79
	v_mov_b32_e32 v79, v84
	s_nop 1
	v_permlane32_swap_b32_e32 v84, v79
	v_max_f32_e32 v84, v84, v79
	v_cndmask_b32_e64 v84, v243, v84, s[24:25]
	v_max_f32_e32 v80, v100, v84
	v_max_f32_e32 v82, 0xe0ad78ec, v100
	v_max_f32_e32 v81, 0xe0ad78ec, v80
	v_sub_f32_e32 v82, v82, v81
	v_mov_b32_e32 v100, v80
	v_exp_f32_e32 v82, v82
	v_mov_b32_e32 v83, 0x7149f2ca
	v_cndmask_b32_e64 v83, v83, v81, s[24:25]
	v_sub_f32_e32 v54, v54, v83
	v_sub_f32_e32 v55, v55, v83
	v_sub_f32_e32 v56, v56, v83
	v_sub_f32_e32 v57, v57, v83
	v_exp_f32_e32 v54, v54
	v_exp_f32_e32 v55, v55
	v_exp_f32_e32 v56, v56
	v_exp_f32_e32 v57, v57
	v_sub_f32_e32 v58, v58, v83
	v_sub_f32_e32 v59, v59, v83
	v_sub_f32_e32 v60, v60, v83
	v_sub_f32_e32 v61, v61, v83
	v_exp_f32_e32 v58, v58
	v_exp_f32_e32 v59, v59
	v_exp_f32_e32 v60, v60
	v_exp_f32_e32 v61, v61
	v_sub_f32_e32 v62, v62, v83
	v_sub_f32_e32 v63, v63, v83
	v_sub_f32_e32 v64, v64, v83
	v_sub_f32_e32 v65, v65, v83
	v_exp_f32_e32 v62, v62
	v_exp_f32_e32 v63, v63
	v_exp_f32_e32 v64, v64
	v_exp_f32_e32 v65, v65
	v_sub_f32_e32 v66, v66, v83
	v_sub_f32_e32 v67, v67, v83
	v_sub_f32_e32 v68, v68, v83
	v_sub_f32_e32 v69, v69, v83
	v_exp_f32_e32 v66, v66
	v_exp_f32_e32 v67, v67
	v_exp_f32_e32 v68, v68
	v_exp_f32_e32 v69, v69
	s_nop 0
	v_add_f32_e32 v78, v54, v55
	v_add_f32_e32 v79, v56, v57
	v_add_f32_e32 v80, v58, v59
	v_add_f32_e32 v81, v60, v61
	v_add_f32_e32 v78, v78, v62
	v_add_f32_e32 v79, v79, v63
	v_add_f32_e32 v80, v80, v64
	v_add_f32_e32 v81, v81, v65
	v_add_f32_e32 v78, v78, v66
	v_add_f32_e32 v79, v79, v67
	v_add_f32_e32 v80, v80, v68
	v_add_f32_e32 v81, v81, v69
	v_add_f32_e32 v78, v78, v79
	v_add_f32_e32 v80, v80, v81
	v_add_f32_e32 v78, v78, v80
	v_cvt_pk_bf16_f32 v70, v54, v55
	v_cvt_pk_bf16_f32 v71, v56, v57
	v_cvt_pk_bf16_f32 v72, v58, v59
	v_cvt_pk_bf16_f32 v73, v60, v61
	v_cvt_pk_bf16_f32 v74, v62, v63
	v_cvt_pk_bf16_f32 v75, v64, v65
	v_cvt_pk_bf16_f32 v76, v66, v67
	v_cvt_pk_bf16_f32 v77, v68, v69
	v_mov_b32_e32 v79, v78
	s_nop 1
	v_permlane16_swap_b32_e32 v78, v79
	v_add_f32_e32 v78, v78, v79
	v_mov_b32_e32 v79, v78
	s_nop 1
	v_permlane32_swap_b32_e32 v78, v79
	v_add_f32_e32 v78, v78, v79
	v_fma_f32 v106, v106, v82, v78
	v_cmp_neq_f32_e64 s[4:5], 1.0, v82
	s_cmp_eq_u64 s[4:5], 0
	s_cbranch_scc1 .Lsl2_nosc_30
	v_pk_mul_f32 v[38:39], v[38:39], v[82:83] op_sel_hi:[1,0]
	v_pk_mul_f32 v[40:41], v[40:41], v[82:83] op_sel_hi:[1,0]
	v_pk_mul_f32 v[42:43], v[42:43], v[82:83] op_sel_hi:[1,0]
	v_pk_mul_f32 v[44:45], v[44:45], v[82:83] op_sel_hi:[1,0]
	v_pk_mul_f32 v[46:47], v[46:47], v[82:83] op_sel_hi:[1,0]
	v_pk_mul_f32 v[48:49], v[48:49], v[82:83] op_sel_hi:[1,0]
	v_pk_mul_f32 v[50:51], v[50:51], v[82:83] op_sel_hi:[1,0]
	v_pk_mul_f32 v[52:53], v[52:53], v[82:83] op_sel_hi:[1,0]

; #define LAS __attribute__((address_space(3)))
; template <int D, class SF>
; __device__ __forceinline__ void attn_step(const bf16x8 (&qf)[D / 32], const LAS bf16_t* Ks, const LAS bf16_t* Vt, f32x4 (&o)[D / 16], float& m, float& lsum, float& alpha_out, bf16x8& pf0_out, bf16x8& pf1_out, const int lane, SF sf) {
;     constexpr int KSTR = D + 8;
;     const int c = lane & 15, i = lane >> 4;
;     f32x4 s[4];
; #pragma unroll
;     for (int t = 0; t < 4; ++t) s[t] = (f32x4){0.f, 0.f, 0.f, 0.f};
; #pragma unroll
;     for (int ks = 0; ks < D / 32; ++ks) {
; #pragma unroll
;         for (int t = 0; t < 4; ++t) { const bf16x8 kf = *(const LAS bf16x8*)(Ks + (16 * t + c) * KSTR + ks * 32 + 8 * i); s[t] = mfma16(kf, qf[ks], s[t]); }
;     }
;     float v[16];
; #pragma unroll
;     for (int t = 0; t < 4; ++t)
; #pragma unroll
;         for (int r = 0; r < 4; ++r) v[4 * t + r] = sf(16 * t + 4 * i + r, s[t][r]);
;     float mx = fmaxf(fmaxf(fmaxf(v[0], v[1]), fmaxf(v[2], v[3])), fmaxf(fmaxf(v[4], v[5]), fmaxf(v[6], v[7])));
;     mx = fmaxf(mx, fmaxf(fmaxf(fmaxf(v[8], v[9]), fmaxf(v[10], v[11])), fmaxf(fmaxf(v[12], v[13]), fmaxf(v[14], v[15]))));
;     mx = rows_max(mx);
;     const float mnew = fmaxf(m, mx);
;     const float mc = fmaxf(mnew, -1e20f);
;     const float alpha = __builtin_amdgcn_exp2f(fmaxf(m, -1e20f) - mc);
;     float p[16], rs = 0.f;
; #pragma unroll
;     for (int r = 0; r < 16; ++r) { p[r] = __builtin_amdgcn_exp2f(v[r] - mc); rs += p[r]; }
;     rs = rows_sum(rs);
;     lsum = lsum * alpha + rs; m = mnew;
;     union { u32x4 u; bf16x8 b; } pk0, pk1;
;     pk0.u.x = cvt_pk_bf16(p[0], p[1]); pk0.u.y = cvt_pk_bf16(p[2], p[3]); pk0.u.z = cvt_pk_bf16(p[4], p[5]); pk0.u.w = cvt_pk_bf16(p[6], p[7]);
;     pk1.u.x = cvt_pk_bf16(p[8], p[9]); pk1.u.y = cvt_pk_bf16(p[10], p[11]); pk1.u.z = cvt_pk_bf16(p[12], p[13]); pk1.u.w = cvt_pk_bf16(p[14], p[15]);
;     if (__builtin_amdgcn_ballot_w64(alpha != 1.0f) != 0ull) {
; #pragma unroll
;         for (int dt = 0; dt < D / 16; ++dt) o[dt] *= alpha;
;     }
; #pragma unroll
;     for (int dt = 0; dt < D / 16; ++dt) {
;         const LAS bf16_t* vp = Vt + (16 * dt + c) * 72 + 4 * i;
;         union { u32x4 u; bf16x8 b; } vf0, vf1; const u32x2 a0 = *(const LAS u32x2*)vp, a1 = *(const LAS u32x2*)(vp + 16), b0 = *(const LAS u32x2*)(vp + 32), b1 = *(const LAS u32x2*)(vp + 48);
.Lsl2_skn_29:
	v_lshrrev_b64 v[78:79], s8, v[20:21]
	v_and_b32_e32 v78, 1, v78
	v_cmp_eq_u32_e64 s[24:25], 1, v78
	s_cmp_eq_u64 s[24:25], 0
	s_cbranch_scc1 .Lsl2_skn_31
	v_sub_u32_e32 v78, v98, v139
	v_subrev_u32_e32 v78, s9, v78
	v_lshl_add_u32 v79, v78, 2, v131
	v_add_u32_e32 v79, 0xffffff34, v79
	ds_read_b32 v107, v79 offset:204
	ds_read_b32 v108, v79 offset:200
	ds_read_b32 v109, v79 offset:196
	ds_read_b32 v110, v79 offset:192
	ds_read_b32 v111, v79 offset:140
	ds_read_b32 v112, v79 offset:136
	ds_read_b32 v113, v79 offset:132
	ds_read_b32 v133, v79 offset:128
	ds_read_b128 v[198:201], v102 offset:34816
	ds_read_b128 v[206:209], v102 offset:37120
	ds_read_b128 v[202:205], v102 offset:34880
	ds_read_b128 v[210:213], v102 offset:37184
	ds_read_b128 v[214:217], v102 offset:39424
	ds_read_b128 v[222:225], v102 offset:41728
	ds_read_b128 v[218:221], v102 offset:39488
	ds_read_b128 v[226:229], v102 offset:41792
	s_waitcnt lgkmcnt(6)
	v_mfma_f32_16x16x32_bf16 v[54:57], v[198:201], v[10:13], 0
	v_mfma_f32_16x16x32_bf16 v[58:61], v[206:209], v[10:13], 0
	s_waitcnt lgkmcnt(4)
	v_mfma_f32_16x16x32_bf16 v[54:57], v[202:205], v[14:17], v[54:57]
	v_mfma_f32_16x16x32_bf16 v[58:61], v[210:213], v[14:17], v[58:61]
	s_waitcnt lgkmcnt(2)
	v_mfma_f32_16x16x32_bf16 v[62:65], v[214:217], v[10:13], 0
	v_mfma_f32_16x16x32_bf16 v[66:69], v[222:225], v[10:13], 0
	s_waitcnt lgkmcnt(0)
	v_mfma_f32_16x16x32_bf16 v[62:65], v[218:221], v[14:17], v[62:65]
	v_mfma_f32_16x16x32_bf16 v[66:69], v[226:229], v[14:17], v[66:69]
	ds_read_b64_tr_b16 v[198:199], v104 offset:44032
	ds_read_b64_tr_b16 v[200:201], v104 offset:46336
	ds_read_b64_tr_b16 v[202:203], v104 offset:48640
	ds_read_b64_tr_b16 v[204:205], v104 offset:50944
	ds_read_b64_tr_b16 v[206:207], v104 offset:44064
	ds_read_b64_tr_b16 v[208:209], v104 offset:46368
	ds_read_b64_tr_b16 v[210:211], v104 offset:48672
	v_fmamk_f32 v54, v54, 0x3fb8aa3b, v107
	v_fmamk_f32 v55, v55, 0x3fb8aa3b, v108
	v_fmamk_f32 v56, v56, 0x3fb8aa3b, v109
	v_fmamk_f32 v57, v57, 0x3fb8aa3b, v110
	v_fmamk_f32 v58, v58, 0x3fb8aa3b, v111
	v_fmamk_f32 v59, v59, 0x3fb8aa3b, v112
	v_fmamk_f32 v60, v60, 0x3fb8aa3b, v113
	v_fmamk_f32 v61, v61, 0x3fb8aa3b, v133
	ds_read_b32 v107, v79 offset:76
	ds_read_b32 v108, v79 offset:72
	ds_read_b32 v109, v79 offset:68
	ds_read_b32 v110, v79 offset:64
	ds_read_b32 v111, v79 offset:12
	ds_read_b32 v112, v79 offset:8
	ds_read_b32 v113, v79 offset:4
	ds_read_b32 v133, v79 offset:0
	ds_read_b64_tr_b16 v[212:213], v104 offset:50976
	ds_read_b64_tr_b16 v[214:215], v104 offset:44096
	ds_read_b64_tr_b16 v[216:217], v104 offset:46400
	ds_read_b64_tr_b16 v[218:219], v104 offset:48704
	ds_read_b64_tr_b16 v[220:221], v104 offset:51008
	ds_read_b64_tr_b16 v[222:223], v104 offset:44128
	ds_read_b64_tr_b16 v[224:225], v104 offset:46432
	ds_read_b64_tr_b16 v[226:227], v104 offset:48736
	ds_read_b64_tr_b16 v[228:229], v104 offset:51040
	s_waitcnt lgkmcnt(9)
	v_fmamk_f32 v62, v62, 0x3fb8aa3b, v107
	v_fmamk_f32 v63, v63, 0x3fb8aa3b, v108
	v_fmamk_f32 v64, v64, 0x3fb8aa3b, v109
	v_fmamk_f32 v65, v65, 0x3fb8aa3b, v110
	v_fmamk_f32 v66, v66, 0x3fb8aa3b, v111
	v_fmamk_f32 v67, v67, 0x3fb8aa3b, v112
	v_fmamk_f32 v68, v68, 0x3fb8aa3b, v113
	v_fmamk_f32 v69, v69, 0x3fb8aa3b, v133
	v_max3_f32 v84, v54, v55, v56
	v_max3_f32 v79, v57, v58, v59
	v_max3_f32 v80, v60, v61, v62
	v_max3_f32 v81, v63, v64, v65
	v_max3_f32 v83, v66, v67, v68
	v_max3_f32 v84, v84, v79, v69
	v_max3_f32 v80, v80, v81, v83
	v_max_f32_e32 v84, v84, v80
	v_mov_b32_e32 v79, v84
	s_nop 1
	v_permlane16_swap_b32_e32 v84, v79
	v_max_f32_e32 v84, v84, v79
	v_mov_b32_e32 v79, v84
	s_nop 1
	v_permlane32_swap_b32_e32 v84, v79
	v_max_f32_e32 v84, v84, v79
	v_cndmask_b32_e64 v84, v243, v84, s[24:25]
	v_max_f32_e32 v80, v93, v84
	v_max_f32_e32 v82, 0xe0ad78ec, v93
	v_max_f32_e32 v81, 0xe0ad78ec, v80
	v_sub_f32_e32 v82, v82, v81
	v_mov_b32_e32 v93, v80
	v_exp_f32_e32 v82, v82
	v_mov_b32_e32 v83, 0x7149f2ca
	v_cndmask_b32_e64 v83, v83, v81, s[24:25]
	v_sub_f32_e32 v54, v54, v83
	v_sub_f32_e32 v55, v55, v83
	v_sub_f32_e32 v56, v56, v83
	v_sub_f32_e32 v57, v57, v83
	v_exp_f32_e32 v54, v54
	v_exp_f32_e32 v55, v55
	v_exp_f32_e32 v56, v56
	v_exp_f32_e32 v57, v57
	v_sub_f32_e32 v58, v58, v83
	v_sub_f32_e32 v59, v59, v83
	v_sub_f32_e32 v60, v60, v83
	v_sub_f32_e32 v61, v61, v83
	v_exp_f32_e32 v58, v58
	v_exp_f32_e32 v59, v59
	v_exp_f32_e32 v60, v60
	v_exp_f32_e32 v61, v61
	v_sub_f32_e32 v62, v62, v83
	v_sub_f32_e32 v63, v63, v83
	v_sub_f32_e32 v64, v64, v83
	v_sub_f32_e32 v65, v65, v83
	v_exp_f32_e32 v62, v62
	v_exp_f32_e32 v63, v63
	v_exp_f32_e32 v64, v64
	v_exp_f32_e32 v65, v65
	v_sub_f32_e32 v66, v66, v83
	v_sub_f32_e32 v67, v67, v83
	v_sub_f32_e32 v68, v68, v83
	v_sub_f32_e32 v69, v69, v83
	v_exp_f32_e32 v66, v66
	v_exp_f32_e32 v67, v67
	v_exp_f32_e32 v68, v68
	v_exp_f32_e32 v69, v69
	s_nop 0
	v_add_f32_e32 v78, v54, v55
	v_add_f32_e32 v79, v56, v57
	v_add_f32_e32 v80, v58, v59
	v_add_f32_e32 v81, v60, v61
	v_add_f32_e32 v78, v78, v62
	v_add_f32_e32 v79, v79, v63
	v_add_f32_e32 v80, v80, v64
	v_add_f32_e32 v81, v81, v65
	v_add_f32_e32 v78, v78, v66
	v_add_f32_e32 v79, v79, v67
	v_add_f32_e32 v80, v80, v68
	v_add_f32_e32 v81, v81, v69
	v_add_f32_e32 v78, v78, v79
	v_add_f32_e32 v80, v80, v81
	v_add_f32_e32 v78, v78, v80
	v_cvt_pk_bf16_f32 v70, v54, v55
	v_cvt_pk_bf16_f32 v71, v56, v57
	v_cvt_pk_bf16_f32 v72, v58, v59
	v_cvt_pk_bf16_f32 v73, v60, v61
	v_cvt_pk_bf16_f32 v74, v62, v63
	v_cvt_pk_bf16_f32 v75, v64, v65
	v_cvt_pk_bf16_f32 v76, v66, v67
	v_cvt_pk_bf16_f32 v77, v68, v69
	v_mov_b32_e32 v79, v78
	s_nop 1
	v_permlane16_swap_b32_e32 v78, v79
	v_add_f32_e32 v78, v78, v79
	v_mov_b32_e32 v79, v78
	s_nop 1
	v_permlane32_swap_b32_e32 v78, v79
	v_add_f32_e32 v78, v78, v79
	v_fma_f32 v105, v105, v82, v78
	v_cmp_neq_f32_e64 s[4:5], 1.0, v82
	s_cmp_eq_u64 s[4:5], 0
	s_cbranch_scc1 .Lsl2_nosc_32
	v_pk_mul_f32 v[22:23], v[22:23], v[82:83] op_sel_hi:[1,0]
	v_pk_mul_f32 v[24:25], v[24:25], v[82:83] op_sel_hi:[1,0]
	v_pk_mul_f32 v[26:27], v[26:27], v[82:83] op_sel_hi:[1,0]
	v_pk_mul_f32 v[28:29], v[28:29], v[82:83] op_sel_hi:[1,0]
	v_pk_mul_f32 v[34:35], v[34:35], v[82:83] op_sel_hi:[1,0]
	v_pk_mul_f32 v[36:37], v[36:37], v[82:83] op_sel_hi:[1,0]
	v_pk_mul_f32 v[30:31], v[30:31], v[82:83] op_sel_hi:[1,0]
	v_pk_mul_f32 v[32:33], v[32:33], v[82:83] op_sel_hi:[1,0]

; #define LAS __attribute__((address_space(3)))
; __device__ __forceinline__ f32x4 mfma16(bf16x8 a, bf16x8 b, f32x4 c) { return __builtin_amdgcn_mfma_f32_16x16x32_bf16(a, b, c, 0, 0, 0); }
; template <int D, class SF>
; __device__ __forceinline__ void attn_step(const bf16x8 (&qf)[D / 32], const LAS bf16_t* Ks, const LAS bf16_t* Vt, f32x4 (&o)[D / 16], float& m, float& lsum, float& alpha_out, bf16x8& pf0_out, bf16x8& pf1_out, const int lane, SF sf) {
;     ...
;     for (int ks = 0; ks < D / 32; ++ks) {
; #pragma unroll
;         for (int t = 0; t < 4; ++t) { const bf16x8 kf = *(const LAS bf16x8*)(Ks + (16 * t + c) * KSTR + ks * 32 + 8 * i); s[t] = mfma16(kf, qf[ks], s[t]); }
;     }
;     float v[16];
; #pragma unroll
;     for (int t = 0; t < 4; ++t)
; #pragma unroll
;         for (int r = 0; r < 4; ++r) v[4 * t + r] = sf(16 * t + 4 * i + r, s[t][r]);
; __device__ __forceinline__ void nsa_unit(LAS unsigned char* lds, const Ctx& P, int l, int b, int hkv, int tb) {
;     ...
;                 for (int sb = 0; sb < 2; ++sb) { const bool selj = (ms[sb] >> j) & 1ull; const int tqs = tq[sb];
;                     if (far) {
;                         if (__builtin_amdgcn_ballot_w64(selj) == 0ull) continue;
;                         attn_step<64>(qf[sb], Ks, Vt, o[sb], m[sb], lsum[sb], alpha, pf, pf1, lane,
;                             [&](int, float s) { return selj ? s * LOG2E + cfar : NEGBIG; });
;                     } else { const int kp0 = j * 64;
;                         attn_step<64>(qf[sb], Ks, Vt, o[sb], m[sb], lsum[sb], alpha, pf, pf1, lane,
;                             [&](int kk, float s) { const int dist = tqs - (kp0 + kk); return (selj && dist >= 0) ? s * LOG2E + lut[min((unsigned)dist, 1023u)] : NEGBIG; });
.Lsl2_diagb_24:
	v_lshrrev_b64 v[78:79], s8, v[18:19]
	v_and_b32_e32 v78, 1, v78
	v_cmp_eq_u32_e64 s[24:25], 1, v78
	s_cmp_eq_u64 s[24:25], 0
	s_cbranch_scc1 .Lsl2_skd_33
	v_sub_u32_e32 v78, v130, v139
	v_subrev_u32_e32 v78, s9, v78
	v_subrev_u32_e32 v107, 0, v78
	v_min_u32_e32 v107, 0x3ff, v107
	v_lshl_add_u32 v107, v107, 2, v131
	ds_read_b32 v107, v107
	v_subrev_u32_e32 v108, 1, v78
	v_min_u32_e32 v108, 0x3ff, v108
	v_lshl_add_u32 v108, v108, 2, v131
	ds_read_b32 v108, v108
	v_subrev_u32_e32 v109, 2, v78
	v_min_u32_e32 v109, 0x3ff, v109
	v_lshl_add_u32 v109, v109, 2, v131
	ds_read_b32 v109, v109
	v_subrev_u32_e32 v110, 3, v78
	v_min_u32_e32 v110, 0x3ff, v110
	v_lshl_add_u32 v110, v110, 2, v131
	ds_read_b32 v110, v110
	v_subrev_u32_e32 v111, 16, v78
	v_min_u32_e32 v111, 0x3ff, v111
	v_lshl_add_u32 v111, v111, 2, v131
	ds_read_b32 v111, v111
	v_subrev_u32_e32 v112, 17, v78
	v_min_u32_e32 v112, 0x3ff, v112
	v_lshl_add_u32 v112, v112, 2, v131
	ds_read_b32 v112, v112
	v_subrev_u32_e32 v113, 18, v78
	v_min_u32_e32 v113, 0x3ff, v113
	v_lshl_add_u32 v113, v113, 2, v131
	ds_read_b32 v113, v113
	v_subrev_u32_e32 v133, 19, v78
	v_min_u32_e32 v133, 0x3ff, v133
	v_lshl_add_u32 v133, v133, 2, v131
	ds_read_b32 v133, v133
	ds_read_b128 v[198:201], v102 offset:34816
	ds_read_b128 v[206:209], v102 offset:37120
	ds_read_b128 v[202:205], v102 offset:34880
	ds_read_b128 v[210:213], v102 offset:37184
	ds_read_b128 v[214:217], v102 offset:39424
	ds_read_b128 v[222:225], v102 offset:41728
	ds_read_b128 v[218:221], v102 offset:39488
	ds_read_b128 v[226:229], v102 offset:41792
	s_waitcnt lgkmcnt(6)
	v_mfma_f32_16x16x32_bf16 v[54:57], v[198:201], v[2:5], 0
	v_mfma_f32_16x16x32_bf16 v[58:61], v[206:209], v[2:5], 0
	s_waitcnt lgkmcnt(4)
	v_mfma_f32_16x16x32_bf16 v[54:57], v[202:205], v[6:9], v[54:57]
	v_mfma_f32_16x16x32_bf16 v[58:61], v[210:213], v[6:9], v[58:61]
	s_waitcnt lgkmcnt(2)
	v_mfma_f32_16x16x32_bf16 v[62:65], v[214:217], v[2:5], 0
	v_mfma_f32_16x16x32_bf16 v[66:69], v[222:225], v[2:5], 0
	s_waitcnt lgkmcnt(0)
	v_mfma_f32_16x16x32_bf16 v[62:65], v[218:221], v[6:9], v[62:65]
	v_mfma_f32_16x16x32_bf16 v[66:69], v[226:229], v[6:9], v[66:69]
	ds_read_b64_tr_b16 v[198:199], v104 offset:44032
	ds_read_b64_tr_b16 v[200:201], v104 offset:46336
	ds_read_b64_tr_b16 v[202:203], v104 offset:48640
	ds_read_b64_tr_b16 v[204:205], v104 offset:50944
	ds_read_b64_tr_b16 v[206:207], v104 offset:44064
	ds_read_b64_tr_b16 v[208:209], v104 offset:46368
	ds_read_b64_tr_b16 v[210:211], v104 offset:48672
	v_fmamk_f32 v54, v54, 0x3fb8aa3b, v107
	v_fmamk_f32 v55, v55, 0x3fb8aa3b, v108
	v_fmamk_f32 v56, v56, 0x3fb8aa3b, v109
	v_fmamk_f32 v57, v57, 0x3fb8aa3b, v110
	v_fmamk_f32 v58, v58, 0x3fb8aa3b, v111
	v_fmamk_f32 v59, v59, 0x3fb8aa3b, v112
	v_fmamk_f32 v60, v60, 0x3fb8aa3b, v113
	v_fmamk_f32 v61, v61, 0x3fb8aa3b, v133
	v_cmp_le_i32_e32 vcc, 0, v78
	s_nop 1
	v_cndmask_b32_e32 v54, v243, v54, vcc
	v_cmp_le_i32_e32 vcc, 1, v78
	s_nop 1
	v_cndmask_b32_e32 v55, v243, v55, vcc
	v_cmp_le_i32_e32 vcc, 2, v78
	s_nop 1
	v_cndmask_b32_e32 v56, v243, v56, vcc
	v_cmp_le_i32_e32 vcc, 3, v78
	s_nop 1
	v_cndmask_b32_e32 v57, v243, v57, vcc
	v_cmp_le_i32_e32 vcc, 16, v78
	s_nop 1
	v_cndmask_b32_e32 v58, v243, v58, vcc
	v_cmp_le_i32_e32 vcc, 17, v78
	s_nop 1
	v_cndmask_b32_e32 v59, v243, v59, vcc
	v_cmp_le_i32_e32 vcc, 18, v78
	s_nop 1
	v_cndmask_b32_e32 v60, v243, v60, vcc
	v_cmp_le_i32_e32 vcc, 19, v78
	s_nop 1
	v_cndmask_b32_e32 v61, v243, v61, vcc
	v_subrev_u32_e32 v107, 32, v78
	v_min_u32_e32 v107, 0x3ff, v107
	v_lshl_add_u32 v107, v107, 2, v131
	ds_read_b32 v107, v107
	v_subrev_u32_e32 v108, 33, v78
	v_min_u32_e32 v108, 0x3ff, v108
	v_lshl_add_u32 v108, v108, 2, v131
	ds_read_b32 v108, v108
	v_subrev_u32_e32 v109, 34, v78
	v_min_u32_e32 v109, 0x3ff, v109
	v_lshl_add_u32 v109, v109, 2, v131
	ds_read_b32 v109, v109
	v_subrev_u32_e32 v110, 35, v78
	v_min_u32_e32 v110, 0x3ff, v110
	v_lshl_add_u32 v110, v110, 2, v131
	ds_read_b32 v110, v110
	v_subrev_u32_e32 v111, 48, v78
	v_min_u32_e32 v111, 0x3ff, v111
	v_lshl_add_u32 v111, v111, 2, v131
	ds_read_b32 v111, v111
	v_subrev_u32_e32 v112, 49, v78
	v_min_u32_e32 v112, 0x3ff, v112
	v_lshl_add_u32 v112, v112, 2, v131
	ds_read_b32 v112, v112
	v_subrev_u32_e32 v113, 50, v78
	v_min_u32_e32 v113, 0x3ff, v113
	v_lshl_add_u32 v113, v113, 2, v131
	ds_read_b32 v113, v113
	v_subrev_u32_e32 v133, 51, v78
	v_min_u32_e32 v133, 0x3ff, v133
	v_lshl_add_u32 v133, v133, 2, v131
	ds_read_b32 v133, v133
	ds_read_b64_tr_b16 v[212:213], v104 offset:50976
	ds_read_b64_tr_b16 v[214:215], v104 offset:44096
	ds_read_b64_tr_b16 v[216:217], v104 offset:46400
	ds_read_b64_tr_b16 v[218:219], v104 offset:48704
	ds_read_b64_tr_b16 v[220:221], v104 offset:51008
	ds_read_b64_tr_b16 v[222:223], v104 offset:44128
	ds_read_b64_tr_b16 v[224:225], v104 offset:46432
	ds_read_b64_tr_b16 v[226:227], v104 offset:48736
	ds_read_b64_tr_b16 v[228:229], v104 offset:51040
	s_waitcnt lgkmcnt(9)
; __device__ __forceinline__ unsigned cvt_pk_bf16(float lo, float hi) { unsigned r; asm("v_cvt_pk_bf16_f32 %0, %1, %2" : "=v"(r) : "v"(lo), "v"(hi)); return r; }
; template <int D, class SF>
; __device__ __forceinline__ void attn_step(const bf16x8 (&qf)[D / 32], const LAS bf16_t* Ks, const LAS bf16_t* Vt, f32x4 (&o)[D / 16], float& m, float& lsum, float& alpha_out, bf16x8& pf0_out, bf16x8& pf1_out, const int lane, SF sf) {
;     ...
;         for (int r = 0; r < 4; ++r) v[4 * t + r] = sf(16 * t + 4 * i + r, s[t][r]);
;     float mx = fmaxf(fmaxf(fmaxf(v[0], v[1]), fmaxf(v[2], v[3])), fmaxf(fmaxf(v[4], v[5]), fmaxf(v[6], v[7])));
;     mx = fmaxf(mx, fmaxf(fmaxf(fmaxf(v[8], v[9]), fmaxf(v[10], v[11])), fmaxf(fmaxf(v[12], v[13]), fmaxf(v[14], v[15]))));
;     mx = rows_max(mx);
;     const float mnew = fmaxf(m, mx);
;     const float mc = fmaxf(mnew, -1e20f);
;     const float alpha = __builtin_amdgcn_exp2f(fmaxf(m, -1e20f) - mc);
;     float p[16], rs = 0.f;
; #pragma unroll
;     for (int r = 0; r < 16; ++r) { p[r] = __builtin_amdgcn_exp2f(v[r] - mc); rs += p[r]; }
;     rs = rows_sum(rs);
;     lsum = lsum * alpha + rs; m = mnew;
;     union { u32x4 u; bf16x8 b; } pk0, pk1;
;     pk0.u.x = cvt_pk_bf16(p[0], p[1]); pk0.u.y = cvt_pk_bf16(p[2], p[3]); pk0.u.z = cvt_pk_bf16(p[4], p[5]); pk0.u.w = cvt_pk_bf16(p[6], p[7]);
;     pk1.u.x = cvt_pk_bf16(p[8], p[9]); pk1.u.y = cvt_pk_bf16(p[10], p[11]); pk1.u.z = cvt_pk_bf16(p[12], p[13]); pk1.u.w = cvt_pk_bf16(p[14], p[15]);
;     if (__builtin_amdgcn_ballot_w64(alpha != 1.0f) != 0ull) {
; #pragma unroll
;         for (int dt = 0; dt < D / 16; ++dt) o[dt] *= alpha;
;     }
	v_fmamk_f32 v62, v62, 0x3fb8aa3b, v107
	v_fmamk_f32 v63, v63, 0x3fb8aa3b, v108
	v_fmamk_f32 v64, v64, 0x3fb8aa3b, v109
	v_fmamk_f32 v65, v65, 0x3fb8aa3b, v110
	v_fmamk_f32 v66, v66, 0x3fb8aa3b, v111
	v_fmamk_f32 v67, v67, 0x3fb8aa3b, v112
	v_fmamk_f32 v68, v68, 0x3fb8aa3b, v113
	v_fmamk_f32 v69, v69, 0x3fb8aa3b, v133
	v_cmp_le_i32_e32 vcc, 32, v78
	s_nop 1
	v_cndmask_b32_e32 v62, v243, v62, vcc
	v_cmp_le_i32_e32 vcc, 33, v78
	s_nop 1
	v_cndmask_b32_e32 v63, v243, v63, vcc
	v_cmp_le_i32_e32 vcc, 34, v78
	s_nop 1
	v_cndmask_b32_e32 v64, v243, v64, vcc
	v_cmp_le_i32_e32 vcc, 35, v78
	s_nop 1
	v_cndmask_b32_e32 v65, v243, v65, vcc
	v_cmp_le_i32_e32 vcc, 48, v78
	s_nop 1
	v_cndmask_b32_e32 v66, v243, v66, vcc
	v_cmp_le_i32_e32 vcc, 49, v78
	s_nop 1
	v_cndmask_b32_e32 v67, v243, v67, vcc
	v_cmp_le_i32_e32 vcc, 50, v78
	s_nop 1
	v_cndmask_b32_e32 v68, v243, v68, vcc
	v_cmp_le_i32_e32 vcc, 51, v78
	s_nop 1
	v_cndmask_b32_e32 v69, v243, v69, vcc
	v_max3_f32 v84, v54, v55, v56
	v_max3_f32 v79, v57, v58, v59
	v_max3_f32 v80, v60, v61, v62
	v_max3_f32 v81, v63, v64, v65
	v_max3_f32 v83, v66, v67, v68
	v_max3_f32 v84, v84, v79, v69
	v_max3_f32 v80, v80, v81, v83
	v_max_f32_e32 v84, v84, v80
	v_mov_b32_e32 v79, v84
	s_nop 1
	v_permlane16_swap_b32_e32 v84, v79
	v_max_f32_e32 v84, v84, v79
	v_mov_b32_e32 v79, v84
	s_nop 1
	v_permlane32_swap_b32_e32 v84, v79
	v_max_f32_e32 v84, v84, v79
	v_cndmask_b32_e64 v84, v243, v84, s[24:25]
	v_max_f32_e32 v80, v100, v84
	v_max_f32_e32 v82, 0xe0ad78ec, v100
	v_max_f32_e32 v81, 0xe0ad78ec, v80
	v_sub_f32_e32 v82, v82, v81
	v_mov_b32_e32 v100, v80
	v_exp_f32_e32 v82, v82
	v_mov_b32_e32 v83, 0x7149f2ca
	v_cndmask_b32_e64 v83, v83, v81, s[24:25]
	v_sub_f32_e32 v54, v54, v83
	v_sub_f32_e32 v55, v55, v83
	v_sub_f32_e32 v56, v56, v83
	v_sub_f32_e32 v57, v57, v83
	v_exp_f32_e32 v54, v54
	v_exp_f32_e32 v55, v55
	v_exp_f32_e32 v56, v56
	v_exp_f32_e32 v57, v57
	v_sub_f32_e32 v58, v58, v83
	v_sub_f32_e32 v59, v59, v83
	v_sub_f32_e32 v60, v60, v83
	v_sub_f32_e32 v61, v61, v83
	v_exp_f32_e32 v58, v58
	v_exp_f32_e32 v59, v59
	v_exp_f32_e32 v60, v60
	v_exp_f32_e32 v61, v61
	v_sub_f32_e32 v62, v62, v83
	v_sub_f32_e32 v63, v63, v83
	v_sub_f32_e32 v64, v64, v83
	v_sub_f32_e32 v65, v65, v83
	v_exp_f32_e32 v62, v62
	v_exp_f32_e32 v63, v63
	v_exp_f32_e32 v64, v64
	v_exp_f32_e32 v65, v65
	v_sub_f32_e32 v66, v66, v83
	v_sub_f32_e32 v67, v67, v83
	v_sub_f32_e32 v68, v68, v83
	v_sub_f32_e32 v69, v69, v83
	v_exp_f32_e32 v66, v66
	v_exp_f32_e32 v67, v67
	v_exp_f32_e32 v68, v68
	v_exp_f32_e32 v69, v69
	s_nop 0
	v_add_f32_e32 v78, v54, v55
	v_add_f32_e32 v79, v56, v57
	v_add_f32_e32 v80, v58, v59
	v_add_f32_e32 v81, v60, v61
	v_add_f32_e32 v78, v78, v62
	v_add_f32_e32 v79, v79, v63
	v_add_f32_e32 v80, v80, v64
	v_add_f32_e32 v81, v81, v65
	v_add_f32_e32 v78, v78, v66
	v_add_f32_e32 v79, v79, v67
	v_add_f32_e32 v80, v80, v68
	v_add_f32_e32 v81, v81, v69
	v_add_f32_e32 v78, v78, v79
	v_add_f32_e32 v80, v80, v81
	v_add_f32_e32 v78, v78, v80
	v_cvt_pk_bf16_f32 v70, v54, v55
	v_cvt_pk_bf16_f32 v71, v56, v57
	v_cvt_pk_bf16_f32 v72, v58, v59
	v_cvt_pk_bf16_f32 v73, v60, v61
	v_cvt_pk_bf16_f32 v74, v62, v63
	v_cvt_pk_bf16_f32 v75, v64, v65
	v_cvt_pk_bf16_f32 v76, v66, v67
	v_cvt_pk_bf16_f32 v77, v68, v69
	v_mov_b32_e32 v79, v78
	s_nop 1
	v_permlane16_swap_b32_e32 v78, v79
	v_add_f32_e32 v78, v78, v79
	v_mov_b32_e32 v79, v78
	s_nop 1
	v_permlane32_swap_b32_e32 v78, v79
	v_add_f32_e32 v78, v78, v79
	v_fma_f32 v106, v106, v82, v78
	v_cmp_neq_f32_e64 s[4:5], 1.0, v82
	s_cmp_eq_u64 s[4:5], 0
	s_cbranch_scc1 .Lsl2_nosc_34
	v_pk_mul_f32 v[38:39], v[38:39], v[82:83] op_sel_hi:[1,0]
	v_pk_mul_f32 v[40:41], v[40:41], v[82:83] op_sel_hi:[1,0]
	v_pk_mul_f32 v[42:43], v[42:43], v[82:83] op_sel_hi:[1,0]
	v_pk_mul_f32 v[44:45], v[44:45], v[82:83] op_sel_hi:[1,0]
	v_pk_mul_f32 v[46:47], v[46:47], v[82:83] op_sel_hi:[1,0]
	v_pk_mul_f32 v[48:49], v[48:49], v[82:83] op_sel_hi:[1,0]
	v_pk_mul_f32 v[50:51], v[50:51], v[82:83] op_sel_hi:[1,0]
	v_pk_mul_f32 v[52:53], v[52:53], v[82:83] op_sel_hi:[1,0]

; #define LAS __attribute__((address_space(3)))
; __device__ __forceinline__ f32x4 mfma16(bf16x8 a, bf16x8 b, f32x4 c) { return __builtin_amdgcn_mfma_f32_16x16x32_bf16(a, b, c, 0, 0, 0); }
; template <int D, class SF>
; __device__ __forceinline__ void attn_step(const bf16x8 (&qf)[D / 32], const LAS bf16_t* Ks, const LAS bf16_t* Vt, f32x4 (&o)[D / 16], float& m, float& lsum, float& alpha_out, bf16x8& pf0_out, bf16x8& pf1_out, const int lane, SF sf) {
;     ...
;     for (int ks = 0; ks < D / 32; ++ks) {
; #pragma unroll
;         for (int t = 0; t < 4; ++t) { const bf16x8 kf = *(const LAS bf16x8*)(Ks + (16 * t + c) * KSTR + ks * 32 + 8 * i); s[t] = mfma16(kf, qf[ks], s[t]); }
;     }
;     float v[16];
; #pragma unroll
;     for (int t = 0; t < 4; ++t)
; #pragma unroll
;         for (int r = 0; r < 4; ++r) v[4 * t + r] = sf(16 * t + 4 * i + r, s[t][r]);
; __device__ __forceinline__ void nsa_unit(LAS unsigned char* lds, const Ctx& P, int l, int b, int hkv, int tb) {
;     ...
;                 for (int sb = 0; sb < 2; ++sb) { const bool selj = (ms[sb] >> j) & 1ull; const int tqs = tq[sb];
;                     if (far) {
;                         if (__builtin_amdgcn_ballot_w64(selj) == 0ull) continue;
;                         attn_step<64>(qf[sb], Ks, Vt, o[sb], m[sb], lsum[sb], alpha, pf, pf1, lane,
;                             [&](int, float s) { return selj ? s * LOG2E + cfar : NEGBIG; });
;                     } else { const int kp0 = j * 64;
;                         attn_step<64>(qf[sb], Ks, Vt, o[sb], m[sb], lsum[sb], alpha, pf, pf1, lane,
;                             [&](int kk, float s) { const int dist = tqs - (kp0 + kk); return (selj && dist >= 0) ? s * LOG2E + lut[min((unsigned)dist, 1023u)] : NEGBIG; });
.Lsl2_skd_33:
	v_lshrrev_b64 v[78:79], s8, v[20:21]
	v_and_b32_e32 v78, 1, v78
	v_cmp_eq_u32_e64 s[24:25], 1, v78
	s_cmp_eq_u64 s[24:25], 0
	s_cbranch_scc1 .Lsl2_skd_35
	v_sub_u32_e32 v78, v98, v139
	v_subrev_u32_e32 v78, s9, v78
	v_subrev_u32_e32 v107, 0, v78
	v_min_u32_e32 v107, 0x3ff, v107
	v_lshl_add_u32 v107, v107, 2, v131
	ds_read_b32 v107, v107
	v_subrev_u32_e32 v108, 1, v78
	v_min_u32_e32 v108, 0x3ff, v108
	v_lshl_add_u32 v108, v108, 2, v131
	ds_read_b32 v108, v108
	v_subrev_u32_e32 v109, 2, v78
	v_min_u32_e32 v109, 0x3ff, v109
	v_lshl_add_u32 v109, v109, 2, v131
	ds_read_b32 v109, v109
	v_subrev_u32_e32 v110, 3, v78
	v_min_u32_e32 v110, 0x3ff, v110
	v_lshl_add_u32 v110, v110, 2, v131
	ds_read_b32 v110, v110
	v_subrev_u32_e32 v111, 16, v78
	v_min_u32_e32 v111, 0x3ff, v111
	v_lshl_add_u32 v111, v111, 2, v131
	ds_read_b32 v111, v111
	v_subrev_u32_e32 v112, 17, v78
	v_min_u32_e32 v112, 0x3ff, v112
	v_lshl_add_u32 v112, v112, 2, v131
	ds_read_b32 v112, v112
	v_subrev_u32_e32 v113, 18, v78
	v_min_u32_e32 v113, 0x3ff, v113
	v_lshl_add_u32 v113, v113, 2, v131
	ds_read_b32 v113, v113
	v_subrev_u32_e32 v133, 19, v78
	v_min_u32_e32 v133, 0x3ff, v133
	v_lshl_add_u32 v133, v133, 2, v131
	ds_read_b32 v133, v133
	ds_read_b128 v[198:201], v102 offset:34816
	ds_read_b128 v[206:209], v102 offset:37120
	ds_read_b128 v[202:205], v102 offset:34880
	ds_read_b128 v[210:213], v102 offset:37184
	ds_read_b128 v[214:217], v102 offset:39424
	ds_read_b128 v[222:225], v102 offset:41728
	ds_read_b128 v[218:221], v102 offset:39488
	ds_read_b128 v[226:229], v102 offset:41792
	s_waitcnt lgkmcnt(6)
	v_mfma_f32_16x16x32_bf16 v[54:57], v[198:201], v[10:13], 0
	v_mfma_f32_16x16x32_bf16 v[58:61], v[206:209], v[10:13], 0
	s_waitcnt lgkmcnt(4)
	v_mfma_f32_16x16x32_bf16 v[54:57], v[202:205], v[14:17], v[54:57]
	v_mfma_f32_16x16x32_bf16 v[58:61], v[210:213], v[14:17], v[58:61]
	s_waitcnt lgkmcnt(2)
	v_mfma_f32_16x16x32_bf16 v[62:65], v[214:217], v[10:13], 0
	v_mfma_f32_16x16x32_bf16 v[66:69], v[222:225], v[10:13], 0
	s_waitcnt lgkmcnt(0)
	v_mfma_f32_16x16x32_bf16 v[62:65], v[218:221], v[14:17], v[62:65]
	v_mfma_f32_16x16x32_bf16 v[66:69], v[226:229], v[14:17], v[66:69]
	ds_read_b64_tr_b16 v[198:199], v104 offset:44032
	ds_read_b64_tr_b16 v[200:201], v104 offset:46336
	ds_read_b64_tr_b16 v[202:203], v104 offset:48640
	ds_read_b64_tr_b16 v[204:205], v104 offset:50944
	ds_read_b64_tr_b16 v[206:207], v104 offset:44064
	ds_read_b64_tr_b16 v[208:209], v104 offset:46368
	ds_read_b64_tr_b16 v[210:211], v104 offset:48672
	v_fmamk_f32 v54, v54, 0x3fb8aa3b, v107
	v_fmamk_f32 v55, v55, 0x3fb8aa3b, v108
	v_fmamk_f32 v56, v56, 0x3fb8aa3b, v109
	v_fmamk_f32 v57, v57, 0x3fb8aa3b, v110
	v_fmamk_f32 v58, v58, 0x3fb8aa3b, v111
	v_fmamk_f32 v59, v59, 0x3fb8aa3b, v112
	v_fmamk_f32 v60, v60, 0x3fb8aa3b, v113
	v_fmamk_f32 v61, v61, 0x3fb8aa3b, v133
	v_cmp_le_i32_e32 vcc, 0, v78
	s_nop 1
	v_cndmask_b32_e32 v54, v243, v54, vcc
	v_cmp_le_i32_e32 vcc, 1, v78
	s_nop 1
	v_cndmask_b32_e32 v55, v243, v55, vcc
	v_cmp_le_i32_e32 vcc, 2, v78
	s_nop 1
	v_cndmask_b32_e32 v56, v243, v56, vcc
	v_cmp_le_i32_e32 vcc, 3, v78
	s_nop 1
	v_cndmask_b32_e32 v57, v243, v57, vcc
	v_cmp_le_i32_e32 vcc, 16, v78
	s_nop 1
	v_cndmask_b32_e32 v58, v243, v58, vcc
	v_cmp_le_i32_e32 vcc, 17, v78
	s_nop 1
	v_cndmask_b32_e32 v59, v243, v59, vcc
	v_cmp_le_i32_e32 vcc, 18, v78
	s_nop 1
	v_cndmask_b32_e32 v60, v243, v60, vcc
	v_cmp_le_i32_e32 vcc, 19, v78
	s_nop 1
	v_cndmask_b32_e32 v61, v243, v61, vcc
	v_subrev_u32_e32 v107, 32, v78
	v_min_u32_e32 v107, 0x3ff, v107
	v_lshl_add_u32 v107, v107, 2, v131
	ds_read_b32 v107, v107
	v_subrev_u32_e32 v108, 33, v78
	v_min_u32_e32 v108, 0x3ff, v108
	v_lshl_add_u32 v108, v108, 2, v131
	ds_read_b32 v108, v108
	v_subrev_u32_e32 v109, 34, v78
	v_min_u32_e32 v109, 0x3ff, v109
	v_lshl_add_u32 v109, v109, 2, v131
	ds_read_b32 v109, v109
	v_subrev_u32_e32 v110, 35, v78
	v_min_u32_e32 v110, 0x3ff, v110
	v_lshl_add_u32 v110, v110, 2, v131
	ds_read_b32 v110, v110
	v_subrev_u32_e32 v111, 48, v78
	v_min_u32_e32 v111, 0x3ff, v111
	v_lshl_add_u32 v111, v111, 2, v131
	ds_read_b32 v111, v111
	v_subrev_u32_e32 v112, 49, v78
	v_min_u32_e32 v112, 0x3ff, v112
	v_lshl_add_u32 v112, v112, 2, v131
	ds_read_b32 v112, v112
	v_subrev_u32_e32 v113, 50, v78
	v_min_u32_e32 v113, 0x3ff, v113
	v_lshl_add_u32 v113, v113, 2, v131
	ds_read_b32 v113, v113
	v_subrev_u32_e32 v133, 51, v78
	v_min_u32_e32 v133, 0x3ff, v133
	v_lshl_add_u32 v133, v133, 2, v131
	ds_read_b32 v133, v133
	ds_read_b64_tr_b16 v[212:213], v104 offset:50976
	ds_read_b64_tr_b16 v[214:215], v104 offset:44096
	ds_read_b64_tr_b16 v[216:217], v104 offset:46400
	ds_read_b64_tr_b16 v[218:219], v104 offset:48704
	ds_read_b64_tr_b16 v[220:221], v104 offset:51008
	ds_read_b64_tr_b16 v[222:223], v104 offset:44128
	ds_read_b64_tr_b16 v[224:225], v104 offset:46432
	ds_read_b64_tr_b16 v[226:227], v104 offset:48736
	ds_read_b64_tr_b16 v[228:229], v104 offset:51040
	s_waitcnt lgkmcnt(9)
; __device__ __forceinline__ unsigned cvt_pk_bf16(float lo, float hi) { unsigned r; asm("v_cvt_pk_bf16_f32 %0, %1, %2" : "=v"(r) : "v"(lo), "v"(hi)); return r; }
; template <int D, class SF>
; __device__ __forceinline__ void attn_step(const bf16x8 (&qf)[D / 32], const LAS bf16_t* Ks, const LAS bf16_t* Vt, f32x4 (&o)[D / 16], float& m, float& lsum, float& alpha_out, bf16x8& pf0_out, bf16x8& pf1_out, const int lane, SF sf) {
;     ...
;         for (int r = 0; r < 4; ++r) v[4 * t + r] = sf(16 * t + 4 * i + r, s[t][r]);
;     float mx = fmaxf(fmaxf(fmaxf(v[0], v[1]), fmaxf(v[2], v[3])), fmaxf(fmaxf(v[4], v[5]), fmaxf(v[6], v[7])));
;     mx = fmaxf(mx, fmaxf(fmaxf(fmaxf(v[8], v[9]), fmaxf(v[10], v[11])), fmaxf(fmaxf(v[12], v[13]), fmaxf(v[14], v[15]))));
;     mx = rows_max(mx);
;     const float mnew = fmaxf(m, mx);
;     const float mc = fmaxf(mnew, -1e20f);
;     const float alpha = __builtin_amdgcn_exp2f(fmaxf(m, -1e20f) - mc);
;     float p[16], rs = 0.f;
; #pragma unroll
;     for (int r = 0; r < 16; ++r) { p[r] = __builtin_amdgcn_exp2f(v[r] - mc); rs += p[r]; }
;     rs = rows_sum(rs);
;     lsum = lsum * alpha + rs; m = mnew;
;     union { u32x4 u; bf16x8 b; } pk0, pk1;
;     pk0.u.x = cvt_pk_bf16(p[0], p[1]); pk0.u.y = cvt_pk_bf16(p[2], p[3]); pk0.u.z = cvt_pk_bf16(p[4], p[5]); pk0.u.w = cvt_pk_bf16(p[6], p[7]);
;     pk1.u.x = cvt_pk_bf16(p[8], p[9]); pk1.u.y = cvt_pk_bf16(p[10], p[11]); pk1.u.z = cvt_pk_bf16(p[12], p[13]); pk1.u.w = cvt_pk_bf16(p[14], p[15]);
;     if (__builtin_amdgcn_ballot_w64(alpha != 1.0f) != 0ull) {
; #pragma unroll
;         for (int dt = 0; dt < D / 16; ++dt) o[dt] *= alpha;
;     }
	v_fmamk_f32 v62, v62, 0x3fb8aa3b, v107
	v_fmamk_f32 v63, v63, 0x3fb8aa3b, v108
	v_fmamk_f32 v64, v64, 0x3fb8aa3b, v109
	v_fmamk_f32 v65, v65, 0x3fb8aa3b, v110
	v_fmamk_f32 v66, v66, 0x3fb8aa3b, v111
	v_fmamk_f32 v67, v67, 0x3fb8aa3b, v112
	v_fmamk_f32 v68, v68, 0x3fb8aa3b, v113
	v_fmamk_f32 v69, v69, 0x3fb8aa3b, v133
	v_cmp_le_i32_e32 vcc, 32, v78
	s_nop 1
	v_cndmask_b32_e32 v62, v243, v62, vcc
	v_cmp_le_i32_e32 vcc, 33, v78
	s_nop 1
	v_cndmask_b32_e32 v63, v243, v63, vcc
	v_cmp_le_i32_e32 vcc, 34, v78
	s_nop 1
	v_cndmask_b32_e32 v64, v243, v64, vcc
	v_cmp_le_i32_e32 vcc, 35, v78
	s_nop 1
	v_cndmask_b32_e32 v65, v243, v65, vcc
	v_cmp_le_i32_e32 vcc, 48, v78
	s_nop 1
	v_cndmask_b32_e32 v66, v243, v66, vcc
	v_cmp_le_i32_e32 vcc, 49, v78
	s_nop 1
	v_cndmask_b32_e32 v67, v243, v67, vcc
	v_cmp_le_i32_e32 vcc, 50, v78
	s_nop 1
	v_cndmask_b32_e32 v68, v243, v68, vcc
	v_cmp_le_i32_e32 vcc, 51, v78
	s_nop 1
	v_cndmask_b32_e32 v69, v243, v69, vcc
	v_max3_f32 v84, v54, v55, v56
	v_max3_f32 v79, v57, v58, v59
	v_max3_f32 v80, v60, v61, v62
	v_max3_f32 v81, v63, v64, v65
	v_max3_f32 v83, v66, v67, v68
	v_max3_f32 v84, v84, v79, v69
	v_max3_f32 v80, v80, v81, v83
	v_max_f32_e32 v84, v84, v80
	v_mov_b32_e32 v79, v84
	s_nop 1
	v_permlane16_swap_b32_e32 v84, v79
	v_max_f32_e32 v84, v84, v79
	v_mov_b32_e32 v79, v84
	s_nop 1
	v_permlane32_swap_b32_e32 v84, v79
	v_max_f32_e32 v84, v84, v79
	v_cndmask_b32_e64 v84, v243, v84, s[24:25]
	v_max_f32_e32 v80, v93, v84
	v_max_f32_e32 v82, 0xe0ad78ec, v93
	v_max_f32_e32 v81, 0xe0ad78ec, v80
	v_sub_f32_e32 v82, v82, v81
	v_mov_b32_e32 v93, v80
	v_exp_f32_e32 v82, v82
	v_mov_b32_e32 v83, 0x7149f2ca
	v_cndmask_b32_e64 v83, v83, v81, s[24:25]
	v_sub_f32_e32 v54, v54, v83
	v_sub_f32_e32 v55, v55, v83
	v_sub_f32_e32 v56, v56, v83
	v_sub_f32_e32 v57, v57, v83
	v_exp_f32_e32 v54, v54
	v_exp_f32_e32 v55, v55
	v_exp_f32_e32 v56, v56
	v_exp_f32_e32 v57, v57
	v_sub_f32_e32 v58, v58, v83
	v_sub_f32_e32 v59, v59, v83
	v_sub_f32_e32 v60, v60, v83
	v_sub_f32_e32 v61, v61, v83
	v_exp_f32_e32 v58, v58
	v_exp_f32_e32 v59, v59
	v_exp_f32_e32 v60, v60
	v_exp_f32_e32 v61, v61
	v_sub_f32_e32 v62, v62, v83
	v_sub_f32_e32 v63, v63, v83
	v_sub_f32_e32 v64, v64, v83
	v_sub_f32_e32 v65, v65, v83
	v_exp_f32_e32 v62, v62
	v_exp_f32_e32 v63, v63
	v_exp_f32_e32 v64, v64
	v_exp_f32_e32 v65, v65
	v_sub_f32_e32 v66, v66, v83
	v_sub_f32_e32 v67, v67, v83
	v_sub_f32_e32 v68, v68, v83
	v_sub_f32_e32 v69, v69, v83
	v_exp_f32_e32 v66, v66
	v_exp_f32_e32 v67, v67
	v_exp_f32_e32 v68, v68
	v_exp_f32_e32 v69, v69
	s_nop 0
	v_add_f32_e32 v78, v54, v55
	v_add_f32_e32 v79, v56, v57
	v_add_f32_e32 v80, v58, v59
	v_add_f32_e32 v81, v60, v61
	v_add_f32_e32 v78, v78, v62
	v_add_f32_e32 v79, v79, v63
	v_add_f32_e32 v80, v80, v64
	v_add_f32_e32 v81, v81, v65
	v_add_f32_e32 v78, v78, v66
	v_add_f32_e32 v79, v79, v67
	v_add_f32_e32 v80, v80, v68
	v_add_f32_e32 v81, v81, v69
	v_add_f32_e32 v78, v78, v79
	v_add_f32_e32 v80, v80, v81
	v_add_f32_e32 v78, v78, v80
	v_cvt_pk_bf16_f32 v70, v54, v55
	v_cvt_pk_bf16_f32 v71, v56, v57
	v_cvt_pk_bf16_f32 v72, v58, v59
	v_cvt_pk_bf16_f32 v73, v60, v61
	v_cvt_pk_bf16_f32 v74, v62, v63
	v_cvt_pk_bf16_f32 v75, v64, v65
	v_cvt_pk_bf16_f32 v76, v66, v67
	v_cvt_pk_bf16_f32 v77, v68, v69
	v_mov_b32_e32 v79, v78
	s_nop 1
	v_permlane16_swap_b32_e32 v78, v79
	v_add_f32_e32 v78, v78, v79
	v_mov_b32_e32 v79, v78
	s_nop 1
	v_permlane32_swap_b32_e32 v78, v79
	v_add_f32_e32 v78, v78, v79
	v_fma_f32 v105, v105, v82, v78
	v_cmp_neq_f32_e64 s[4:5], 1.0, v82
	s_cmp_eq_u64 s[4:5], 0
	s_cbranch_scc1 .Lsl2_nosc_36
	v_pk_mul_f32 v[22:23], v[22:23], v[82:83] op_sel_hi:[1,0]
	v_pk_mul_f32 v[24:25], v[24:25], v[82:83] op_sel_hi:[1,0]
	v_pk_mul_f32 v[26:27], v[26:27], v[82:83] op_sel_hi:[1,0]
	v_pk_mul_f32 v[28:29], v[28:29], v[82:83] op_sel_hi:[1,0]
	v_pk_mul_f32 v[34:35], v[34:35], v[82:83] op_sel_hi:[1,0]
	v_pk_mul_f32 v[36:37], v[36:37], v[82:83] op_sel_hi:[1,0]
	v_pk_mul_f32 v[30:31], v[30:31], v[82:83] op_sel_hi:[1,0]
	v_pk_mul_f32 v[32:33], v[32:33], v[82:83] op_sel_hi:[1,0]

; __device__ __forceinline__ void nsa_unit(LAS unsigned char* lds, const Ctx& P, int l, int b, int hkv, int tb) {
;     ...
;         while (Ur != 0ull) {
;             const int ja = __builtin_ctzll(Ur); Ur &= Ur - 1ull; const bool hasb = Ur != 0ull; int jb = 0; if (hasb) { jb = __builtin_ctzll(Ur); Ur &= Ur - 1ull; }
;             __syncthreads();
;             load2(kb, vb, LDH, ja * 64, jb * 64, hasb, SEQ - 1);
;             __syncthreads();
.Lsl2_skd_35:
.Lsl2_doneb_22:
.Lsl2_skipb_21:
	s_bitcmp1_b32 s13, 0
	s_cbranch_scc1 .Lsl2_top
	s_nop 7

; #define LAS __attribute__((address_space(3)))
; __device__ __forceinline__ f32x4 mfma16(bf16x8 a, bf16x8 b, f32x4 c) { return __builtin_amdgcn_mfma_f32_16x16x32_bf16(a, b, c, 0, 0, 0); }
; template <int D, class SF>
; __device__ __forceinline__ void attn_step(const bf16x8 (&qf)[D / 32], const LAS bf16_t* Ks, const LAS bf16_t* Vt, f32x4 (&o)[D / 16], float& m, float& lsum, float& alpha_out, bf16x8& pf0_out, bf16x8& pf1_out, const int lane, SF sf) {
;     ...
;     for (int ks = 0; ks < D / 32; ++ks) {
; #pragma unroll
;         for (int t = 0; t < 4; ++t) { const bf16x8 kf = *(const LAS bf16x8*)(Ks + (16 * t + c) * KSTR + ks * 32 + 8 * i); s[t] = mfma16(kf, qf[ks], s[t]); }
;     }
;     float v[16];
; #pragma unroll
;     for (int t = 0; t < 4; ++t)
; #pragma unroll
;         for (int r = 0; r < 4; ++r) v[4 * t + r] = sf(16 * t + 4 * i + r, s[t][r]);
; __device__ __forceinline__ void nsa_unit(LAS unsigned char* lds, const Ctx& P, int l, int b, int hkv, int tb) {
;     ...
;         const bf16_t* kb = H + (size_t)b * SEQ * LDH + C_KW + hkv * 64; const bf16_t* vb = H + (size_t)b * SEQ * LDH + C_VW + hkv * 64;
;         const int kfirst = (t0 >= 256) ? 0 : (256 - t0) / 64;
;         for (int k = kfirst; k < 5; k += 2) { const int p0 = t0 - 256 + 64 * k; const bool hasb = k + 1 < 5;
;             __syncthreads();
;             load2(kb, vb, LDH, p0, p0 + 64, hasb, SEQ - 1);
;             __syncthreads();
; #pragma unroll
;             for (int sl = 0; sl < 2; ++sl) if (sl == 0 || hasb) { const LAS bf16_t* Ks = KV + sl * 9216; const LAS bf16_t* Vt = Ks + 4608; const int kp0 = p0 + sl * 64;
; #pragma unroll
;                 for (int sb = 0; sb < 2; ++sb) { const int tqs = tq[sb];
;                     attn_step<64>(qf[sb], Ks, Vt, o[sb], m[sb], lsum[sb], alpha, pf, pf1, lane,
;                         [&](int kk, float s) { const int kpos = kp0 + kk, dist = tqs - kpos; return (dist >= 0 && dist < 256 && kpos >= 0) ? s * LOG2E + lut[min((unsigned)dist, 1023u)] : NEGBIG; }); }
.LBB0_601:
	s_add_i32 s20, s44, 2
	s_add_i32 s12, s55, 0xffffff00
	v_add_u32_e32 v178, v150, v148
	v_lshrrev_b32_e32 v90, 2, v97
	v_lshl_add_u32 v90, v103, 2, v90
	v_mul_u32_u24_e32 v90, 0x90, v90
	v_and_b32_e32 v91, 3, v97
	v_lshl_add_u32 v179, v91, 3, v90
	v_mov_b32_e32 v180, v98
	v_add_u32_e32 v116, 0xc000, v178
	v_add_u32_e32 v117, 0xc000, v179
	v_add_u32_e32 v181, 0xc000, v146
	s_cmp_gt_u32 s20, 0
	s_cbranch_scc1 .Lwn_wl_1
	s_add_i32 s4, s12, 0
	v_add_u32_e32 v92, s4, v144
	v_mul_lo_u32 v92, v92, s75
	v_mov_b32_e32 v93, v1
	v_lshl_add_u64 v[92:93], v[92:93], 1, v[134:135]
	global_load_dwordx4 v[50:53], v[92:93], off
	global_load_dwordx4 v[54:57], v[92:93], off offset:512
.Lwn_wl_1:
	s_cmp_gt_u32 s20, 1
	s_cbranch_scc1 .Lwn_wl_2
	s_add_i32 s4, s12, 64
	v_add_u32_e32 v92, s4, v144
	v_mul_lo_u32 v92, v92, s75
	v_mov_b32_e32 v93, v1
	v_lshl_add_u64 v[92:93], v[92:93], 1, v[134:135]
	global_load_dwordx4 v[58:61], v[92:93], off
	global_load_dwordx4 v[62:65], v[92:93], off offset:512
.Lwn_wl_2:
	s_cmp_gt_u32 s20, 2
	s_cbranch_scc1 .Lwn_wl_3
	s_add_i32 s4, s12, 128
	v_add_u32_e32 v92, s4, v144
	v_mul_lo_u32 v92, v92, s75
	v_mov_b32_e32 v93, v1
	v_lshl_add_u64 v[92:93], v[92:93], 1, v[134:135]
	global_load_dwordx4 v[66:69], v[92:93], off
	global_load_dwordx4 v[70:73], v[92:93], off offset:512
.Lwn_wl_3:
	s_cmp_gt_u32 s20, 3
	s_cbranch_scc1 .Lwn_wl_4
	s_add_i32 s4, s12, 192
	v_add_u32_e32 v92, s4, v144
	v_mul_lo_u32 v92, v92, s75
	v_mov_b32_e32 v93, v1
	v_lshl_add_u64 v[92:93], v[92:93], 1, v[134:135]
	global_load_dwordx4 v[74:77], v[92:93], off
	global_load_dwordx4 v[78:81], v[92:93], off offset:512
.Lwn_wl_4:
	s_cmp_gt_u32 s20, 4
	s_cbranch_scc1 .Lwn_wl_5
	s_add_i32 s4, s12, 256
	v_add_u32_e32 v92, s4, v144
	v_mul_lo_u32 v92, v92, s75
	v_mov_b32_e32 v93, v1
	v_lshl_add_u64 v[92:93], v[92:93], 1, v[134:135]
	global_load_dwordx4 v[100:103], v[92:93], off
	global_load_dwordx4 v[104:107], v[92:93], off offset:512
.Lwn_wl_5:
	s_waitcnt lgkmcnt(0)
	s_barrier
	s_waitcnt vmcnt(0)
	s_cmp_gt_u32 s20, 0
	s_cbranch_scc1 .Lwn_ww_6
	ds_write_b128 v146, v[50:53] offset:16384
	ds_write_b128 v146, v[54:57] offset:25600
.Lwn_ww_6:
	s_cmp_gt_u32 s20, 1
	s_cbranch_scc1 .Lwn_ww_7
	ds_write_b128 v146, v[58:61] offset:34816
	ds_write_b128 v146, v[62:65] offset:44032
.Lwn_ww_7:
	s_cmp_gt_u32 s20, 2
	s_cbranch_scc1 .Lwn_ww_8
	ds_write_b128 v181, v[66:69] offset:4096
	ds_write_b128 v181, v[70:73] offset:13312
.Lwn_ww_8:
	s_cmp_gt_u32 s20, 3
	s_cbranch_scc1 .Lwn_ww_9
	ds_write_b128 v181, v[74:77] offset:22528
	ds_write_b128 v181, v[78:81] offset:31744
.Lwn_ww_9:
	s_cmp_gt_u32 s20, 4
	s_cbranch_scc1 .Lwn_ww_10
	ds_write_b128 v181, v[100:103] offset:40960
	ds_write_b128 v181, v[104:107] offset:50176
.Lwn_ww_10:
	s_waitcnt lgkmcnt(0)
	s_barrier
	s_mov_b64 s[24:25], -1
	s_cmp_gt_u32 s20, 0
	s_cbranch_scc1 .Lwn_wc_11
	s_add_i32 s21, s12, 0
	v_sub_u32_e32 v90, v130, v139
	v_subrev_u32_e32 v90, s21, v90
	v_lshl_add_u32 v91, v90, 2, v131
	v_add_u32_e32 v91, 0xffffff34, v91
	v_add_u32_e32 v97, 0xffffff01, v90
	ds_read_b32 v170, v91 offset:204
	ds_read_b32 v171, v91 offset:200
	ds_read_b32 v172, v91 offset:196
	ds_read_b32 v173, v91 offset:192
	ds_read_b32 v174, v91 offset:140
	ds_read_b32 v175, v91 offset:136
	ds_read_b32 v176, v91 offset:132
	ds_read_b32 v177, v91 offset:128
	ds_read_b128 v[50:53], v178 offset:16384
	ds_read_b128 v[58:61], v178 offset:18688
	ds_read_b128 v[54:57], v178 offset:16448
	ds_read_b128 v[62:65], v178 offset:18752
	ds_read_b128 v[66:69], v178 offset:20992
	ds_read_b128 v[74:77], v178 offset:23296
	ds_read_b128 v[70:73], v178 offset:21056
	ds_read_b128 v[78:81], v178 offset:23360
	s_waitcnt lgkmcnt(6)
	v_mfma_f32_16x16x32_bf16 v[100:103], v[50:53], v[2:5], 0
	v_mfma_f32_16x16x32_bf16 v[104:107], v[58:61], v[2:5], 0
	s_waitcnt lgkmcnt(4)
	v_mfma_f32_16x16x32_bf16 v[100:103], v[54:57], v[6:9], v[100:103]
	v_mfma_f32_16x16x32_bf16 v[104:107], v[62:65], v[6:9], v[104:107]
	s_waitcnt lgkmcnt(2)
	v_mfma_f32_16x16x32_bf16 v[108:111], v[66:69], v[2:5], 0
	v_mfma_f32_16x16x32_bf16 v[112:115], v[74:77], v[2:5], 0
	s_waitcnt lgkmcnt(0)
	v_mfma_f32_16x16x32_bf16 v[108:111], v[70:73], v[6:9], v[108:111]
	v_mfma_f32_16x16x32_bf16 v[112:115], v[78:81], v[6:9], v[112:115]
	ds_read_b64_tr_b16 v[50:51], v179 offset:25600
	ds_read_b64_tr_b16 v[52:53], v179 offset:27904
	ds_read_b64_tr_b16 v[54:55], v179 offset:30208
	ds_read_b64_tr_b16 v[56:57], v179 offset:32512
	ds_read_b64_tr_b16 v[58:59], v179 offset:25632
	ds_read_b64_tr_b16 v[60:61], v179 offset:27936
	ds_read_b64_tr_b16 v[62:63], v179 offset:30240
	v_fmamk_f32 v100, v100, 0x3fb8aa3b, v170
	v_fmamk_f32 v101, v101, 0x3fb8aa3b, v171
	v_fmamk_f32 v102, v102, 0x3fb8aa3b, v172
	v_fmamk_f32 v103, v103, 0x3fb8aa3b, v173
	v_fmamk_f32 v104, v104, 0x3fb8aa3b, v174
	v_fmamk_f32 v105, v105, 0x3fb8aa3b, v175
	v_fmamk_f32 v106, v106, 0x3fb8aa3b, v176
	v_fmamk_f32 v107, v107, 0x3fb8aa3b, v177
	v_cmp_ge_i32_e32 vcc, 0, v97
	s_nop 1
	v_cndmask_b32_e32 v100, v243, v100, vcc
	v_cmp_ge_i32_e32 vcc, 1, v97
	s_nop 1
	v_cndmask_b32_e32 v101, v243, v101, vcc
	v_cmp_ge_i32_e32 vcc, 2, v97
	s_nop 1
	v_cndmask_b32_e32 v102, v243, v102, vcc
	v_cmp_ge_i32_e32 vcc, 3, v97
	s_nop 1
	v_cndmask_b32_e32 v103, v243, v103, vcc
	v_cmp_ge_i32_e32 vcc, 16, v97
	s_nop 1
	v_cndmask_b32_e32 v104, v243, v104, vcc
	v_cmp_ge_i32_e32 vcc, 17, v97
	s_nop 1
	v_cndmask_b32_e32 v105, v243, v105, vcc
	v_cmp_ge_i32_e32 vcc, 18, v97
	s_nop 1
	v_cndmask_b32_e32 v106, v243, v106, vcc
	v_cmp_ge_i32_e32 vcc, 19, v97
	s_nop 1
	v_cndmask_b32_e32 v107, v243, v107, vcc
	ds_read_b32 v170, v91 offset:76
	ds_read_b32 v171, v91 offset:72
	ds_read_b32 v172, v91 offset:68
	ds_read_b32 v173, v91 offset:64
	ds_read_b32 v174, v91 offset:12
	ds_read_b32 v175, v91 offset:8
	ds_read_b32 v176, v91 offset:4
	ds_read_b32 v177, v91 offset:0
	ds_read_b64_tr_b16 v[64:65], v179 offset:32544
	ds_read_b64_tr_b16 v[66:67], v179 offset:25664
	ds_read_b64_tr_b16 v[68:69], v179 offset:27968
	ds_read_b64_tr_b16 v[70:71], v179 offset:30272
	ds_read_b64_tr_b16 v[72:73], v179 offset:32576
	ds_read_b64_tr_b16 v[74:75], v179 offset:25696
	ds_read_b64_tr_b16 v[76:77], v179 offset:28000
	ds_read_b64_tr_b16 v[78:79], v179 offset:30304
	ds_read_b64_tr_b16 v[80:81], v179 offset:32608
	s_waitcnt lgkmcnt(9)
; #define LAS __attribute__((address_space(3)))
; __device__ __forceinline__ unsigned cvt_pk_bf16(float lo, float hi) { unsigned r; asm("v_cvt_pk_bf16_f32 %0, %1, %2" : "=v"(r) : "v"(lo), "v"(hi)); return r; }
; __device__ __forceinline__ f32x4 mfma16(bf16x8 a, bf16x8 b, f32x4 c) { return __builtin_amdgcn_mfma_f32_16x16x32_bf16(a, b, c, 0, 0, 0); }
; template <int D, class SF>
; __device__ __forceinline__ void attn_step(const bf16x8 (&qf)[D / 32], const LAS bf16_t* Ks, const LAS bf16_t* Vt, f32x4 (&o)[D / 16], float& m, float& lsum, float& alpha_out, bf16x8& pf0_out, bf16x8& pf1_out, const int lane, SF sf) {
;     ...
;         for (int r = 0; r < 4; ++r) v[4 * t + r] = sf(16 * t + 4 * i + r, s[t][r]);
;     float mx = fmaxf(fmaxf(fmaxf(v[0], v[1]), fmaxf(v[2], v[3])), fmaxf(fmaxf(v[4], v[5]), fmaxf(v[6], v[7])));
;     mx = fmaxf(mx, fmaxf(fmaxf(fmaxf(v[8], v[9]), fmaxf(v[10], v[11])), fmaxf(fmaxf(v[12], v[13]), fmaxf(v[14], v[15]))));
;     mx = rows_max(mx);
;     const float mnew = fmaxf(m, mx);
;     const float mc = fmaxf(mnew, -1e20f);
;     const float alpha = __builtin_amdgcn_exp2f(fmaxf(m, -1e20f) - mc);
;     float p[16], rs = 0.f;
; #pragma unroll
;     for (int r = 0; r < 16; ++r) { p[r] = __builtin_amdgcn_exp2f(v[r] - mc); rs += p[r]; }
;     rs = rows_sum(rs);
;     lsum = lsum * alpha + rs; m = mnew;
;     union { u32x4 u; bf16x8 b; } pk0, pk1;
;     pk0.u.x = cvt_pk_bf16(p[0], p[1]); pk0.u.y = cvt_pk_bf16(p[2], p[3]); pk0.u.z = cvt_pk_bf16(p[4], p[5]); pk0.u.w = cvt_pk_bf16(p[6], p[7]);
;     pk1.u.x = cvt_pk_bf16(p[8], p[9]); pk1.u.y = cvt_pk_bf16(p[10], p[11]); pk1.u.z = cvt_pk_bf16(p[12], p[13]); pk1.u.w = cvt_pk_bf16(p[14], p[15]);
;     if (__builtin_amdgcn_ballot_w64(alpha != 1.0f) != 0ull) {
; #pragma unroll
;         for (int dt = 0; dt < D / 16; ++dt) o[dt] *= alpha;
;     }
; #pragma unroll
;     for (int dt = 0; dt < D / 16; ++dt) {
;         const LAS bf16_t* vp = Vt + (16 * dt + c) * 72 + 4 * i;
;         union { u32x4 u; bf16x8 b; } vf0, vf1; const u32x2 a0 = *(const LAS u32x2*)vp, a1 = *(const LAS u32x2*)(vp + 16), b0 = *(const LAS u32x2*)(vp + 32), b1 = *(const LAS u32x2*)(vp + 48);
;         vf0.u.x = a0.x; vf0.u.y = a0.y; vf0.u.z = a1.x; vf0.u.w = a1.y; vf1.u.x = b0.x; vf1.u.y = b0.y; vf1.u.z = b1.x; vf1.u.w = b1.y;
;         o[dt] = mfma16(vf0.b, pk0.b, o[dt]); o[dt] = mfma16(vf1.b, pk1.b, o[dt]);
;     }
	v_fmamk_f32 v108, v108, 0x3fb8aa3b, v170
	v_fmamk_f32 v109, v109, 0x3fb8aa3b, v171
	v_fmamk_f32 v110, v110, 0x3fb8aa3b, v172
	v_fmamk_f32 v111, v111, 0x3fb8aa3b, v173
	v_fmamk_f32 v112, v112, 0x3fb8aa3b, v174
	v_fmamk_f32 v113, v113, 0x3fb8aa3b, v175
	v_fmamk_f32 v114, v114, 0x3fb8aa3b, v176
	v_fmamk_f32 v115, v115, 0x3fb8aa3b, v177
	v_cmp_ge_i32_e32 vcc, 32, v97
	s_nop 1
	v_cndmask_b32_e32 v108, v243, v108, vcc
	v_cmp_ge_i32_e32 vcc, 33, v97
	s_nop 1
	v_cndmask_b32_e32 v109, v243, v109, vcc
	v_cmp_ge_i32_e32 vcc, 34, v97
	s_nop 1
	v_cndmask_b32_e32 v110, v243, v110, vcc
	v_cmp_ge_i32_e32 vcc, 35, v97
	s_nop 1
	v_cndmask_b32_e32 v111, v243, v111, vcc
	v_cmp_ge_i32_e32 vcc, 48, v97
	s_nop 1
	v_cndmask_b32_e32 v112, v243, v112, vcc
	v_cmp_ge_i32_e32 vcc, 49, v97
	s_nop 1
	v_cndmask_b32_e32 v113, v243, v113, vcc
	v_cmp_ge_i32_e32 vcc, 50, v97
	s_nop 1
	v_cndmask_b32_e32 v114, v243, v114, vcc
	v_cmp_ge_i32_e32 vcc, 51, v97
	s_nop 1
	v_cndmask_b32_e32 v115, v243, v115, vcc
	v_max3_f32 v96, v100, v101, v102
	v_max3_f32 v91, v103, v104, v105
	v_max3_f32 v92, v106, v107, v108
	v_max3_f32 v93, v109, v110, v111
	v_max3_f32 v95, v112, v113, v114
	v_max3_f32 v96, v96, v91, v115
	v_max3_f32 v92, v92, v93, v95
	v_max_f32_e32 v96, v96, v92
	v_mov_b32_e32 v91, v96
	s_nop 1
	v_permlane16_swap_b32_e32 v96, v91
	v_max_f32_e32 v96, v96, v91
	v_mov_b32_e32 v91, v96
	s_nop 1
	v_permlane32_swap_b32_e32 v96, v91
	v_max_f32_e32 v96, v96, v91
	v_max_f32_e32 v92, v162, v96
	v_max_f32_e32 v94, 0xe0ad78ec, v162
	v_max_f32_e32 v93, 0xe0ad78ec, v92
	v_sub_f32_e32 v94, v94, v93
	v_mov_b32_e32 v162, v92
	v_exp_f32_e32 v94, v94
	v_sub_f32_e32 v100, v100, v93
	v_sub_f32_e32 v101, v101, v93
	v_sub_f32_e32 v102, v102, v93
	v_sub_f32_e32 v103, v103, v93
	v_exp_f32_e32 v100, v100
	v_exp_f32_e32 v101, v101
	v_exp_f32_e32 v102, v102
	v_exp_f32_e32 v103, v103
	v_sub_f32_e32 v104, v104, v93
	v_sub_f32_e32 v105, v105, v93
	v_sub_f32_e32 v106, v106, v93
	v_sub_f32_e32 v107, v107, v93
	v_exp_f32_e32 v104, v104
	v_exp_f32_e32 v105, v105
	v_exp_f32_e32 v106, v106
	v_exp_f32_e32 v107, v107
	v_sub_f32_e32 v108, v108, v93
	v_sub_f32_e32 v109, v109, v93
	v_sub_f32_e32 v110, v110, v93
	v_sub_f32_e32 v111, v111, v93
	v_exp_f32_e32 v108, v108
	v_exp_f32_e32 v109, v109
	v_exp_f32_e32 v110, v110
	v_exp_f32_e32 v111, v111
	v_sub_f32_e32 v112, v112, v93
	v_sub_f32_e32 v113, v113, v93
	v_sub_f32_e32 v114, v114, v93
	v_sub_f32_e32 v115, v115, v93
	v_exp_f32_e32 v112, v112
	v_exp_f32_e32 v113, v113
	v_exp_f32_e32 v114, v114
	v_exp_f32_e32 v115, v115
	s_nop 0
	v_add_f32_e32 v90, v100, v101
	v_add_f32_e32 v91, v102, v103
	v_add_f32_e32 v92, v104, v105
	v_add_f32_e32 v93, v106, v107
	v_add_f32_e32 v90, v90, v108
	v_add_f32_e32 v91, v91, v109
	v_add_f32_e32 v92, v92, v110
	v_add_f32_e32 v93, v93, v111
	v_add_f32_e32 v90, v90, v112
	v_add_f32_e32 v91, v91, v113
	v_add_f32_e32 v92, v92, v114
	v_add_f32_e32 v93, v93, v115
	v_add_f32_e32 v90, v90, v91
	v_add_f32_e32 v92, v92, v93
	v_add_f32_e32 v90, v90, v92
	v_cvt_pk_bf16_f32 v82, v100, v101
	v_cvt_pk_bf16_f32 v83, v102, v103
	v_cvt_pk_bf16_f32 v84, v104, v105
	v_cvt_pk_bf16_f32 v85, v106, v107
	v_cvt_pk_bf16_f32 v86, v108, v109
	v_cvt_pk_bf16_f32 v87, v110, v111
	v_cvt_pk_bf16_f32 v88, v112, v113
	v_cvt_pk_bf16_f32 v89, v114, v115
	v_mov_b32_e32 v91, v90
	s_nop 1
	v_permlane16_swap_b32_e32 v90, v91
	v_add_f32_e32 v90, v90, v91
	v_mov_b32_e32 v91, v90
	s_nop 1
	v_permlane32_swap_b32_e32 v90, v91
	v_add_f32_e32 v90, v90, v91
	v_fma_f32 v161, v161, v94, v90
	v_cmp_neq_f32_e64 s[4:5], 1.0, v94
	s_cmp_eq_u64 s[4:5], 0
	s_cbranch_scc1 .Lwn_nosc_12
	v_pk_mul_f32 v[46:47], v[46:47], v[94:95] op_sel_hi:[1,0]
	v_pk_mul_f32 v[48:49], v[48:49], v[94:95] op_sel_hi:[1,0]
	v_pk_mul_f32 v[42:43], v[42:43], v[94:95] op_sel_hi:[1,0]
	v_pk_mul_f32 v[44:45], v[44:45], v[94:95] op_sel_hi:[1,0]
	v_pk_mul_f32 v[38:39], v[38:39], v[94:95] op_sel_hi:[1,0]
	v_pk_mul_f32 v[40:41], v[40:41], v[94:95] op_sel_hi:[1,0]
	v_pk_mul_f32 v[34:35], v[34:35], v[94:95] op_sel_hi:[1,0]
	v_pk_mul_f32 v[36:37], v[36:37], v[94:95] op_sel_hi:[1,0]
.Lwn_nosc_12:
	s_waitcnt lgkmcnt(0)
	s_nop 1
	v_mfma_f32_16x16x32_bf16 v[46:49], v[50:53], v[82:85], v[46:49]
	v_mfma_f32_16x16x32_bf16 v[42:45], v[58:61], v[82:85], v[42:45]
	v_mfma_f32_16x16x32_bf16 v[38:41], v[66:69], v[82:85], v[38:41]
	v_mfma_f32_16x16x32_bf16 v[34:37], v[74:77], v[82:85], v[34:37]
	v_mfma_f32_16x16x32_bf16 v[46:49], v[54:57], v[86:89], v[46:49]
	v_mfma_f32_16x16x32_bf16 v[42:45], v[62:65], v[86:89], v[42:45]
	v_mfma_f32_16x16x32_bf16 v[38:41], v[70:73], v[86:89], v[38:41]
	v_mfma_f32_16x16x32_bf16 v[34:37], v[78:81], v[86:89], v[34:37]
	v_sub_u32_e32 v90, v180, v139
	v_subrev_u32_e32 v90, s21, v90
	v_lshl_add_u32 v91, v90, 2, v131
	v_add_u32_e32 v91, 0xffffff34, v91
	v_add_u32_e32 v97, 0xffffff01, v90
	ds_read_b32 v170, v91 offset:204
	ds_read_b32 v171, v91 offset:200
	ds_read_b32 v172, v91 offset:196
	ds_read_b32 v173, v91 offset:192
	ds_read_b32 v174, v91 offset:140
	ds_read_b32 v175, v91 offset:136
	ds_read_b32 v176, v91 offset:132
	ds_read_b32 v177, v91 offset:128
	ds_read_b128 v[50:53], v178 offset:16384
	ds_read_b128 v[58:61], v178 offset:18688
	ds_read_b128 v[54:57], v178 offset:16448
	ds_read_b128 v[62:65], v178 offset:18752
	ds_read_b128 v[66:69], v178 offset:20992
	ds_read_b128 v[74:77], v178 offset:23296
	ds_read_b128 v[70:73], v178 offset:21056
	ds_read_b128 v[78:81], v178 offset:23360
	s_waitcnt lgkmcnt(6)
	v_mfma_f32_16x16x32_bf16 v[100:103], v[50:53], v[10:13], 0
	v_mfma_f32_16x16x32_bf16 v[104:107], v[58:61], v[10:13], 0
	s_waitcnt lgkmcnt(4)
; #define LAS __attribute__((address_space(3)))
; __device__ __forceinline__ unsigned cvt_pk_bf16(float lo, float hi) { unsigned r; asm("v_cvt_pk_bf16_f32 %0, %1, %2" : "=v"(r) : "v"(lo), "v"(hi)); return r; }
; __device__ __forceinline__ f32x4 mfma16(bf16x8 a, bf16x8 b, f32x4 c) { return __builtin_amdgcn_mfma_f32_16x16x32_bf16(a, b, c, 0, 0, 0); }
; template <int D, class SF>
; __device__ __forceinline__ void attn_step(const bf16x8 (&qf)[D / 32], const LAS bf16_t* Ks, const LAS bf16_t* Vt, f32x4 (&o)[D / 16], float& m, float& lsum, float& alpha_out, bf16x8& pf0_out, bf16x8& pf1_out, const int lane, SF sf) {
;     ...
;     for (int ks = 0; ks < D / 32; ++ks) {
; #pragma unroll
;         for (int t = 0; t < 4; ++t) { const bf16x8 kf = *(const LAS bf16x8*)(Ks + (16 * t + c) * KSTR + ks * 32 + 8 * i); s[t] = mfma16(kf, qf[ks], s[t]); }
;     }
;     float v[16];
; #pragma unroll
;     for (int t = 0; t < 4; ++t)
; #pragma unroll
;         for (int r = 0; r < 4; ++r) v[4 * t + r] = sf(16 * t + 4 * i + r, s[t][r]);
;     float mx = fmaxf(fmaxf(fmaxf(v[0], v[1]), fmaxf(v[2], v[3])), fmaxf(fmaxf(v[4], v[5]), fmaxf(v[6], v[7])));
;     mx = fmaxf(mx, fmaxf(fmaxf(fmaxf(v[8], v[9]), fmaxf(v[10], v[11])), fmaxf(fmaxf(v[12], v[13]), fmaxf(v[14], v[15]))));
;     mx = rows_max(mx);
;     const float mnew = fmaxf(m, mx);
;     const float mc = fmaxf(mnew, -1e20f);
;     const float alpha = __builtin_amdgcn_exp2f(fmaxf(m, -1e20f) - mc);
;     float p[16], rs = 0.f;
; #pragma unroll
;     for (int r = 0; r < 16; ++r) { p[r] = __builtin_amdgcn_exp2f(v[r] - mc); rs += p[r]; }
;     rs = rows_sum(rs);
;     lsum = lsum * alpha + rs; m = mnew;
;     union { u32x4 u; bf16x8 b; } pk0, pk1;
;     pk0.u.x = cvt_pk_bf16(p[0], p[1]); pk0.u.y = cvt_pk_bf16(p[2], p[3]); pk0.u.z = cvt_pk_bf16(p[4], p[5]); pk0.u.w = cvt_pk_bf16(p[6], p[7]);
;     pk1.u.x = cvt_pk_bf16(p[8], p[9]); pk1.u.y = cvt_pk_bf16(p[10], p[11]); pk1.u.z = cvt_pk_bf16(p[12], p[13]); pk1.u.w = cvt_pk_bf16(p[14], p[15]);
;     if (__builtin_amdgcn_ballot_w64(alpha != 1.0f) != 0ull) {
; #pragma unroll
;         for (int dt = 0; dt < D / 16; ++dt) o[dt] *= alpha;
;     }
	v_mfma_f32_16x16x32_bf16 v[100:103], v[54:57], v[14:17], v[100:103]
	v_mfma_f32_16x16x32_bf16 v[104:107], v[62:65], v[14:17], v[104:107]
	s_waitcnt lgkmcnt(2)
	v_mfma_f32_16x16x32_bf16 v[108:111], v[66:69], v[10:13], 0
	v_mfma_f32_16x16x32_bf16 v[112:115], v[74:77], v[10:13], 0
	s_waitcnt lgkmcnt(0)
	v_mfma_f32_16x16x32_bf16 v[108:111], v[70:73], v[14:17], v[108:111]
	v_mfma_f32_16x16x32_bf16 v[112:115], v[78:81], v[14:17], v[112:115]
	ds_read_b64_tr_b16 v[50:51], v179 offset:25600
	ds_read_b64_tr_b16 v[52:53], v179 offset:27904
	ds_read_b64_tr_b16 v[54:55], v179 offset:30208
	ds_read_b64_tr_b16 v[56:57], v179 offset:32512
	ds_read_b64_tr_b16 v[58:59], v179 offset:25632
	ds_read_b64_tr_b16 v[60:61], v179 offset:27936
	ds_read_b64_tr_b16 v[62:63], v179 offset:30240
	v_fmamk_f32 v100, v100, 0x3fb8aa3b, v170
	v_fmamk_f32 v101, v101, 0x3fb8aa3b, v171
	v_fmamk_f32 v102, v102, 0x3fb8aa3b, v172
	v_fmamk_f32 v103, v103, 0x3fb8aa3b, v173
	v_fmamk_f32 v104, v104, 0x3fb8aa3b, v174
	v_fmamk_f32 v105, v105, 0x3fb8aa3b, v175
	v_fmamk_f32 v106, v106, 0x3fb8aa3b, v176
	v_fmamk_f32 v107, v107, 0x3fb8aa3b, v177
	v_cmp_ge_i32_e32 vcc, 0, v97
	s_nop 1
	v_cndmask_b32_e32 v100, v243, v100, vcc
	v_cmp_ge_i32_e32 vcc, 1, v97
	s_nop 1
	v_cndmask_b32_e32 v101, v243, v101, vcc
	v_cmp_ge_i32_e32 vcc, 2, v97
	s_nop 1
	v_cndmask_b32_e32 v102, v243, v102, vcc
	v_cmp_ge_i32_e32 vcc, 3, v97
	s_nop 1
	v_cndmask_b32_e32 v103, v243, v103, vcc
	v_cmp_ge_i32_e32 vcc, 16, v97
	s_nop 1
	v_cndmask_b32_e32 v104, v243, v104, vcc
	v_cmp_ge_i32_e32 vcc, 17, v97
	s_nop 1
	v_cndmask_b32_e32 v105, v243, v105, vcc
	v_cmp_ge_i32_e32 vcc, 18, v97
	s_nop 1
	v_cndmask_b32_e32 v106, v243, v106, vcc
	v_cmp_ge_i32_e32 vcc, 19, v97
	s_nop 1
	v_cndmask_b32_e32 v107, v243, v107, vcc
	ds_read_b32 v170, v91 offset:76
	ds_read_b32 v171, v91 offset:72
	ds_read_b32 v172, v91 offset:68
	ds_read_b32 v173, v91 offset:64
	ds_read_b32 v174, v91 offset:12
	ds_read_b32 v175, v91 offset:8
	ds_read_b32 v176, v91 offset:4
	ds_read_b32 v177, v91 offset:0
	ds_read_b64_tr_b16 v[64:65], v179 offset:32544
	ds_read_b64_tr_b16 v[66:67], v179 offset:25664
	ds_read_b64_tr_b16 v[68:69], v179 offset:27968
	ds_read_b64_tr_b16 v[70:71], v179 offset:30272
	ds_read_b64_tr_b16 v[72:73], v179 offset:32576
	ds_read_b64_tr_b16 v[74:75], v179 offset:25696
	ds_read_b64_tr_b16 v[76:77], v179 offset:28000
	ds_read_b64_tr_b16 v[78:79], v179 offset:30304
	ds_read_b64_tr_b16 v[80:81], v179 offset:32608
	s_waitcnt lgkmcnt(9)
	v_fmamk_f32 v108, v108, 0x3fb8aa3b, v170
	v_fmamk_f32 v109, v109, 0x3fb8aa3b, v171
	v_fmamk_f32 v110, v110, 0x3fb8aa3b, v172
	v_fmamk_f32 v111, v111, 0x3fb8aa3b, v173
	v_fmamk_f32 v112, v112, 0x3fb8aa3b, v174
	v_fmamk_f32 v113, v113, 0x3fb8aa3b, v175
	v_fmamk_f32 v114, v114, 0x3fb8aa3b, v176
	v_fmamk_f32 v115, v115, 0x3fb8aa3b, v177
	v_cmp_ge_i32_e32 vcc, 32, v97
	s_nop 1
	v_cndmask_b32_e32 v108, v243, v108, vcc
	v_cmp_ge_i32_e32 vcc, 33, v97
	s_nop 1
	v_cndmask_b32_e32 v109, v243, v109, vcc
	v_cmp_ge_i32_e32 vcc, 34, v97
	s_nop 1
	v_cndmask_b32_e32 v110, v243, v110, vcc
	v_cmp_ge_i32_e32 vcc, 35, v97
	s_nop 1
	v_cndmask_b32_e32 v111, v243, v111, vcc
	v_cmp_ge_i32_e32 vcc, 48, v97
	s_nop 1
	v_cndmask_b32_e32 v112, v243, v112, vcc
	v_cmp_ge_i32_e32 vcc, 49, v97
	s_nop 1
	v_cndmask_b32_e32 v113, v243, v113, vcc
	v_cmp_ge_i32_e32 vcc, 50, v97
	s_nop 1
	v_cndmask_b32_e32 v114, v243, v114, vcc
	v_cmp_ge_i32_e32 vcc, 51, v97
	s_nop 1
	v_cndmask_b32_e32 v115, v243, v115, vcc
	v_max3_f32 v96, v100, v101, v102
	v_max3_f32 v91, v103, v104, v105
	v_max3_f32 v92, v106, v107, v108
	v_max3_f32 v93, v109, v110, v111
	v_max3_f32 v95, v112, v113, v114
	v_max3_f32 v96, v96, v91, v115
	v_max3_f32 v92, v92, v93, v95
	v_max_f32_e32 v96, v96, v92
	v_mov_b32_e32 v91, v96
	s_nop 1
	v_permlane16_swap_b32_e32 v96, v91
	v_max_f32_e32 v96, v96, v91
	v_mov_b32_e32 v91, v96
	s_nop 1
	v_permlane32_swap_b32_e32 v96, v91
	v_max_f32_e32 v96, v96, v91
	v_max_f32_e32 v92, v160, v96
	v_max_f32_e32 v94, 0xe0ad78ec, v160
	v_max_f32_e32 v93, 0xe0ad78ec, v92
	v_sub_f32_e32 v94, v94, v93
	v_mov_b32_e32 v160, v92
	v_exp_f32_e32 v94, v94
	v_sub_f32_e32 v100, v100, v93
	v_sub_f32_e32 v101, v101, v93
	v_sub_f32_e32 v102, v102, v93
	v_sub_f32_e32 v103, v103, v93
	v_exp_f32_e32 v100, v100
	v_exp_f32_e32 v101, v101
	v_exp_f32_e32 v102, v102
	v_exp_f32_e32 v103, v103
	v_sub_f32_e32 v104, v104, v93
	v_sub_f32_e32 v105, v105, v93
	v_sub_f32_e32 v106, v106, v93
	v_sub_f32_e32 v107, v107, v93
	v_exp_f32_e32 v104, v104
	v_exp_f32_e32 v105, v105
	v_exp_f32_e32 v106, v106
	v_exp_f32_e32 v107, v107
	v_sub_f32_e32 v108, v108, v93
	v_sub_f32_e32 v109, v109, v93
	v_sub_f32_e32 v110, v110, v93
	v_sub_f32_e32 v111, v111, v93
	v_exp_f32_e32 v108, v108
	v_exp_f32_e32 v109, v109
	v_exp_f32_e32 v110, v110
	v_exp_f32_e32 v111, v111
	v_sub_f32_e32 v112, v112, v93
	v_sub_f32_e32 v113, v113, v93
	v_sub_f32_e32 v114, v114, v93
	v_sub_f32_e32 v115, v115, v93
	v_exp_f32_e32 v112, v112
	v_exp_f32_e32 v113, v113
	v_exp_f32_e32 v114, v114
	v_exp_f32_e32 v115, v115
	s_nop 0
	v_add_f32_e32 v90, v100, v101
	v_add_f32_e32 v91, v102, v103
	v_add_f32_e32 v92, v104, v105
	v_add_f32_e32 v93, v106, v107
	v_add_f32_e32 v90, v90, v108
	v_add_f32_e32 v91, v91, v109
	v_add_f32_e32 v92, v92, v110
	v_add_f32_e32 v93, v93, v111
	v_add_f32_e32 v90, v90, v112
	v_add_f32_e32 v91, v91, v113
	v_add_f32_e32 v92, v92, v114
	v_add_f32_e32 v93, v93, v115
	v_add_f32_e32 v90, v90, v91
	v_add_f32_e32 v92, v92, v93
	v_add_f32_e32 v90, v90, v92
	v_cvt_pk_bf16_f32 v82, v100, v101
	v_cvt_pk_bf16_f32 v83, v102, v103
	v_cvt_pk_bf16_f32 v84, v104, v105
	v_cvt_pk_bf16_f32 v85, v106, v107
	v_cvt_pk_bf16_f32 v86, v108, v109
	v_cvt_pk_bf16_f32 v87, v110, v111
	v_cvt_pk_bf16_f32 v88, v112, v113
	v_cvt_pk_bf16_f32 v89, v114, v115
	v_mov_b32_e32 v91, v90
	s_nop 1
	v_permlane16_swap_b32_e32 v90, v91
	v_add_f32_e32 v90, v90, v91
	v_mov_b32_e32 v91, v90
	s_nop 1
	v_permlane32_swap_b32_e32 v90, v91
	v_add_f32_e32 v90, v90, v91
	v_fma_f32 v159, v159, v94, v90
	v_cmp_neq_f32_e64 s[4:5], 1.0, v94
	s_cmp_eq_u64 s[4:5], 0
	s_cbranch_scc1 .Lwn_nosc_13
	v_pk_mul_f32 v[30:31], v[30:31], v[94:95] op_sel_hi:[1,0]
	v_pk_mul_f32 v[32:33], v[32:33], v[94:95] op_sel_hi:[1,0]
	v_pk_mul_f32 v[26:27], v[26:27], v[94:95] op_sel_hi:[1,0]
	v_pk_mul_f32 v[28:29], v[28:29], v[94:95] op_sel_hi:[1,0]
	v_pk_mul_f32 v[22:23], v[22:23], v[94:95] op_sel_hi:[1,0]
	v_pk_mul_f32 v[24:25], v[24:25], v[94:95] op_sel_hi:[1,0]
	v_pk_mul_f32 v[18:19], v[18:19], v[94:95] op_sel_hi:[1,0]
	v_pk_mul_f32 v[20:21], v[20:21], v[94:95] op_sel_hi:[1,0]
; template <int D, class SF>
; __device__ __forceinline__ void attn_step(const bf16x8 (&qf)[D / 32], const LAS bf16_t* Ks, const LAS bf16_t* Vt, f32x4 (&o)[D / 16], float& m, float& lsum, float& alpha_out, bf16x8& pf0_out, bf16x8& pf1_out, const int lane, SF sf) {
;     ...
;     for (int ks = 0; ks < D / 32; ++ks) {
; #pragma unroll
;         for (int t = 0; t < 4; ++t) { const bf16x8 kf = *(const LAS bf16x8*)(Ks + (16 * t + c) * KSTR + ks * 32 + 8 * i); s[t] = mfma16(kf, qf[ks], s[t]); }
;     }
;     float v[16];
; #pragma unroll
;     for (int t = 0; t < 4; ++t)
; #pragma unroll
;         for (int r = 0; r < 4; ++r) v[4 * t + r] = sf(16 * t + 4 * i + r, s[t][r]);
;     float mx = fmaxf(fmaxf(fmaxf(v[0], v[1]), fmaxf(v[2], v[3])), fmaxf(fmaxf(v[4], v[5]), fmaxf(v[6], v[7])));
;     mx = fmaxf(mx, fmaxf(fmaxf(fmaxf(v[8], v[9]), fmaxf(v[10], v[11])), fmaxf(fmaxf(v[12], v[13]), fmaxf(v[14], v[15]))));
;     mx = rows_max(mx);
;     const float mnew = fmaxf(m, mx);
;     const float mc = fmaxf(mnew, -1e20f);
;     const float alpha = __builtin_amdgcn_exp2f(fmaxf(m, -1e20f) - mc);
;     float p[16], rs = 0.f;
; #pragma unroll
;     for (int r = 0; r < 16; ++r) { p[r] = __builtin_amdgcn_exp2f(v[r] - mc); rs += p[r]; }
;     rs = rows_sum(rs);
;     lsum = lsum * alpha + rs; m = mnew;
;     union { u32x4 u; bf16x8 b; } pk0, pk1;
;     pk0.u.x = cvt_pk_bf16(p[0], p[1]); pk0.u.y = cvt_pk_bf16(p[2], p[3]); pk0.u.z = cvt_pk_bf16(p[4], p[5]); pk0.u.w = cvt_pk_bf16(p[6], p[7]);
;     pk1.u.x = cvt_pk_bf16(p[8], p[9]); pk1.u.y = cvt_pk_bf16(p[10], p[11]); pk1.u.z = cvt_pk_bf16(p[12], p[13]); pk1.u.w = cvt_pk_bf16(p[14], p[15]);
;     if (__builtin_amdgcn_ballot_w64(alpha != 1.0f) != 0ull) {
; #pragma unroll
; __device__ __forceinline__ void nsa_unit(LAS unsigned char* lds, const Ctx& P, int l, int b, int hkv, int tb) {
;     ...
;             for (int sl = 0; sl < 2; ++sl) if (sl == 0 || hasb) { const LAS bf16_t* Ks = KV + sl * 9216; const LAS bf16_t* Vt = Ks + 4608; const int kp0 = p0 + sl * 64;
; #pragma unroll
;                 for (int sb = 0; sb < 2; ++sb) { const int tqs = tq[sb];
;                     attn_step<64>(qf[sb], Ks, Vt, o[sb], m[sb], lsum[sb], alpha, pf, pf1, lane,
;                         [&](int kk, float s) { const int kpos = kp0 + kk, dist = tqs - kpos; return (dist >= 0 && dist < 256 && kpos >= 0) ? s * LOG2E + lut[min((unsigned)dist, 1023u)] : NEGBIG; }); }
.Lwn_nosc_13:
	s_waitcnt lgkmcnt(0)
	s_nop 1
	v_mfma_f32_16x16x32_bf16 v[30:33], v[50:53], v[82:85], v[30:33]
	v_mfma_f32_16x16x32_bf16 v[26:29], v[58:61], v[82:85], v[26:29]
	v_mfma_f32_16x16x32_bf16 v[22:25], v[66:69], v[82:85], v[22:25]
	v_mfma_f32_16x16x32_bf16 v[18:21], v[74:77], v[82:85], v[18:21]
	v_mfma_f32_16x16x32_bf16 v[30:33], v[54:57], v[86:89], v[30:33]
	v_mfma_f32_16x16x32_bf16 v[26:29], v[62:65], v[86:89], v[26:29]
	v_mfma_f32_16x16x32_bf16 v[22:25], v[70:73], v[86:89], v[22:25]
	v_mfma_f32_16x16x32_bf16 v[18:21], v[78:81], v[86:89], v[18:21]
.Lwn_wc_11:
	s_cmp_gt_u32 s20, 1
	s_cbranch_scc1 .Lwn_wc_14
	s_add_i32 s21, s12, 64
	v_sub_u32_e32 v90, v130, v139
	v_subrev_u32_e32 v90, s21, v90
	v_lshl_add_u32 v91, v90, 2, v131
	v_add_u32_e32 v91, 0xffffff34, v91
	ds_read_b32 v170, v91 offset:204
	ds_read_b32 v171, v91 offset:200
	ds_read_b32 v172, v91 offset:196
	ds_read_b32 v173, v91 offset:192
	ds_read_b32 v174, v91 offset:140
	ds_read_b32 v175, v91 offset:136
	ds_read_b32 v176, v91 offset:132
	ds_read_b32 v177, v91 offset:128
	ds_read_b128 v[50:53], v178 offset:34816
	ds_read_b128 v[58:61], v178 offset:37120
	ds_read_b128 v[54:57], v178 offset:34880
	ds_read_b128 v[62:65], v178 offset:37184
	ds_read_b128 v[66:69], v178 offset:39424
	ds_read_b128 v[74:77], v178 offset:41728
	ds_read_b128 v[70:73], v178 offset:39488
	ds_read_b128 v[78:81], v178 offset:41792
	s_waitcnt lgkmcnt(6)
	v_mfma_f32_16x16x32_bf16 v[100:103], v[50:53], v[2:5], 0
	v_mfma_f32_16x16x32_bf16 v[104:107], v[58:61], v[2:5], 0
	s_waitcnt lgkmcnt(4)
	v_mfma_f32_16x16x32_bf16 v[100:103], v[54:57], v[6:9], v[100:103]
	v_mfma_f32_16x16x32_bf16 v[104:107], v[62:65], v[6:9], v[104:107]
	s_waitcnt lgkmcnt(2)
	v_mfma_f32_16x16x32_bf16 v[108:111], v[66:69], v[2:5], 0
	v_mfma_f32_16x16x32_bf16 v[112:115], v[74:77], v[2:5], 0
	s_waitcnt lgkmcnt(0)
	v_mfma_f32_16x16x32_bf16 v[108:111], v[70:73], v[6:9], v[108:111]
	v_mfma_f32_16x16x32_bf16 v[112:115], v[78:81], v[6:9], v[112:115]
	ds_read_b64_tr_b16 v[50:51], v179 offset:44032
	ds_read_b64_tr_b16 v[52:53], v179 offset:46336
	ds_read_b64_tr_b16 v[54:55], v179 offset:48640
	ds_read_b64_tr_b16 v[56:57], v179 offset:50944
	ds_read_b64_tr_b16 v[58:59], v179 offset:44064
	ds_read_b64_tr_b16 v[60:61], v179 offset:46368
	ds_read_b64_tr_b16 v[62:63], v179 offset:48672
	v_fmamk_f32 v100, v100, 0x3fb8aa3b, v170
	v_fmamk_f32 v101, v101, 0x3fb8aa3b, v171
	v_fmamk_f32 v102, v102, 0x3fb8aa3b, v172
	v_fmamk_f32 v103, v103, 0x3fb8aa3b, v173
	v_fmamk_f32 v104, v104, 0x3fb8aa3b, v174
	v_fmamk_f32 v105, v105, 0x3fb8aa3b, v175
	v_fmamk_f32 v106, v106, 0x3fb8aa3b, v176
	v_fmamk_f32 v107, v107, 0x3fb8aa3b, v177
	ds_read_b32 v170, v91 offset:76
	ds_read_b32 v171, v91 offset:72
	ds_read_b32 v172, v91 offset:68
	ds_read_b32 v173, v91 offset:64
	ds_read_b32 v174, v91 offset:12
	ds_read_b32 v175, v91 offset:8
	ds_read_b32 v176, v91 offset:4
	ds_read_b32 v177, v91 offset:0
	ds_read_b64_tr_b16 v[64:65], v179 offset:50976
	ds_read_b64_tr_b16 v[66:67], v179 offset:44096
	ds_read_b64_tr_b16 v[68:69], v179 offset:46400
	ds_read_b64_tr_b16 v[70:71], v179 offset:48704
	ds_read_b64_tr_b16 v[72:73], v179 offset:51008
	ds_read_b64_tr_b16 v[74:75], v179 offset:44128
	ds_read_b64_tr_b16 v[76:77], v179 offset:46432
	ds_read_b64_tr_b16 v[78:79], v179 offset:48736
	ds_read_b64_tr_b16 v[80:81], v179 offset:51040
	s_waitcnt lgkmcnt(9)
	v_fmamk_f32 v108, v108, 0x3fb8aa3b, v170
	v_fmamk_f32 v109, v109, 0x3fb8aa3b, v171
	v_fmamk_f32 v110, v110, 0x3fb8aa3b, v172
	v_fmamk_f32 v111, v111, 0x3fb8aa3b, v173
	v_fmamk_f32 v112, v112, 0x3fb8aa3b, v174
	v_fmamk_f32 v113, v113, 0x3fb8aa3b, v175
	v_fmamk_f32 v114, v114, 0x3fb8aa3b, v176
	v_fmamk_f32 v115, v115, 0x3fb8aa3b, v177
	v_max3_f32 v96, v100, v101, v102
	v_max3_f32 v91, v103, v104, v105
	v_max3_f32 v92, v106, v107, v108
	v_max3_f32 v93, v109, v110, v111
	v_max3_f32 v95, v112, v113, v114
	v_max3_f32 v96, v96, v91, v115
	v_max3_f32 v92, v92, v93, v95
	v_max_f32_e32 v96, v96, v92
	v_mov_b32_e32 v91, v96
	s_nop 1
	v_permlane16_swap_b32_e32 v96, v91
	v_max_f32_e32 v96, v96, v91
	v_mov_b32_e32 v91, v96
	s_nop 1
	v_permlane32_swap_b32_e32 v96, v91
	v_max_f32_e32 v96, v96, v91
	v_max_f32_e32 v92, v162, v96
	v_max_f32_e32 v94, 0xe0ad78ec, v162
	v_max_f32_e32 v93, 0xe0ad78ec, v92
	v_sub_f32_e32 v94, v94, v93
	v_mov_b32_e32 v162, v92
	v_exp_f32_e32 v94, v94
	v_sub_f32_e32 v100, v100, v93
	v_sub_f32_e32 v101, v101, v93
	v_sub_f32_e32 v102, v102, v93
	v_sub_f32_e32 v103, v103, v93
	v_exp_f32_e32 v100, v100
	v_exp_f32_e32 v101, v101
	v_exp_f32_e32 v102, v102
	v_exp_f32_e32 v103, v103
	v_sub_f32_e32 v104, v104, v93
	v_sub_f32_e32 v105, v105, v93
	v_sub_f32_e32 v106, v106, v93
	v_sub_f32_e32 v107, v107, v93
	v_exp_f32_e32 v104, v104
	v_exp_f32_e32 v105, v105
	v_exp_f32_e32 v106, v106
	v_exp_f32_e32 v107, v107
	v_sub_f32_e32 v108, v108, v93
	v_sub_f32_e32 v109, v109, v93
	v_sub_f32_e32 v110, v110, v93
	v_sub_f32_e32 v111, v111, v93
	v_exp_f32_e32 v108, v108
	v_exp_f32_e32 v109, v109
	v_exp_f32_e32 v110, v110
	v_exp_f32_e32 v111, v111
	v_sub_f32_e32 v112, v112, v93
	v_sub_f32_e32 v113, v113, v93
	v_sub_f32_e32 v114, v114, v93
	v_sub_f32_e32 v115, v115, v93
	v_exp_f32_e32 v112, v112
	v_exp_f32_e32 v113, v113
	v_exp_f32_e32 v114, v114
	v_exp_f32_e32 v115, v115
	s_nop 0
	v_add_f32_e32 v90, v100, v101
	v_add_f32_e32 v91, v102, v103
	v_add_f32_e32 v92, v104, v105
	v_add_f32_e32 v93, v106, v107
	v_add_f32_e32 v90, v90, v108
	v_add_f32_e32 v91, v91, v109
	v_add_f32_e32 v92, v92, v110
	v_add_f32_e32 v93, v93, v111
	v_add_f32_e32 v90, v90, v112
	v_add_f32_e32 v91, v91, v113
	v_add_f32_e32 v92, v92, v114
	v_add_f32_e32 v93, v93, v115
	v_add_f32_e32 v90, v90, v91
	v_add_f32_e32 v92, v92, v93
	v_add_f32_e32 v90, v90, v92
	v_cvt_pk_bf16_f32 v82, v100, v101
	v_cvt_pk_bf16_f32 v83, v102, v103
	v_cvt_pk_bf16_f32 v84, v104, v105
	v_cvt_pk_bf16_f32 v85, v106, v107
	v_cvt_pk_bf16_f32 v86, v108, v109
	v_cvt_pk_bf16_f32 v87, v110, v111
	v_cvt_pk_bf16_f32 v88, v112, v113
	v_cvt_pk_bf16_f32 v89, v114, v115
	v_mov_b32_e32 v91, v90
	s_nop 1
	v_permlane16_swap_b32_e32 v90, v91
	v_add_f32_e32 v90, v90, v91
	v_mov_b32_e32 v91, v90
	s_nop 1
	v_permlane32_swap_b32_e32 v90, v91
	v_add_f32_e32 v90, v90, v91
	v_fma_f32 v161, v161, v94, v90
	v_cmp_neq_f32_e64 s[4:5], 1.0, v94
	s_cmp_eq_u64 s[4:5], 0
	s_cbranch_scc1 .Lwn_nosc_15
	v_pk_mul_f32 v[46:47], v[46:47], v[94:95] op_sel_hi:[1,0]
	v_pk_mul_f32 v[48:49], v[48:49], v[94:95] op_sel_hi:[1,0]
	v_pk_mul_f32 v[42:43], v[42:43], v[94:95] op_sel_hi:[1,0]
	v_pk_mul_f32 v[44:45], v[44:45], v[94:95] op_sel_hi:[1,0]
	v_pk_mul_f32 v[38:39], v[38:39], v[94:95] op_sel_hi:[1,0]
	v_pk_mul_f32 v[40:41], v[40:41], v[94:95] op_sel_hi:[1,0]
	v_pk_mul_f32 v[34:35], v[34:35], v[94:95] op_sel_hi:[1,0]
	v_pk_mul_f32 v[36:37], v[36:37], v[94:95] op_sel_hi:[1,0]
; #define LAS __attribute__((address_space(3)))
; template <int D, class SF>
; __device__ __forceinline__ void attn_step(const bf16x8 (&qf)[D / 32], const LAS bf16_t* Ks, const LAS bf16_t* Vt, f32x4 (&o)[D / 16], float& m, float& lsum, float& alpha_out, bf16x8& pf0_out, bf16x8& pf1_out, const int lane, SF sf) {
;     ...
;     for (int ks = 0; ks < D / 32; ++ks) {
; #pragma unroll
;         for (int t = 0; t < 4; ++t) { const bf16x8 kf = *(const LAS bf16x8*)(Ks + (16 * t + c) * KSTR + ks * 32 + 8 * i); s[t] = mfma16(kf, qf[ks], s[t]); }
;     }
;     float v[16];
; #pragma unroll
;     for (int t = 0; t < 4; ++t)
; #pragma unroll
;         for (int r = 0; r < 4; ++r) v[4 * t + r] = sf(16 * t + 4 * i + r, s[t][r]);
;     float mx = fmaxf(fmaxf(fmaxf(v[0], v[1]), fmaxf(v[2], v[3])), fmaxf(fmaxf(v[4], v[5]), fmaxf(v[6], v[7])));
;     mx = fmaxf(mx, fmaxf(fmaxf(fmaxf(v[8], v[9]), fmaxf(v[10], v[11])), fmaxf(fmaxf(v[12], v[13]), fmaxf(v[14], v[15]))));
;     mx = rows_max(mx);
;     const float mnew = fmaxf(m, mx);
;     const float mc = fmaxf(mnew, -1e20f);
;     const float alpha = __builtin_amdgcn_exp2f(fmaxf(m, -1e20f) - mc);
;     float p[16], rs = 0.f;
; #pragma unroll
;     for (int r = 0; r < 16; ++r) { p[r] = __builtin_amdgcn_exp2f(v[r] - mc); rs += p[r]; }
;     rs = rows_sum(rs);
;     lsum = lsum * alpha + rs; m = mnew;
;     union { u32x4 u; bf16x8 b; } pk0, pk1;
;     pk0.u.x = cvt_pk_bf16(p[0], p[1]); pk0.u.y = cvt_pk_bf16(p[2], p[3]); pk0.u.z = cvt_pk_bf16(p[4], p[5]); pk0.u.w = cvt_pk_bf16(p[6], p[7]);
;     pk1.u.x = cvt_pk_bf16(p[8], p[9]); pk1.u.y = cvt_pk_bf16(p[10], p[11]); pk1.u.z = cvt_pk_bf16(p[12], p[13]); pk1.u.w = cvt_pk_bf16(p[14], p[15]);
;     if (__builtin_amdgcn_ballot_w64(alpha != 1.0f) != 0ull) {
; #pragma unroll
;         for (int dt = 0; dt < D / 16; ++dt) o[dt] *= alpha;
;     }
; #pragma unroll
;     for (int dt = 0; dt < D / 16; ++dt) {
;         const LAS bf16_t* vp = Vt + (16 * dt + c) * 72 + 4 * i;
;         union { u32x4 u; bf16x8 b; } vf0, vf1; const u32x2 a0 = *(const LAS u32x2*)vp, a1 = *(const LAS u32x2*)(vp + 16), b0 = *(const LAS u32x2*)(vp + 32), b1 = *(const LAS u32x2*)(vp + 48);
;         vf0.u.x = a0.x; vf0.u.y = a0.y; vf0.u.z = a1.x; vf0.u.w = a1.y; vf1.u.x = b0.x; vf1.u.y = b0.y; vf1.u.z = b1.x; vf1.u.w = b1.y;
;         o[dt] = mfma16(vf0.b, pk0.b, o[dt]); o[dt] = mfma16(vf1.b, pk1.b, o[dt]);
;     }
.Lwn_nosc_15:
	s_waitcnt lgkmcnt(0)
	s_nop 1
	v_mfma_f32_16x16x32_bf16 v[46:49], v[50:53], v[82:85], v[46:49]
	v_mfma_f32_16x16x32_bf16 v[42:45], v[58:61], v[82:85], v[42:45]
	v_mfma_f32_16x16x32_bf16 v[38:41], v[66:69], v[82:85], v[38:41]
	v_mfma_f32_16x16x32_bf16 v[34:37], v[74:77], v[82:85], v[34:37]
	v_mfma_f32_16x16x32_bf16 v[46:49], v[54:57], v[86:89], v[46:49]
	v_mfma_f32_16x16x32_bf16 v[42:45], v[62:65], v[86:89], v[42:45]
	v_mfma_f32_16x16x32_bf16 v[38:41], v[70:73], v[86:89], v[38:41]
	v_mfma_f32_16x16x32_bf16 v[34:37], v[78:81], v[86:89], v[34:37]
	v_sub_u32_e32 v90, v180, v139
	v_subrev_u32_e32 v90, s21, v90
	v_lshl_add_u32 v91, v90, 2, v131
	v_add_u32_e32 v91, 0xffffff34, v91
	ds_read_b32 v170, v91 offset:204
	ds_read_b32 v171, v91 offset:200
	ds_read_b32 v172, v91 offset:196
	ds_read_b32 v173, v91 offset:192
	ds_read_b32 v174, v91 offset:140
	ds_read_b32 v175, v91 offset:136
	ds_read_b32 v176, v91 offset:132
	ds_read_b32 v177, v91 offset:128
	ds_read_b128 v[50:53], v178 offset:34816
	ds_read_b128 v[58:61], v178 offset:37120
	ds_read_b128 v[54:57], v178 offset:34880
	ds_read_b128 v[62:65], v178 offset:37184
	ds_read_b128 v[66:69], v178 offset:39424
	ds_read_b128 v[74:77], v178 offset:41728
	ds_read_b128 v[70:73], v178 offset:39488
	ds_read_b128 v[78:81], v178 offset:41792
	s_waitcnt lgkmcnt(6)
	v_mfma_f32_16x16x32_bf16 v[100:103], v[50:53], v[10:13], 0
	v_mfma_f32_16x16x32_bf16 v[104:107], v[58:61], v[10:13], 0
	s_waitcnt lgkmcnt(4)
	v_mfma_f32_16x16x32_bf16 v[100:103], v[54:57], v[14:17], v[100:103]
	v_mfma_f32_16x16x32_bf16 v[104:107], v[62:65], v[14:17], v[104:107]
	s_waitcnt lgkmcnt(2)
	v_mfma_f32_16x16x32_bf16 v[108:111], v[66:69], v[10:13], 0
	v_mfma_f32_16x16x32_bf16 v[112:115], v[74:77], v[10:13], 0
	s_waitcnt lgkmcnt(0)
	v_mfma_f32_16x16x32_bf16 v[108:111], v[70:73], v[14:17], v[108:111]
	v_mfma_f32_16x16x32_bf16 v[112:115], v[78:81], v[14:17], v[112:115]
	ds_read_b64_tr_b16 v[50:51], v179 offset:44032
	ds_read_b64_tr_b16 v[52:53], v179 offset:46336
	ds_read_b64_tr_b16 v[54:55], v179 offset:48640
	ds_read_b64_tr_b16 v[56:57], v179 offset:50944
	ds_read_b64_tr_b16 v[58:59], v179 offset:44064
	ds_read_b64_tr_b16 v[60:61], v179 offset:46368
	ds_read_b64_tr_b16 v[62:63], v179 offset:48672
	v_fmamk_f32 v100, v100, 0x3fb8aa3b, v170
	v_fmamk_f32 v101, v101, 0x3fb8aa3b, v171
	v_fmamk_f32 v102, v102, 0x3fb8aa3b, v172
	v_fmamk_f32 v103, v103, 0x3fb8aa3b, v173
	v_fmamk_f32 v104, v104, 0x3fb8aa3b, v174
	v_fmamk_f32 v105, v105, 0x3fb8aa3b, v175
	v_fmamk_f32 v106, v106, 0x3fb8aa3b, v176
	v_fmamk_f32 v107, v107, 0x3fb8aa3b, v177
	ds_read_b32 v170, v91 offset:76
	ds_read_b32 v171, v91 offset:72
	ds_read_b32 v172, v91 offset:68
	ds_read_b32 v173, v91 offset:64
	ds_read_b32 v174, v91 offset:12
	ds_read_b32 v175, v91 offset:8
	ds_read_b32 v176, v91 offset:4
	ds_read_b32 v177, v91 offset:0
	ds_read_b64_tr_b16 v[64:65], v179 offset:50976
	ds_read_b64_tr_b16 v[66:67], v179 offset:44096
	ds_read_b64_tr_b16 v[68:69], v179 offset:46400
	ds_read_b64_tr_b16 v[70:71], v179 offset:48704
	ds_read_b64_tr_b16 v[72:73], v179 offset:51008
	ds_read_b64_tr_b16 v[74:75], v179 offset:44128
	ds_read_b64_tr_b16 v[76:77], v179 offset:46432
	ds_read_b64_tr_b16 v[78:79], v179 offset:48736
	ds_read_b64_tr_b16 v[80:81], v179 offset:51040
	s_waitcnt lgkmcnt(9)
	v_fmamk_f32 v108, v108, 0x3fb8aa3b, v170
	v_fmamk_f32 v109, v109, 0x3fb8aa3b, v171
	v_fmamk_f32 v110, v110, 0x3fb8aa3b, v172
	v_fmamk_f32 v111, v111, 0x3fb8aa3b, v173
	v_fmamk_f32 v112, v112, 0x3fb8aa3b, v174
	v_fmamk_f32 v113, v113, 0x3fb8aa3b, v175
	v_fmamk_f32 v114, v114, 0x3fb8aa3b, v176
	v_fmamk_f32 v115, v115, 0x3fb8aa3b, v177
	v_max3_f32 v96, v100, v101, v102
	v_max3_f32 v91, v103, v104, v105
	v_max3_f32 v92, v106, v107, v108
	v_max3_f32 v93, v109, v110, v111
	v_max3_f32 v95, v112, v113, v114
	v_max3_f32 v96, v96, v91, v115
	v_max3_f32 v92, v92, v93, v95
	v_max_f32_e32 v96, v96, v92
	v_mov_b32_e32 v91, v96
	s_nop 1
	v_permlane16_swap_b32_e32 v96, v91
	v_max_f32_e32 v96, v96, v91
	v_mov_b32_e32 v91, v96
	s_nop 1
	v_permlane32_swap_b32_e32 v96, v91
	v_max_f32_e32 v96, v96, v91
	v_max_f32_e32 v92, v160, v96
	v_max_f32_e32 v94, 0xe0ad78ec, v160
	v_max_f32_e32 v93, 0xe0ad78ec, v92
	v_sub_f32_e32 v94, v94, v93
	v_mov_b32_e32 v160, v92
	v_exp_f32_e32 v94, v94
	v_sub_f32_e32 v100, v100, v93
	v_sub_f32_e32 v101, v101, v93
	v_sub_f32_e32 v102, v102, v93
	v_sub_f32_e32 v103, v103, v93
	v_exp_f32_e32 v100, v100
	v_exp_f32_e32 v101, v101
	v_exp_f32_e32 v102, v102
	v_exp_f32_e32 v103, v103
	v_sub_f32_e32 v104, v104, v93
	v_sub_f32_e32 v105, v105, v93
	v_sub_f32_e32 v106, v106, v93
	v_sub_f32_e32 v107, v107, v93
	v_exp_f32_e32 v104, v104
	v_exp_f32_e32 v105, v105
	v_exp_f32_e32 v106, v106
	v_exp_f32_e32 v107, v107
	v_sub_f32_e32 v108, v108, v93
	v_sub_f32_e32 v109, v109, v93
	v_sub_f32_e32 v110, v110, v93
	v_sub_f32_e32 v111, v111, v93
	v_exp_f32_e32 v108, v108
	v_exp_f32_e32 v109, v109
	v_exp_f32_e32 v110, v110
	v_exp_f32_e32 v111, v111
	v_sub_f32_e32 v112, v112, v93
	v_sub_f32_e32 v113, v113, v93
	v_sub_f32_e32 v114, v114, v93
	v_sub_f32_e32 v115, v115, v93
	v_exp_f32_e32 v112, v112
	v_exp_f32_e32 v113, v113
	v_exp_f32_e32 v114, v114
	v_exp_f32_e32 v115, v115
	s_nop 0
	v_add_f32_e32 v90, v100, v101
	v_add_f32_e32 v91, v102, v103
	v_add_f32_e32 v92, v104, v105
	v_add_f32_e32 v93, v106, v107
	v_add_f32_e32 v90, v90, v108
	v_add_f32_e32 v91, v91, v109
	v_add_f32_e32 v92, v92, v110
	v_add_f32_e32 v93, v93, v111
	v_add_f32_e32 v90, v90, v112
	v_add_f32_e32 v91, v91, v113
	v_add_f32_e32 v92, v92, v114
	v_add_f32_e32 v93, v93, v115
	v_add_f32_e32 v90, v90, v91
	v_add_f32_e32 v92, v92, v93
	v_add_f32_e32 v90, v90, v92
	v_cvt_pk_bf16_f32 v82, v100, v101
	v_cvt_pk_bf16_f32 v83, v102, v103
	v_cvt_pk_bf16_f32 v84, v104, v105
	v_cvt_pk_bf16_f32 v85, v106, v107
	v_cvt_pk_bf16_f32 v86, v108, v109
	v_cvt_pk_bf16_f32 v87, v110, v111
	v_cvt_pk_bf16_f32 v88, v112, v113
	v_cvt_pk_bf16_f32 v89, v114, v115
	v_mov_b32_e32 v91, v90
	s_nop 1
	v_permlane16_swap_b32_e32 v90, v91
	v_add_f32_e32 v90, v90, v91
	v_mov_b32_e32 v91, v90
	s_nop 1
	v_permlane32_swap_b32_e32 v90, v91
	v_add_f32_e32 v90, v90, v91
	v_fma_f32 v159, v159, v94, v90
	v_cmp_neq_f32_e64 s[4:5], 1.0, v94
	s_cmp_eq_u64 s[4:5], 0
	s_cbranch_scc1 .Lwn_nosc_16
	v_pk_mul_f32 v[30:31], v[30:31], v[94:95] op_sel_hi:[1,0]
	v_pk_mul_f32 v[32:33], v[32:33], v[94:95] op_sel_hi:[1,0]
	v_pk_mul_f32 v[26:27], v[26:27], v[94:95] op_sel_hi:[1,0]
	v_pk_mul_f32 v[28:29], v[28:29], v[94:95] op_sel_hi:[1,0]
	v_pk_mul_f32 v[22:23], v[22:23], v[94:95] op_sel_hi:[1,0]
	v_pk_mul_f32 v[24:25], v[24:25], v[94:95] op_sel_hi:[1,0]
	v_pk_mul_f32 v[18:19], v[18:19], v[94:95] op_sel_hi:[1,0]
	v_pk_mul_f32 v[20:21], v[20:21], v[94:95] op_sel_hi:[1,0]

; template <int D, class SF>
; __device__ __forceinline__ void attn_step(const bf16x8 (&qf)[D / 32], const LAS bf16_t* Ks, const LAS bf16_t* Vt, f32x4 (&o)[D / 16], float& m, float& lsum, float& alpha_out, bf16x8& pf0_out, bf16x8& pf1_out, const int lane, SF sf) {
;     ...
;     for (int ks = 0; ks < D / 32; ++ks) {
; #pragma unroll
;         for (int t = 0; t < 4; ++t) { const bf16x8 kf = *(const LAS bf16x8*)(Ks + (16 * t + c) * KSTR + ks * 32 + 8 * i); s[t] = mfma16(kf, qf[ks], s[t]); }
;     }
;     float v[16];
; #pragma unroll
;     for (int t = 0; t < 4; ++t)
; #pragma unroll
;         for (int r = 0; r < 4; ++r) v[4 * t + r] = sf(16 * t + 4 * i + r, s[t][r]);
;     float mx = fmaxf(fmaxf(fmaxf(v[0], v[1]), fmaxf(v[2], v[3])), fmaxf(fmaxf(v[4], v[5]), fmaxf(v[6], v[7])));
;     mx = fmaxf(mx, fmaxf(fmaxf(fmaxf(v[8], v[9]), fmaxf(v[10], v[11])), fmaxf(fmaxf(v[12], v[13]), fmaxf(v[14], v[15]))));
;     mx = rows_max(mx);
;     const float mnew = fmaxf(m, mx);
;     const float mc = fmaxf(mnew, -1e20f);
;     const float alpha = __builtin_amdgcn_exp2f(fmaxf(m, -1e20f) - mc);
;     float p[16], rs = 0.f;
; #pragma unroll
;     for (int r = 0; r < 16; ++r) { p[r] = __builtin_amdgcn_exp2f(v[r] - mc); rs += p[r]; }
;     rs = rows_sum(rs);
;     lsum = lsum * alpha + rs; m = mnew;
;     union { u32x4 u; bf16x8 b; } pk0, pk1;
;     pk0.u.x = cvt_pk_bf16(p[0], p[1]); pk0.u.y = cvt_pk_bf16(p[2], p[3]); pk0.u.z = cvt_pk_bf16(p[4], p[5]); pk0.u.w = cvt_pk_bf16(p[6], p[7]);
;     pk1.u.x = cvt_pk_bf16(p[8], p[9]); pk1.u.y = cvt_pk_bf16(p[10], p[11]); pk1.u.z = cvt_pk_bf16(p[12], p[13]); pk1.u.w = cvt_pk_bf16(p[14], p[15]);
;     if (__builtin_amdgcn_ballot_w64(alpha != 1.0f) != 0ull) {
; #pragma unroll
; __device__ __forceinline__ void nsa_unit(LAS unsigned char* lds, const Ctx& P, int l, int b, int hkv, int tb) {
;     ...
;             for (int sl = 0; sl < 2; ++sl) if (sl == 0 || hasb) { const LAS bf16_t* Ks = KV + sl * 9216; const LAS bf16_t* Vt = Ks + 4608; const int kp0 = p0 + sl * 64;
; #pragma unroll
;                 for (int sb = 0; sb < 2; ++sb) { const int tqs = tq[sb];
;                     attn_step<64>(qf[sb], Ks, Vt, o[sb], m[sb], lsum[sb], alpha, pf, pf1, lane,
;                         [&](int kk, float s) { const int kpos = kp0 + kk, dist = tqs - kpos; return (dist >= 0 && dist < 256 && kpos >= 0) ? s * LOG2E + lut[min((unsigned)dist, 1023u)] : NEGBIG; }); }
.Lwn_wc_14:
	s_cmp_gt_u32 s20, 2
	s_cbranch_scc1 .Lwn_wc_17
	s_add_i32 s21, s12, 128
	v_sub_u32_e32 v90, v130, v139
	v_subrev_u32_e32 v90, s21, v90
	v_lshl_add_u32 v91, v90, 2, v131
	v_add_u32_e32 v91, 0xffffff34, v91
	ds_read_b32 v170, v91 offset:204
	ds_read_b32 v171, v91 offset:200
	ds_read_b32 v172, v91 offset:196
	ds_read_b32 v173, v91 offset:192
	ds_read_b32 v174, v91 offset:140
	ds_read_b32 v175, v91 offset:136
	ds_read_b32 v176, v91 offset:132
	ds_read_b32 v177, v91 offset:128
	ds_read_b128 v[50:53], v116 offset:4096
	ds_read_b128 v[58:61], v116 offset:6400
	ds_read_b128 v[54:57], v116 offset:4160
	ds_read_b128 v[62:65], v116 offset:6464
	ds_read_b128 v[66:69], v116 offset:8704
	ds_read_b128 v[74:77], v116 offset:11008
	ds_read_b128 v[70:73], v116 offset:8768
	ds_read_b128 v[78:81], v116 offset:11072
	s_waitcnt lgkmcnt(6)
	v_mfma_f32_16x16x32_bf16 v[100:103], v[50:53], v[2:5], 0
	v_mfma_f32_16x16x32_bf16 v[104:107], v[58:61], v[2:5], 0
	s_waitcnt lgkmcnt(4)
	v_mfma_f32_16x16x32_bf16 v[100:103], v[54:57], v[6:9], v[100:103]
	v_mfma_f32_16x16x32_bf16 v[104:107], v[62:65], v[6:9], v[104:107]
	s_waitcnt lgkmcnt(2)
	v_mfma_f32_16x16x32_bf16 v[108:111], v[66:69], v[2:5], 0
	v_mfma_f32_16x16x32_bf16 v[112:115], v[74:77], v[2:5], 0
	s_waitcnt lgkmcnt(0)
	v_mfma_f32_16x16x32_bf16 v[108:111], v[70:73], v[6:9], v[108:111]
	v_mfma_f32_16x16x32_bf16 v[112:115], v[78:81], v[6:9], v[112:115]
	ds_read_b64_tr_b16 v[50:51], v117 offset:13312
	ds_read_b64_tr_b16 v[52:53], v117 offset:15616
	ds_read_b64_tr_b16 v[54:55], v117 offset:17920
	ds_read_b64_tr_b16 v[56:57], v117 offset:20224
	ds_read_b64_tr_b16 v[58:59], v117 offset:13344
	ds_read_b64_tr_b16 v[60:61], v117 offset:15648
	ds_read_b64_tr_b16 v[62:63], v117 offset:17952
	v_fmamk_f32 v100, v100, 0x3fb8aa3b, v170
	v_fmamk_f32 v101, v101, 0x3fb8aa3b, v171
	v_fmamk_f32 v102, v102, 0x3fb8aa3b, v172
	v_fmamk_f32 v103, v103, 0x3fb8aa3b, v173
	v_fmamk_f32 v104, v104, 0x3fb8aa3b, v174
	v_fmamk_f32 v105, v105, 0x3fb8aa3b, v175
	v_fmamk_f32 v106, v106, 0x3fb8aa3b, v176
	v_fmamk_f32 v107, v107, 0x3fb8aa3b, v177
	ds_read_b32 v170, v91 offset:76
	ds_read_b32 v171, v91 offset:72
	ds_read_b32 v172, v91 offset:68
	ds_read_b32 v173, v91 offset:64
	ds_read_b32 v174, v91 offset:12
	ds_read_b32 v175, v91 offset:8
	ds_read_b32 v176, v91 offset:4
	ds_read_b32 v177, v91 offset:0
	ds_read_b64_tr_b16 v[64:65], v117 offset:20256
	ds_read_b64_tr_b16 v[66:67], v117 offset:13376
	ds_read_b64_tr_b16 v[68:69], v117 offset:15680
	ds_read_b64_tr_b16 v[70:71], v117 offset:17984
	ds_read_b64_tr_b16 v[72:73], v117 offset:20288
	ds_read_b64_tr_b16 v[74:75], v117 offset:13408
	ds_read_b64_tr_b16 v[76:77], v117 offset:15712
	ds_read_b64_tr_b16 v[78:79], v117 offset:18016
	ds_read_b64_tr_b16 v[80:81], v117 offset:20320
	s_waitcnt lgkmcnt(9)
	v_fmamk_f32 v108, v108, 0x3fb8aa3b, v170
	v_fmamk_f32 v109, v109, 0x3fb8aa3b, v171
	v_fmamk_f32 v110, v110, 0x3fb8aa3b, v172
	v_fmamk_f32 v111, v111, 0x3fb8aa3b, v173
	v_fmamk_f32 v112, v112, 0x3fb8aa3b, v174
	v_fmamk_f32 v113, v113, 0x3fb8aa3b, v175
	v_fmamk_f32 v114, v114, 0x3fb8aa3b, v176
	v_fmamk_f32 v115, v115, 0x3fb8aa3b, v177
	v_max3_f32 v96, v100, v101, v102
	v_max3_f32 v91, v103, v104, v105
	v_max3_f32 v92, v106, v107, v108
	v_max3_f32 v93, v109, v110, v111
	v_max3_f32 v95, v112, v113, v114
	v_max3_f32 v96, v96, v91, v115
	v_max3_f32 v92, v92, v93, v95
	v_max_f32_e32 v96, v96, v92
	v_mov_b32_e32 v91, v96
	s_nop 1
	v_permlane16_swap_b32_e32 v96, v91
	v_max_f32_e32 v96, v96, v91
	v_mov_b32_e32 v91, v96
	s_nop 1
	v_permlane32_swap_b32_e32 v96, v91
	v_max_f32_e32 v96, v96, v91
	v_max_f32_e32 v92, v162, v96
	v_max_f32_e32 v94, 0xe0ad78ec, v162
	v_max_f32_e32 v93, 0xe0ad78ec, v92
	v_sub_f32_e32 v94, v94, v93
	v_mov_b32_e32 v162, v92
	v_exp_f32_e32 v94, v94
	v_sub_f32_e32 v100, v100, v93
	v_sub_f32_e32 v101, v101, v93
	v_sub_f32_e32 v102, v102, v93
	v_sub_f32_e32 v103, v103, v93
	v_exp_f32_e32 v100, v100
	v_exp_f32_e32 v101, v101
	v_exp_f32_e32 v102, v102
	v_exp_f32_e32 v103, v103
	v_sub_f32_e32 v104, v104, v93
	v_sub_f32_e32 v105, v105, v93
	v_sub_f32_e32 v106, v106, v93
	v_sub_f32_e32 v107, v107, v93
	v_exp_f32_e32 v104, v104
	v_exp_f32_e32 v105, v105
	v_exp_f32_e32 v106, v106
	v_exp_f32_e32 v107, v107
	v_sub_f32_e32 v108, v108, v93
	v_sub_f32_e32 v109, v109, v93
	v_sub_f32_e32 v110, v110, v93
	v_sub_f32_e32 v111, v111, v93
	v_exp_f32_e32 v108, v108
	v_exp_f32_e32 v109, v109
	v_exp_f32_e32 v110, v110
	v_exp_f32_e32 v111, v111
	v_sub_f32_e32 v112, v112, v93
	v_sub_f32_e32 v113, v113, v93
	v_sub_f32_e32 v114, v114, v93
	v_sub_f32_e32 v115, v115, v93
	v_exp_f32_e32 v112, v112
	v_exp_f32_e32 v113, v113
	v_exp_f32_e32 v114, v114
	v_exp_f32_e32 v115, v115
	s_nop 0
	v_add_f32_e32 v90, v100, v101
	v_add_f32_e32 v91, v102, v103
	v_add_f32_e32 v92, v104, v105
	v_add_f32_e32 v93, v106, v107
	v_add_f32_e32 v90, v90, v108
	v_add_f32_e32 v91, v91, v109
	v_add_f32_e32 v92, v92, v110
	v_add_f32_e32 v93, v93, v111
	v_add_f32_e32 v90, v90, v112
	v_add_f32_e32 v91, v91, v113
	v_add_f32_e32 v92, v92, v114
	v_add_f32_e32 v93, v93, v115
	v_add_f32_e32 v90, v90, v91
	v_add_f32_e32 v92, v92, v93
	v_add_f32_e32 v90, v90, v92
	v_cvt_pk_bf16_f32 v82, v100, v101
	v_cvt_pk_bf16_f32 v83, v102, v103
	v_cvt_pk_bf16_f32 v84, v104, v105
	v_cvt_pk_bf16_f32 v85, v106, v107
	v_cvt_pk_bf16_f32 v86, v108, v109
	v_cvt_pk_bf16_f32 v87, v110, v111
	v_cvt_pk_bf16_f32 v88, v112, v113
	v_cvt_pk_bf16_f32 v89, v114, v115
	v_mov_b32_e32 v91, v90
	s_nop 1
	v_permlane16_swap_b32_e32 v90, v91
	v_add_f32_e32 v90, v90, v91
	v_mov_b32_e32 v91, v90
	s_nop 1
	v_permlane32_swap_b32_e32 v90, v91
	v_add_f32_e32 v90, v90, v91
	v_fma_f32 v161, v161, v94, v90
	v_cmp_neq_f32_e64 s[4:5], 1.0, v94
	s_cmp_eq_u64 s[4:5], 0
	s_cbranch_scc1 .Lwn_nosc_18
	v_pk_mul_f32 v[46:47], v[46:47], v[94:95] op_sel_hi:[1,0]
	v_pk_mul_f32 v[48:49], v[48:49], v[94:95] op_sel_hi:[1,0]
	v_pk_mul_f32 v[42:43], v[42:43], v[94:95] op_sel_hi:[1,0]
	v_pk_mul_f32 v[44:45], v[44:45], v[94:95] op_sel_hi:[1,0]
	v_pk_mul_f32 v[38:39], v[38:39], v[94:95] op_sel_hi:[1,0]
	v_pk_mul_f32 v[40:41], v[40:41], v[94:95] op_sel_hi:[1,0]
	v_pk_mul_f32 v[34:35], v[34:35], v[94:95] op_sel_hi:[1,0]
	v_pk_mul_f32 v[36:37], v[36:37], v[94:95] op_sel_hi:[1,0]
; #define LAS __attribute__((address_space(3)))
; template <int D, class SF>
; __device__ __forceinline__ void attn_step(const bf16x8 (&qf)[D / 32], const LAS bf16_t* Ks, const LAS bf16_t* Vt, f32x4 (&o)[D / 16], float& m, float& lsum, float& alpha_out, bf16x8& pf0_out, bf16x8& pf1_out, const int lane, SF sf) {
;     ...
;     for (int ks = 0; ks < D / 32; ++ks) {
; #pragma unroll
;         for (int t = 0; t < 4; ++t) { const bf16x8 kf = *(const LAS bf16x8*)(Ks + (16 * t + c) * KSTR + ks * 32 + 8 * i); s[t] = mfma16(kf, qf[ks], s[t]); }
;     }
;     float v[16];
; #pragma unroll
;     for (int t = 0; t < 4; ++t)
; #pragma unroll
;         for (int r = 0; r < 4; ++r) v[4 * t + r] = sf(16 * t + 4 * i + r, s[t][r]);
;     float mx = fmaxf(fmaxf(fmaxf(v[0], v[1]), fmaxf(v[2], v[3])), fmaxf(fmaxf(v[4], v[5]), fmaxf(v[6], v[7])));
;     mx = fmaxf(mx, fmaxf(fmaxf(fmaxf(v[8], v[9]), fmaxf(v[10], v[11])), fmaxf(fmaxf(v[12], v[13]), fmaxf(v[14], v[15]))));
;     mx = rows_max(mx);
;     const float mnew = fmaxf(m, mx);
;     const float mc = fmaxf(mnew, -1e20f);
;     const float alpha = __builtin_amdgcn_exp2f(fmaxf(m, -1e20f) - mc);
;     float p[16], rs = 0.f;
; #pragma unroll
;     for (int r = 0; r < 16; ++r) { p[r] = __builtin_amdgcn_exp2f(v[r] - mc); rs += p[r]; }
;     rs = rows_sum(rs);
;     lsum = lsum * alpha + rs; m = mnew;
;     union { u32x4 u; bf16x8 b; } pk0, pk1;
;     pk0.u.x = cvt_pk_bf16(p[0], p[1]); pk0.u.y = cvt_pk_bf16(p[2], p[3]); pk0.u.z = cvt_pk_bf16(p[4], p[5]); pk0.u.w = cvt_pk_bf16(p[6], p[7]);
;     pk1.u.x = cvt_pk_bf16(p[8], p[9]); pk1.u.y = cvt_pk_bf16(p[10], p[11]); pk1.u.z = cvt_pk_bf16(p[12], p[13]); pk1.u.w = cvt_pk_bf16(p[14], p[15]);
;     if (__builtin_amdgcn_ballot_w64(alpha != 1.0f) != 0ull) {
; #pragma unroll
;         for (int dt = 0; dt < D / 16; ++dt) o[dt] *= alpha;
;     }
; #pragma unroll
;     for (int dt = 0; dt < D / 16; ++dt) {
;         const LAS bf16_t* vp = Vt + (16 * dt + c) * 72 + 4 * i;
;         union { u32x4 u; bf16x8 b; } vf0, vf1; const u32x2 a0 = *(const LAS u32x2*)vp, a1 = *(const LAS u32x2*)(vp + 16), b0 = *(const LAS u32x2*)(vp + 32), b1 = *(const LAS u32x2*)(vp + 48);
;         vf0.u.x = a0.x; vf0.u.y = a0.y; vf0.u.z = a1.x; vf0.u.w = a1.y; vf1.u.x = b0.x; vf1.u.y = b0.y; vf1.u.z = b1.x; vf1.u.w = b1.y;
;         o[dt] = mfma16(vf0.b, pk0.b, o[dt]); o[dt] = mfma16(vf1.b, pk1.b, o[dt]);
;     }
.Lwn_nosc_18:
	s_waitcnt lgkmcnt(0)
	s_nop 1
	v_mfma_f32_16x16x32_bf16 v[46:49], v[50:53], v[82:85], v[46:49]
	v_mfma_f32_16x16x32_bf16 v[42:45], v[58:61], v[82:85], v[42:45]
	v_mfma_f32_16x16x32_bf16 v[38:41], v[66:69], v[82:85], v[38:41]
	v_mfma_f32_16x16x32_bf16 v[34:37], v[74:77], v[82:85], v[34:37]
	v_mfma_f32_16x16x32_bf16 v[46:49], v[54:57], v[86:89], v[46:49]
	v_mfma_f32_16x16x32_bf16 v[42:45], v[62:65], v[86:89], v[42:45]
	v_mfma_f32_16x16x32_bf16 v[38:41], v[70:73], v[86:89], v[38:41]
	v_mfma_f32_16x16x32_bf16 v[34:37], v[78:81], v[86:89], v[34:37]
	v_sub_u32_e32 v90, v180, v139
	v_subrev_u32_e32 v90, s21, v90
	v_lshl_add_u32 v91, v90, 2, v131
	v_add_u32_e32 v91, 0xffffff34, v91
	ds_read_b32 v170, v91 offset:204
	ds_read_b32 v171, v91 offset:200
	ds_read_b32 v172, v91 offset:196
	ds_read_b32 v173, v91 offset:192
	ds_read_b32 v174, v91 offset:140
	ds_read_b32 v175, v91 offset:136
	ds_read_b32 v176, v91 offset:132
	ds_read_b32 v177, v91 offset:128
	ds_read_b128 v[50:53], v116 offset:4096
	ds_read_b128 v[58:61], v116 offset:6400
	ds_read_b128 v[54:57], v116 offset:4160
	ds_read_b128 v[62:65], v116 offset:6464
	ds_read_b128 v[66:69], v116 offset:8704
	ds_read_b128 v[74:77], v116 offset:11008
	ds_read_b128 v[70:73], v116 offset:8768
	ds_read_b128 v[78:81], v116 offset:11072
	s_waitcnt lgkmcnt(6)
	v_mfma_f32_16x16x32_bf16 v[100:103], v[50:53], v[10:13], 0
	v_mfma_f32_16x16x32_bf16 v[104:107], v[58:61], v[10:13], 0
	s_waitcnt lgkmcnt(4)
	v_mfma_f32_16x16x32_bf16 v[100:103], v[54:57], v[14:17], v[100:103]
	v_mfma_f32_16x16x32_bf16 v[104:107], v[62:65], v[14:17], v[104:107]
	s_waitcnt lgkmcnt(2)
	v_mfma_f32_16x16x32_bf16 v[108:111], v[66:69], v[10:13], 0
	v_mfma_f32_16x16x32_bf16 v[112:115], v[74:77], v[10:13], 0
	s_waitcnt lgkmcnt(0)
	v_mfma_f32_16x16x32_bf16 v[108:111], v[70:73], v[14:17], v[108:111]
	v_mfma_f32_16x16x32_bf16 v[112:115], v[78:81], v[14:17], v[112:115]
	ds_read_b64_tr_b16 v[50:51], v117 offset:13312
	ds_read_b64_tr_b16 v[52:53], v117 offset:15616
	ds_read_b64_tr_b16 v[54:55], v117 offset:17920
	ds_read_b64_tr_b16 v[56:57], v117 offset:20224
	ds_read_b64_tr_b16 v[58:59], v117 offset:13344
	ds_read_b64_tr_b16 v[60:61], v117 offset:15648
	ds_read_b64_tr_b16 v[62:63], v117 offset:17952
	v_fmamk_f32 v100, v100, 0x3fb8aa3b, v170
	v_fmamk_f32 v101, v101, 0x3fb8aa3b, v171
	v_fmamk_f32 v102, v102, 0x3fb8aa3b, v172
	v_fmamk_f32 v103, v103, 0x3fb8aa3b, v173
	v_fmamk_f32 v104, v104, 0x3fb8aa3b, v174
	v_fmamk_f32 v105, v105, 0x3fb8aa3b, v175
	v_fmamk_f32 v106, v106, 0x3fb8aa3b, v176
	v_fmamk_f32 v107, v107, 0x3fb8aa3b, v177
	ds_read_b32 v170, v91 offset:76
	ds_read_b32 v171, v91 offset:72
	ds_read_b32 v172, v91 offset:68
	ds_read_b32 v173, v91 offset:64
	ds_read_b32 v174, v91 offset:12
	ds_read_b32 v175, v91 offset:8
	ds_read_b32 v176, v91 offset:4
	ds_read_b32 v177, v91 offset:0
	ds_read_b64_tr_b16 v[64:65], v117 offset:20256
	ds_read_b64_tr_b16 v[66:67], v117 offset:13376
	ds_read_b64_tr_b16 v[68:69], v117 offset:15680
	ds_read_b64_tr_b16 v[70:71], v117 offset:17984
	ds_read_b64_tr_b16 v[72:73], v117 offset:20288
	ds_read_b64_tr_b16 v[74:75], v117 offset:13408
	ds_read_b64_tr_b16 v[76:77], v117 offset:15712
	ds_read_b64_tr_b16 v[78:79], v117 offset:18016
	ds_read_b64_tr_b16 v[80:81], v117 offset:20320
	s_waitcnt lgkmcnt(9)
	v_fmamk_f32 v108, v108, 0x3fb8aa3b, v170
	v_fmamk_f32 v109, v109, 0x3fb8aa3b, v171
	v_fmamk_f32 v110, v110, 0x3fb8aa3b, v172
	v_fmamk_f32 v111, v111, 0x3fb8aa3b, v173
	v_fmamk_f32 v112, v112, 0x3fb8aa3b, v174
	v_fmamk_f32 v113, v113, 0x3fb8aa3b, v175
	v_fmamk_f32 v114, v114, 0x3fb8aa3b, v176
	v_fmamk_f32 v115, v115, 0x3fb8aa3b, v177
	v_max3_f32 v96, v100, v101, v102
	v_max3_f32 v91, v103, v104, v105
	v_max3_f32 v92, v106, v107, v108
	v_max3_f32 v93, v109, v110, v111
	v_max3_f32 v95, v112, v113, v114
	v_max3_f32 v96, v96, v91, v115
	v_max3_f32 v92, v92, v93, v95
	v_max_f32_e32 v96, v96, v92
	v_mov_b32_e32 v91, v96
	s_nop 1
	v_permlane16_swap_b32_e32 v96, v91
	v_max_f32_e32 v96, v96, v91
	v_mov_b32_e32 v91, v96
	s_nop 1
	v_permlane32_swap_b32_e32 v96, v91
	v_max_f32_e32 v96, v96, v91
	v_max_f32_e32 v92, v160, v96
	v_max_f32_e32 v94, 0xe0ad78ec, v160
	v_max_f32_e32 v93, 0xe0ad78ec, v92
	v_sub_f32_e32 v94, v94, v93
	v_mov_b32_e32 v160, v92
	v_exp_f32_e32 v94, v94
	v_sub_f32_e32 v100, v100, v93
	v_sub_f32_e32 v101, v101, v93
	v_sub_f32_e32 v102, v102, v93
	v_sub_f32_e32 v103, v103, v93
	v_exp_f32_e32 v100, v100
	v_exp_f32_e32 v101, v101
	v_exp_f32_e32 v102, v102
	v_exp_f32_e32 v103, v103
	v_sub_f32_e32 v104, v104, v93
	v_sub_f32_e32 v105, v105, v93
	v_sub_f32_e32 v106, v106, v93
	v_sub_f32_e32 v107, v107, v93
	v_exp_f32_e32 v104, v104
	v_exp_f32_e32 v105, v105
	v_exp_f32_e32 v106, v106
	v_exp_f32_e32 v107, v107
	v_sub_f32_e32 v108, v108, v93
	v_sub_f32_e32 v109, v109, v93
	v_sub_f32_e32 v110, v110, v93
	v_sub_f32_e32 v111, v111, v93
	v_exp_f32_e32 v108, v108
	v_exp_f32_e32 v109, v109
	v_exp_f32_e32 v110, v110
	v_exp_f32_e32 v111, v111
	v_sub_f32_e32 v112, v112, v93
	v_sub_f32_e32 v113, v113, v93
	v_sub_f32_e32 v114, v114, v93
	v_sub_f32_e32 v115, v115, v93
	v_exp_f32_e32 v112, v112
	v_exp_f32_e32 v113, v113
	v_exp_f32_e32 v114, v114
	v_exp_f32_e32 v115, v115
	s_nop 0
	v_add_f32_e32 v90, v100, v101
	v_add_f32_e32 v91, v102, v103
	v_add_f32_e32 v92, v104, v105
	v_add_f32_e32 v93, v106, v107
	v_add_f32_e32 v90, v90, v108
	v_add_f32_e32 v91, v91, v109
	v_add_f32_e32 v92, v92, v110
	v_add_f32_e32 v93, v93, v111
	v_add_f32_e32 v90, v90, v112
	v_add_f32_e32 v91, v91, v113
	v_add_f32_e32 v92, v92, v114
	v_add_f32_e32 v93, v93, v115
	v_add_f32_e32 v90, v90, v91
	v_add_f32_e32 v92, v92, v93
	v_add_f32_e32 v90, v90, v92
	v_cvt_pk_bf16_f32 v82, v100, v101
	v_cvt_pk_bf16_f32 v83, v102, v103
	v_cvt_pk_bf16_f32 v84, v104, v105
	v_cvt_pk_bf16_f32 v85, v106, v107
	v_cvt_pk_bf16_f32 v86, v108, v109
	v_cvt_pk_bf16_f32 v87, v110, v111
	v_cvt_pk_bf16_f32 v88, v112, v113
	v_cvt_pk_bf16_f32 v89, v114, v115
	v_mov_b32_e32 v91, v90
	s_nop 1
	v_permlane16_swap_b32_e32 v90, v91
	v_add_f32_e32 v90, v90, v91
	v_mov_b32_e32 v91, v90
	s_nop 1
	v_permlane32_swap_b32_e32 v90, v91
	v_add_f32_e32 v90, v90, v91
	v_fma_f32 v159, v159, v94, v90
	v_cmp_neq_f32_e64 s[4:5], 1.0, v94
	s_cmp_eq_u64 s[4:5], 0
	s_cbranch_scc1 .Lwn_nosc_19
	v_pk_mul_f32 v[30:31], v[30:31], v[94:95] op_sel_hi:[1,0]
	v_pk_mul_f32 v[32:33], v[32:33], v[94:95] op_sel_hi:[1,0]
	v_pk_mul_f32 v[26:27], v[26:27], v[94:95] op_sel_hi:[1,0]
	v_pk_mul_f32 v[28:29], v[28:29], v[94:95] op_sel_hi:[1,0]
	v_pk_mul_f32 v[22:23], v[22:23], v[94:95] op_sel_hi:[1,0]
	v_pk_mul_f32 v[24:25], v[24:25], v[94:95] op_sel_hi:[1,0]
	v_pk_mul_f32 v[18:19], v[18:19], v[94:95] op_sel_hi:[1,0]
	v_pk_mul_f32 v[20:21], v[20:21], v[94:95] op_sel_hi:[1,0]

; template <int D, class SF>
; __device__ __forceinline__ void attn_step(const bf16x8 (&qf)[D / 32], const LAS bf16_t* Ks, const LAS bf16_t* Vt, f32x4 (&o)[D / 16], float& m, float& lsum, float& alpha_out, bf16x8& pf0_out, bf16x8& pf1_out, const int lane, SF sf) {
;     ...
;     for (int ks = 0; ks < D / 32; ++ks) {
; #pragma unroll
;         for (int t = 0; t < 4; ++t) { const bf16x8 kf = *(const LAS bf16x8*)(Ks + (16 * t + c) * KSTR + ks * 32 + 8 * i); s[t] = mfma16(kf, qf[ks], s[t]); }
;     }
;     float v[16];
; #pragma unroll
;     for (int t = 0; t < 4; ++t)
; #pragma unroll
;         for (int r = 0; r < 4; ++r) v[4 * t + r] = sf(16 * t + 4 * i + r, s[t][r]);
;     float mx = fmaxf(fmaxf(fmaxf(v[0], v[1]), fmaxf(v[2], v[3])), fmaxf(fmaxf(v[4], v[5]), fmaxf(v[6], v[7])));
;     mx = fmaxf(mx, fmaxf(fmaxf(fmaxf(v[8], v[9]), fmaxf(v[10], v[11])), fmaxf(fmaxf(v[12], v[13]), fmaxf(v[14], v[15]))));
;     mx = rows_max(mx);
;     const float mnew = fmaxf(m, mx);
;     const float mc = fmaxf(mnew, -1e20f);
;     const float alpha = __builtin_amdgcn_exp2f(fmaxf(m, -1e20f) - mc);
;     float p[16], rs = 0.f;
; #pragma unroll
;     for (int r = 0; r < 16; ++r) { p[r] = __builtin_amdgcn_exp2f(v[r] - mc); rs += p[r]; }
;     rs = rows_sum(rs);
;     lsum = lsum * alpha + rs; m = mnew;
;     union { u32x4 u; bf16x8 b; } pk0, pk1;
;     pk0.u.x = cvt_pk_bf16(p[0], p[1]); pk0.u.y = cvt_pk_bf16(p[2], p[3]); pk0.u.z = cvt_pk_bf16(p[4], p[5]); pk0.u.w = cvt_pk_bf16(p[6], p[7]);
;     pk1.u.x = cvt_pk_bf16(p[8], p[9]); pk1.u.y = cvt_pk_bf16(p[10], p[11]); pk1.u.z = cvt_pk_bf16(p[12], p[13]); pk1.u.w = cvt_pk_bf16(p[14], p[15]);
;     if (__builtin_amdgcn_ballot_w64(alpha != 1.0f) != 0ull) {
; #pragma unroll
; __device__ __forceinline__ void nsa_unit(LAS unsigned char* lds, const Ctx& P, int l, int b, int hkv, int tb) {
;     ...
;             for (int sl = 0; sl < 2; ++sl) if (sl == 0 || hasb) { const LAS bf16_t* Ks = KV + sl * 9216; const LAS bf16_t* Vt = Ks + 4608; const int kp0 = p0 + sl * 64;
; #pragma unroll
;                 for (int sb = 0; sb < 2; ++sb) { const int tqs = tq[sb];
;                     attn_step<64>(qf[sb], Ks, Vt, o[sb], m[sb], lsum[sb], alpha, pf, pf1, lane,
;                         [&](int kk, float s) { const int kpos = kp0 + kk, dist = tqs - kpos; return (dist >= 0 && dist < 256 && kpos >= 0) ? s * LOG2E + lut[min((unsigned)dist, 1023u)] : NEGBIG; }); }
.Lwn_wc_17:
	s_cmp_gt_u32 s20, 3
	s_cbranch_scc1 .Lwn_wc_20
	s_add_i32 s21, s12, 192
	v_sub_u32_e32 v90, v130, v139
	v_subrev_u32_e32 v90, s21, v90
	v_lshl_add_u32 v91, v90, 2, v131
	v_add_u32_e32 v91, 0xffffff34, v91
	ds_read_b32 v170, v91 offset:204
	ds_read_b32 v171, v91 offset:200
	ds_read_b32 v172, v91 offset:196
	ds_read_b32 v173, v91 offset:192
	ds_read_b32 v174, v91 offset:140
	ds_read_b32 v175, v91 offset:136
	ds_read_b32 v176, v91 offset:132
	ds_read_b32 v177, v91 offset:128
	ds_read_b128 v[50:53], v116 offset:22528
	ds_read_b128 v[58:61], v116 offset:24832
	ds_read_b128 v[54:57], v116 offset:22592
	ds_read_b128 v[62:65], v116 offset:24896
	ds_read_b128 v[66:69], v116 offset:27136
	ds_read_b128 v[74:77], v116 offset:29440
	ds_read_b128 v[70:73], v116 offset:27200
	ds_read_b128 v[78:81], v116 offset:29504
	s_waitcnt lgkmcnt(6)
	v_mfma_f32_16x16x32_bf16 v[100:103], v[50:53], v[2:5], 0
	v_mfma_f32_16x16x32_bf16 v[104:107], v[58:61], v[2:5], 0
	s_waitcnt lgkmcnt(4)
	v_mfma_f32_16x16x32_bf16 v[100:103], v[54:57], v[6:9], v[100:103]
	v_mfma_f32_16x16x32_bf16 v[104:107], v[62:65], v[6:9], v[104:107]
	s_waitcnt lgkmcnt(2)
	v_mfma_f32_16x16x32_bf16 v[108:111], v[66:69], v[2:5], 0
	v_mfma_f32_16x16x32_bf16 v[112:115], v[74:77], v[2:5], 0
	s_waitcnt lgkmcnt(0)
	v_mfma_f32_16x16x32_bf16 v[108:111], v[70:73], v[6:9], v[108:111]
	v_mfma_f32_16x16x32_bf16 v[112:115], v[78:81], v[6:9], v[112:115]
	ds_read_b64_tr_b16 v[50:51], v117 offset:31744
	ds_read_b64_tr_b16 v[52:53], v117 offset:34048
	ds_read_b64_tr_b16 v[54:55], v117 offset:36352
	ds_read_b64_tr_b16 v[56:57], v117 offset:38656
	ds_read_b64_tr_b16 v[58:59], v117 offset:31776
	ds_read_b64_tr_b16 v[60:61], v117 offset:34080
	ds_read_b64_tr_b16 v[62:63], v117 offset:36384
	v_fmamk_f32 v100, v100, 0x3fb8aa3b, v170
	v_fmamk_f32 v101, v101, 0x3fb8aa3b, v171
	v_fmamk_f32 v102, v102, 0x3fb8aa3b, v172
	v_fmamk_f32 v103, v103, 0x3fb8aa3b, v173
	v_fmamk_f32 v104, v104, 0x3fb8aa3b, v174
	v_fmamk_f32 v105, v105, 0x3fb8aa3b, v175
	v_fmamk_f32 v106, v106, 0x3fb8aa3b, v176
	v_fmamk_f32 v107, v107, 0x3fb8aa3b, v177
	ds_read_b32 v170, v91 offset:76
	ds_read_b32 v171, v91 offset:72
	ds_read_b32 v172, v91 offset:68
	ds_read_b32 v173, v91 offset:64
	ds_read_b32 v174, v91 offset:12
	ds_read_b32 v175, v91 offset:8
	ds_read_b32 v176, v91 offset:4
	ds_read_b32 v177, v91 offset:0
	ds_read_b64_tr_b16 v[64:65], v117 offset:38688
	ds_read_b64_tr_b16 v[66:67], v117 offset:31808
	ds_read_b64_tr_b16 v[68:69], v117 offset:34112
	ds_read_b64_tr_b16 v[70:71], v117 offset:36416
	ds_read_b64_tr_b16 v[72:73], v117 offset:38720
	ds_read_b64_tr_b16 v[74:75], v117 offset:31840
	ds_read_b64_tr_b16 v[76:77], v117 offset:34144
	ds_read_b64_tr_b16 v[78:79], v117 offset:36448
	ds_read_b64_tr_b16 v[80:81], v117 offset:38752
	s_waitcnt lgkmcnt(9)
	v_fmamk_f32 v108, v108, 0x3fb8aa3b, v170
	v_fmamk_f32 v109, v109, 0x3fb8aa3b, v171
	v_fmamk_f32 v110, v110, 0x3fb8aa3b, v172
	v_fmamk_f32 v111, v111, 0x3fb8aa3b, v173
	v_fmamk_f32 v112, v112, 0x3fb8aa3b, v174
	v_fmamk_f32 v113, v113, 0x3fb8aa3b, v175
	v_fmamk_f32 v114, v114, 0x3fb8aa3b, v176
	v_fmamk_f32 v115, v115, 0x3fb8aa3b, v177
	v_max3_f32 v96, v100, v101, v102
	v_max3_f32 v91, v103, v104, v105
	v_max3_f32 v92, v106, v107, v108
	v_max3_f32 v93, v109, v110, v111
	v_max3_f32 v95, v112, v113, v114
	v_max3_f32 v96, v96, v91, v115
	v_max3_f32 v92, v92, v93, v95
	v_max_f32_e32 v96, v96, v92
	v_mov_b32_e32 v91, v96
	s_nop 1
	v_permlane16_swap_b32_e32 v96, v91
	v_max_f32_e32 v96, v96, v91
	v_mov_b32_e32 v91, v96
	s_nop 1
	v_permlane32_swap_b32_e32 v96, v91
	v_max_f32_e32 v96, v96, v91
	v_max_f32_e32 v92, v162, v96
	v_max_f32_e32 v94, 0xe0ad78ec, v162
	v_max_f32_e32 v93, 0xe0ad78ec, v92
	v_sub_f32_e32 v94, v94, v93
	v_mov_b32_e32 v162, v92
	v_exp_f32_e32 v94, v94
	v_sub_f32_e32 v100, v100, v93
	v_sub_f32_e32 v101, v101, v93
	v_sub_f32_e32 v102, v102, v93
	v_sub_f32_e32 v103, v103, v93
	v_exp_f32_e32 v100, v100
	v_exp_f32_e32 v101, v101
	v_exp_f32_e32 v102, v102
	v_exp_f32_e32 v103, v103
	v_sub_f32_e32 v104, v104, v93
	v_sub_f32_e32 v105, v105, v93
	v_sub_f32_e32 v106, v106, v93
	v_sub_f32_e32 v107, v107, v93
	v_exp_f32_e32 v104, v104
	v_exp_f32_e32 v105, v105
	v_exp_f32_e32 v106, v106
	v_exp_f32_e32 v107, v107
	v_sub_f32_e32 v108, v108, v93
	v_sub_f32_e32 v109, v109, v93
	v_sub_f32_e32 v110, v110, v93
	v_sub_f32_e32 v111, v111, v93
	v_exp_f32_e32 v108, v108
	v_exp_f32_e32 v109, v109
	v_exp_f32_e32 v110, v110
	v_exp_f32_e32 v111, v111
	v_sub_f32_e32 v112, v112, v93
	v_sub_f32_e32 v113, v113, v93
	v_sub_f32_e32 v114, v114, v93
	v_sub_f32_e32 v115, v115, v93
	v_exp_f32_e32 v112, v112
	v_exp_f32_e32 v113, v113
	v_exp_f32_e32 v114, v114
	v_exp_f32_e32 v115, v115
	s_nop 0
	v_add_f32_e32 v90, v100, v101
	v_add_f32_e32 v91, v102, v103
	v_add_f32_e32 v92, v104, v105
	v_add_f32_e32 v93, v106, v107
	v_add_f32_e32 v90, v90, v108
	v_add_f32_e32 v91, v91, v109
	v_add_f32_e32 v92, v92, v110
	v_add_f32_e32 v93, v93, v111
	v_add_f32_e32 v90, v90, v112
	v_add_f32_e32 v91, v91, v113
	v_add_f32_e32 v92, v92, v114
	v_add_f32_e32 v93, v93, v115
	v_add_f32_e32 v90, v90, v91
	v_add_f32_e32 v92, v92, v93
	v_add_f32_e32 v90, v90, v92
	v_cvt_pk_bf16_f32 v82, v100, v101
	v_cvt_pk_bf16_f32 v83, v102, v103
	v_cvt_pk_bf16_f32 v84, v104, v105
	v_cvt_pk_bf16_f32 v85, v106, v107
	v_cvt_pk_bf16_f32 v86, v108, v109
	v_cvt_pk_bf16_f32 v87, v110, v111
	v_cvt_pk_bf16_f32 v88, v112, v113
	v_cvt_pk_bf16_f32 v89, v114, v115
	v_mov_b32_e32 v91, v90
	s_nop 1
	v_permlane16_swap_b32_e32 v90, v91
	v_add_f32_e32 v90, v90, v91
	v_mov_b32_e32 v91, v90
	s_nop 1
	v_permlane32_swap_b32_e32 v90, v91
	v_add_f32_e32 v90, v90, v91
	v_fma_f32 v161, v161, v94, v90
	v_cmp_neq_f32_e64 s[4:5], 1.0, v94
	s_cmp_eq_u64 s[4:5], 0
	s_cbranch_scc1 .Lwn_nosc_21
	v_pk_mul_f32 v[46:47], v[46:47], v[94:95] op_sel_hi:[1,0]
	v_pk_mul_f32 v[48:49], v[48:49], v[94:95] op_sel_hi:[1,0]
	v_pk_mul_f32 v[42:43], v[42:43], v[94:95] op_sel_hi:[1,0]
	v_pk_mul_f32 v[44:45], v[44:45], v[94:95] op_sel_hi:[1,0]
	v_pk_mul_f32 v[38:39], v[38:39], v[94:95] op_sel_hi:[1,0]
	v_pk_mul_f32 v[40:41], v[40:41], v[94:95] op_sel_hi:[1,0]
	v_pk_mul_f32 v[34:35], v[34:35], v[94:95] op_sel_hi:[1,0]
	v_pk_mul_f32 v[36:37], v[36:37], v[94:95] op_sel_hi:[1,0]
; #define LAS __attribute__((address_space(3)))
; template <int D, class SF>
; __device__ __forceinline__ void attn_step(const bf16x8 (&qf)[D / 32], const LAS bf16_t* Ks, const LAS bf16_t* Vt, f32x4 (&o)[D / 16], float& m, float& lsum, float& alpha_out, bf16x8& pf0_out, bf16x8& pf1_out, const int lane, SF sf) {
;     ...
;     for (int ks = 0; ks < D / 32; ++ks) {
; #pragma unroll
;         for (int t = 0; t < 4; ++t) { const bf16x8 kf = *(const LAS bf16x8*)(Ks + (16 * t + c) * KSTR + ks * 32 + 8 * i); s[t] = mfma16(kf, qf[ks], s[t]); }
;     }
;     float v[16];
; #pragma unroll
;     for (int t = 0; t < 4; ++t)
; #pragma unroll
;         for (int r = 0; r < 4; ++r) v[4 * t + r] = sf(16 * t + 4 * i + r, s[t][r]);
;     float mx = fmaxf(fmaxf(fmaxf(v[0], v[1]), fmaxf(v[2], v[3])), fmaxf(fmaxf(v[4], v[5]), fmaxf(v[6], v[7])));
;     mx = fmaxf(mx, fmaxf(fmaxf(fmaxf(v[8], v[9]), fmaxf(v[10], v[11])), fmaxf(fmaxf(v[12], v[13]), fmaxf(v[14], v[15]))));
;     mx = rows_max(mx);
;     const float mnew = fmaxf(m, mx);
;     const float mc = fmaxf(mnew, -1e20f);
;     const float alpha = __builtin_amdgcn_exp2f(fmaxf(m, -1e20f) - mc);
;     float p[16], rs = 0.f;
; #pragma unroll
;     for (int r = 0; r < 16; ++r) { p[r] = __builtin_amdgcn_exp2f(v[r] - mc); rs += p[r]; }
;     rs = rows_sum(rs);
;     lsum = lsum * alpha + rs; m = mnew;
;     union { u32x4 u; bf16x8 b; } pk0, pk1;
;     pk0.u.x = cvt_pk_bf16(p[0], p[1]); pk0.u.y = cvt_pk_bf16(p[2], p[3]); pk0.u.z = cvt_pk_bf16(p[4], p[5]); pk0.u.w = cvt_pk_bf16(p[6], p[7]);
;     pk1.u.x = cvt_pk_bf16(p[8], p[9]); pk1.u.y = cvt_pk_bf16(p[10], p[11]); pk1.u.z = cvt_pk_bf16(p[12], p[13]); pk1.u.w = cvt_pk_bf16(p[14], p[15]);
;     if (__builtin_amdgcn_ballot_w64(alpha != 1.0f) != 0ull) {
; #pragma unroll
;         for (int dt = 0; dt < D / 16; ++dt) o[dt] *= alpha;
;     }
; #pragma unroll
;     for (int dt = 0; dt < D / 16; ++dt) {
;         const LAS bf16_t* vp = Vt + (16 * dt + c) * 72 + 4 * i;
;         union { u32x4 u; bf16x8 b; } vf0, vf1; const u32x2 a0 = *(const LAS u32x2*)vp, a1 = *(const LAS u32x2*)(vp + 16), b0 = *(const LAS u32x2*)(vp + 32), b1 = *(const LAS u32x2*)(vp + 48);
;         vf0.u.x = a0.x; vf0.u.y = a0.y; vf0.u.z = a1.x; vf0.u.w = a1.y; vf1.u.x = b0.x; vf1.u.y = b0.y; vf1.u.z = b1.x; vf1.u.w = b1.y;
;         o[dt] = mfma16(vf0.b, pk0.b, o[dt]); o[dt] = mfma16(vf1.b, pk1.b, o[dt]);
;     }
.Lwn_nosc_21:
	s_waitcnt lgkmcnt(0)
	s_nop 1
	v_mfma_f32_16x16x32_bf16 v[46:49], v[50:53], v[82:85], v[46:49]
	v_mfma_f32_16x16x32_bf16 v[42:45], v[58:61], v[82:85], v[42:45]
	v_mfma_f32_16x16x32_bf16 v[38:41], v[66:69], v[82:85], v[38:41]
	v_mfma_f32_16x16x32_bf16 v[34:37], v[74:77], v[82:85], v[34:37]
	v_mfma_f32_16x16x32_bf16 v[46:49], v[54:57], v[86:89], v[46:49]
	v_mfma_f32_16x16x32_bf16 v[42:45], v[62:65], v[86:89], v[42:45]
	v_mfma_f32_16x16x32_bf16 v[38:41], v[70:73], v[86:89], v[38:41]
	v_mfma_f32_16x16x32_bf16 v[34:37], v[78:81], v[86:89], v[34:37]
	v_sub_u32_e32 v90, v180, v139
	v_subrev_u32_e32 v90, s21, v90
	v_lshl_add_u32 v91, v90, 2, v131
	v_add_u32_e32 v91, 0xffffff34, v91
	ds_read_b32 v170, v91 offset:204
	ds_read_b32 v171, v91 offset:200
	ds_read_b32 v172, v91 offset:196
	ds_read_b32 v173, v91 offset:192
	ds_read_b32 v174, v91 offset:140
	ds_read_b32 v175, v91 offset:136
	ds_read_b32 v176, v91 offset:132
	ds_read_b32 v177, v91 offset:128
	ds_read_b128 v[50:53], v116 offset:22528
	ds_read_b128 v[58:61], v116 offset:24832
	ds_read_b128 v[54:57], v116 offset:22592
	ds_read_b128 v[62:65], v116 offset:24896
	ds_read_b128 v[66:69], v116 offset:27136
	ds_read_b128 v[74:77], v116 offset:29440
	ds_read_b128 v[70:73], v116 offset:27200
	ds_read_b128 v[78:81], v116 offset:29504
	s_waitcnt lgkmcnt(6)
	v_mfma_f32_16x16x32_bf16 v[100:103], v[50:53], v[10:13], 0
	v_mfma_f32_16x16x32_bf16 v[104:107], v[58:61], v[10:13], 0
	s_waitcnt lgkmcnt(4)
	v_mfma_f32_16x16x32_bf16 v[100:103], v[54:57], v[14:17], v[100:103]
	v_mfma_f32_16x16x32_bf16 v[104:107], v[62:65], v[14:17], v[104:107]
	s_waitcnt lgkmcnt(2)
	v_mfma_f32_16x16x32_bf16 v[108:111], v[66:69], v[10:13], 0
	v_mfma_f32_16x16x32_bf16 v[112:115], v[74:77], v[10:13], 0
	s_waitcnt lgkmcnt(0)
	v_mfma_f32_16x16x32_bf16 v[108:111], v[70:73], v[14:17], v[108:111]
	v_mfma_f32_16x16x32_bf16 v[112:115], v[78:81], v[14:17], v[112:115]
	ds_read_b64_tr_b16 v[50:51], v117 offset:31744
	ds_read_b64_tr_b16 v[52:53], v117 offset:34048
	ds_read_b64_tr_b16 v[54:55], v117 offset:36352
	ds_read_b64_tr_b16 v[56:57], v117 offset:38656
	ds_read_b64_tr_b16 v[58:59], v117 offset:31776
	ds_read_b64_tr_b16 v[60:61], v117 offset:34080
	ds_read_b64_tr_b16 v[62:63], v117 offset:36384
	v_fmamk_f32 v100, v100, 0x3fb8aa3b, v170
	v_fmamk_f32 v101, v101, 0x3fb8aa3b, v171
	v_fmamk_f32 v102, v102, 0x3fb8aa3b, v172
	v_fmamk_f32 v103, v103, 0x3fb8aa3b, v173
	v_fmamk_f32 v104, v104, 0x3fb8aa3b, v174
	v_fmamk_f32 v105, v105, 0x3fb8aa3b, v175
	v_fmamk_f32 v106, v106, 0x3fb8aa3b, v176
	v_fmamk_f32 v107, v107, 0x3fb8aa3b, v177
	ds_read_b32 v170, v91 offset:76
	ds_read_b32 v171, v91 offset:72
	ds_read_b32 v172, v91 offset:68
	ds_read_b32 v173, v91 offset:64
	ds_read_b32 v174, v91 offset:12
	ds_read_b32 v175, v91 offset:8
	ds_read_b32 v176, v91 offset:4
	ds_read_b32 v177, v91 offset:0
	ds_read_b64_tr_b16 v[64:65], v117 offset:38688
	ds_read_b64_tr_b16 v[66:67], v117 offset:31808
	ds_read_b64_tr_b16 v[68:69], v117 offset:34112
	ds_read_b64_tr_b16 v[70:71], v117 offset:36416
	ds_read_b64_tr_b16 v[72:73], v117 offset:38720
	ds_read_b64_tr_b16 v[74:75], v117 offset:31840
	ds_read_b64_tr_b16 v[76:77], v117 offset:34144
	ds_read_b64_tr_b16 v[78:79], v117 offset:36448
	ds_read_b64_tr_b16 v[80:81], v117 offset:38752
	s_waitcnt lgkmcnt(9)
	v_fmamk_f32 v108, v108, 0x3fb8aa3b, v170
	v_fmamk_f32 v109, v109, 0x3fb8aa3b, v171
	v_fmamk_f32 v110, v110, 0x3fb8aa3b, v172
	v_fmamk_f32 v111, v111, 0x3fb8aa3b, v173
	v_fmamk_f32 v112, v112, 0x3fb8aa3b, v174
	v_fmamk_f32 v113, v113, 0x3fb8aa3b, v175
	v_fmamk_f32 v114, v114, 0x3fb8aa3b, v176
	v_fmamk_f32 v115, v115, 0x3fb8aa3b, v177
	v_max3_f32 v96, v100, v101, v102
	v_max3_f32 v91, v103, v104, v105
	v_max3_f32 v92, v106, v107, v108
	v_max3_f32 v93, v109, v110, v111
	v_max3_f32 v95, v112, v113, v114
	v_max3_f32 v96, v96, v91, v115
	v_max3_f32 v92, v92, v93, v95
	v_max_f32_e32 v96, v96, v92
	v_mov_b32_e32 v91, v96
	s_nop 1
	v_permlane16_swap_b32_e32 v96, v91
	v_max_f32_e32 v96, v96, v91
	v_mov_b32_e32 v91, v96
	s_nop 1
	v_permlane32_swap_b32_e32 v96, v91
	v_max_f32_e32 v96, v96, v91
	v_max_f32_e32 v92, v160, v96
	v_max_f32_e32 v94, 0xe0ad78ec, v160
	v_max_f32_e32 v93, 0xe0ad78ec, v92
	v_sub_f32_e32 v94, v94, v93
	v_mov_b32_e32 v160, v92
	v_exp_f32_e32 v94, v94
	v_sub_f32_e32 v100, v100, v93
	v_sub_f32_e32 v101, v101, v93
	v_sub_f32_e32 v102, v102, v93
	v_sub_f32_e32 v103, v103, v93
	v_exp_f32_e32 v100, v100
	v_exp_f32_e32 v101, v101
	v_exp_f32_e32 v102, v102
	v_exp_f32_e32 v103, v103
	v_sub_f32_e32 v104, v104, v93
	v_sub_f32_e32 v105, v105, v93
	v_sub_f32_e32 v106, v106, v93
	v_sub_f32_e32 v107, v107, v93
	v_exp_f32_e32 v104, v104
	v_exp_f32_e32 v105, v105
	v_exp_f32_e32 v106, v106
	v_exp_f32_e32 v107, v107
	v_sub_f32_e32 v108, v108, v93
	v_sub_f32_e32 v109, v109, v93
	v_sub_f32_e32 v110, v110, v93
	v_sub_f32_e32 v111, v111, v93
	v_exp_f32_e32 v108, v108
	v_exp_f32_e32 v109, v109
	v_exp_f32_e32 v110, v110
	v_exp_f32_e32 v111, v111
	v_sub_f32_e32 v112, v112, v93
	v_sub_f32_e32 v113, v113, v93
	v_sub_f32_e32 v114, v114, v93
	v_sub_f32_e32 v115, v115, v93
	v_exp_f32_e32 v112, v112
	v_exp_f32_e32 v113, v113
	v_exp_f32_e32 v114, v114
	v_exp_f32_e32 v115, v115
	s_nop 0
	v_add_f32_e32 v90, v100, v101
	v_add_f32_e32 v91, v102, v103
	v_add_f32_e32 v92, v104, v105
	v_add_f32_e32 v93, v106, v107
	v_add_f32_e32 v90, v90, v108
	v_add_f32_e32 v91, v91, v109
	v_add_f32_e32 v92, v92, v110
	v_add_f32_e32 v93, v93, v111
	v_add_f32_e32 v90, v90, v112
	v_add_f32_e32 v91, v91, v113
	v_add_f32_e32 v92, v92, v114
	v_add_f32_e32 v93, v93, v115
	v_add_f32_e32 v90, v90, v91
	v_add_f32_e32 v92, v92, v93
	v_add_f32_e32 v90, v90, v92
	v_cvt_pk_bf16_f32 v82, v100, v101
	v_cvt_pk_bf16_f32 v83, v102, v103
	v_cvt_pk_bf16_f32 v84, v104, v105
	v_cvt_pk_bf16_f32 v85, v106, v107
	v_cvt_pk_bf16_f32 v86, v108, v109
	v_cvt_pk_bf16_f32 v87, v110, v111
	v_cvt_pk_bf16_f32 v88, v112, v113
	v_cvt_pk_bf16_f32 v89, v114, v115
	v_mov_b32_e32 v91, v90
	s_nop 1
	v_permlane16_swap_b32_e32 v90, v91
	v_add_f32_e32 v90, v90, v91
	v_mov_b32_e32 v91, v90
	s_nop 1
	v_permlane32_swap_b32_e32 v90, v91
	v_add_f32_e32 v90, v90, v91
	v_fma_f32 v159, v159, v94, v90
	v_cmp_neq_f32_e64 s[4:5], 1.0, v94
	s_cmp_eq_u64 s[4:5], 0
	s_cbranch_scc1 .Lwn_nosc_22
	v_pk_mul_f32 v[30:31], v[30:31], v[94:95] op_sel_hi:[1,0]
	v_pk_mul_f32 v[32:33], v[32:33], v[94:95] op_sel_hi:[1,0]
	v_pk_mul_f32 v[26:27], v[26:27], v[94:95] op_sel_hi:[1,0]
	v_pk_mul_f32 v[28:29], v[28:29], v[94:95] op_sel_hi:[1,0]
	v_pk_mul_f32 v[22:23], v[22:23], v[94:95] op_sel_hi:[1,0]
	v_pk_mul_f32 v[24:25], v[24:25], v[94:95] op_sel_hi:[1,0]
	v_pk_mul_f32 v[18:19], v[18:19], v[94:95] op_sel_hi:[1,0]
	v_pk_mul_f32 v[20:21], v[20:21], v[94:95] op_sel_hi:[1,0]

; #define LAS __attribute__((address_space(3)))
; __device__ __forceinline__ f32x4 mfma16(bf16x8 a, bf16x8 b, f32x4 c) { return __builtin_amdgcn_mfma_f32_16x16x32_bf16(a, b, c, 0, 0, 0); }
; template <int D, class SF>
; __device__ __forceinline__ void attn_step(const bf16x8 (&qf)[D / 32], const LAS bf16_t* Ks, const LAS bf16_t* Vt, f32x4 (&o)[D / 16], float& m, float& lsum, float& alpha_out, bf16x8& pf0_out, bf16x8& pf1_out, const int lane, SF sf) {
;     ...
;     for (int ks = 0; ks < D / 32; ++ks) {
; #pragma unroll
;         for (int t = 0; t < 4; ++t) { const bf16x8 kf = *(const LAS bf16x8*)(Ks + (16 * t + c) * KSTR + ks * 32 + 8 * i); s[t] = mfma16(kf, qf[ks], s[t]); }
;     }
;     float v[16];
; #pragma unroll
;     for (int t = 0; t < 4; ++t)
; #pragma unroll
;         for (int r = 0; r < 4; ++r) v[4 * t + r] = sf(16 * t + 4 * i + r, s[t][r]);
; __device__ __forceinline__ void nsa_unit(LAS unsigned char* lds, const Ctx& P, int l, int b, int hkv, int tb) {
;     ...
;             for (int sl = 0; sl < 2; ++sl) if (sl == 0 || hasb) { const LAS bf16_t* Ks = KV + sl * 9216; const LAS bf16_t* Vt = Ks + 4608; const int kp0 = p0 + sl * 64;
; #pragma unroll
;                 for (int sb = 0; sb < 2; ++sb) { const int tqs = tq[sb];
;                     attn_step<64>(qf[sb], Ks, Vt, o[sb], m[sb], lsum[sb], alpha, pf, pf1, lane,
;                         [&](int kk, float s) { const int kpos = kp0 + kk, dist = tqs - kpos; return (dist >= 0 && dist < 256 && kpos >= 0) ? s * LOG2E + lut[min((unsigned)dist, 1023u)] : NEGBIG; }); }
.Lwn_wc_20:
	s_cmp_gt_u32 s20, 4
	s_cbranch_scc1 .Lwn_wc_23
	s_add_i32 s21, s12, 256
	v_sub_u32_e32 v90, v130, v139
	v_subrev_u32_e32 v90, s21, v90
	v_subrev_u32_e32 v170, 0, v90
	v_min_u32_e32 v170, 0x3ff, v170
	v_lshl_add_u32 v170, v170, 2, v131
	ds_read_b32 v170, v170
	v_subrev_u32_e32 v171, 1, v90
	v_min_u32_e32 v171, 0x3ff, v171
	v_lshl_add_u32 v171, v171, 2, v131
	ds_read_b32 v171, v171
	v_subrev_u32_e32 v172, 2, v90
	v_min_u32_e32 v172, 0x3ff, v172
	v_lshl_add_u32 v172, v172, 2, v131
	ds_read_b32 v172, v172
	v_subrev_u32_e32 v173, 3, v90
	v_min_u32_e32 v173, 0x3ff, v173
	v_lshl_add_u32 v173, v173, 2, v131
	ds_read_b32 v173, v173
	v_subrev_u32_e32 v174, 16, v90
	v_min_u32_e32 v174, 0x3ff, v174
	v_lshl_add_u32 v174, v174, 2, v131
	ds_read_b32 v174, v174
	v_subrev_u32_e32 v175, 17, v90
	v_min_u32_e32 v175, 0x3ff, v175
	v_lshl_add_u32 v175, v175, 2, v131
	ds_read_b32 v175, v175
	v_subrev_u32_e32 v176, 18, v90
	v_min_u32_e32 v176, 0x3ff, v176
	v_lshl_add_u32 v176, v176, 2, v131
	ds_read_b32 v176, v176
	v_subrev_u32_e32 v177, 19, v90
	v_min_u32_e32 v177, 0x3ff, v177
	v_lshl_add_u32 v177, v177, 2, v131
	ds_read_b32 v177, v177
	ds_read_b128 v[50:53], v116 offset:40960
	ds_read_b128 v[58:61], v116 offset:43264
	ds_read_b128 v[54:57], v116 offset:41024
	ds_read_b128 v[62:65], v116 offset:43328
	ds_read_b128 v[66:69], v116 offset:45568
	ds_read_b128 v[74:77], v116 offset:47872
	ds_read_b128 v[70:73], v116 offset:45632
	ds_read_b128 v[78:81], v116 offset:47936
	s_waitcnt lgkmcnt(6)
	v_mfma_f32_16x16x32_bf16 v[100:103], v[50:53], v[2:5], 0
	v_mfma_f32_16x16x32_bf16 v[104:107], v[58:61], v[2:5], 0
	s_waitcnt lgkmcnt(4)
	v_mfma_f32_16x16x32_bf16 v[100:103], v[54:57], v[6:9], v[100:103]
	v_mfma_f32_16x16x32_bf16 v[104:107], v[62:65], v[6:9], v[104:107]
	s_waitcnt lgkmcnt(2)
	v_mfma_f32_16x16x32_bf16 v[108:111], v[66:69], v[2:5], 0
	v_mfma_f32_16x16x32_bf16 v[112:115], v[74:77], v[2:5], 0
	s_waitcnt lgkmcnt(0)
	v_mfma_f32_16x16x32_bf16 v[108:111], v[70:73], v[6:9], v[108:111]
	v_mfma_f32_16x16x32_bf16 v[112:115], v[78:81], v[6:9], v[112:115]
	ds_read_b64_tr_b16 v[50:51], v117 offset:50176
	ds_read_b64_tr_b16 v[52:53], v117 offset:52480
	ds_read_b64_tr_b16 v[54:55], v117 offset:54784
	ds_read_b64_tr_b16 v[56:57], v117 offset:57088
	ds_read_b64_tr_b16 v[58:59], v117 offset:50208
	ds_read_b64_tr_b16 v[60:61], v117 offset:52512
	ds_read_b64_tr_b16 v[62:63], v117 offset:54816
	v_fmamk_f32 v100, v100, 0x3fb8aa3b, v170
	v_fmamk_f32 v101, v101, 0x3fb8aa3b, v171
	v_fmamk_f32 v102, v102, 0x3fb8aa3b, v172
	v_fmamk_f32 v103, v103, 0x3fb8aa3b, v173
	v_fmamk_f32 v104, v104, 0x3fb8aa3b, v174
	v_fmamk_f32 v105, v105, 0x3fb8aa3b, v175
	v_fmamk_f32 v106, v106, 0x3fb8aa3b, v176
	v_fmamk_f32 v107, v107, 0x3fb8aa3b, v177
	v_cmp_le_i32_e32 vcc, 0, v90
	s_nop 1
	v_cndmask_b32_e32 v100, v243, v100, vcc
	v_cmp_le_i32_e32 vcc, 1, v90
	s_nop 1
	v_cndmask_b32_e32 v101, v243, v101, vcc
	v_cmp_le_i32_e32 vcc, 2, v90
	s_nop 1
	v_cndmask_b32_e32 v102, v243, v102, vcc
	v_cmp_le_i32_e32 vcc, 3, v90
	s_nop 1
	v_cndmask_b32_e32 v103, v243, v103, vcc
	v_cmp_le_i32_e32 vcc, 16, v90
	s_nop 1
	v_cndmask_b32_e32 v104, v243, v104, vcc
	v_cmp_le_i32_e32 vcc, 17, v90
	s_nop 1
	v_cndmask_b32_e32 v105, v243, v105, vcc
	v_cmp_le_i32_e32 vcc, 18, v90
	s_nop 1
	v_cndmask_b32_e32 v106, v243, v106, vcc
	v_cmp_le_i32_e32 vcc, 19, v90
	s_nop 1
	v_cndmask_b32_e32 v107, v243, v107, vcc
	v_subrev_u32_e32 v170, 32, v90
	v_min_u32_e32 v170, 0x3ff, v170
	v_lshl_add_u32 v170, v170, 2, v131
	ds_read_b32 v170, v170
	v_subrev_u32_e32 v171, 33, v90
	v_min_u32_e32 v171, 0x3ff, v171
	v_lshl_add_u32 v171, v171, 2, v131
	ds_read_b32 v171, v171
	v_subrev_u32_e32 v172, 34, v90
	v_min_u32_e32 v172, 0x3ff, v172
	v_lshl_add_u32 v172, v172, 2, v131
	ds_read_b32 v172, v172
	v_subrev_u32_e32 v173, 35, v90
	v_min_u32_e32 v173, 0x3ff, v173
	v_lshl_add_u32 v173, v173, 2, v131
	ds_read_b32 v173, v173
	v_subrev_u32_e32 v174, 48, v90
	v_min_u32_e32 v174, 0x3ff, v174
	v_lshl_add_u32 v174, v174, 2, v131
	ds_read_b32 v174, v174
	v_subrev_u32_e32 v175, 49, v90
	v_min_u32_e32 v175, 0x3ff, v175
	v_lshl_add_u32 v175, v175, 2, v131
	ds_read_b32 v175, v175
	v_subrev_u32_e32 v176, 50, v90
	v_min_u32_e32 v176, 0x3ff, v176
	v_lshl_add_u32 v176, v176, 2, v131
	ds_read_b32 v176, v176
	v_subrev_u32_e32 v177, 51, v90
	v_min_u32_e32 v177, 0x3ff, v177
	v_lshl_add_u32 v177, v177, 2, v131
	ds_read_b32 v177, v177
	ds_read_b64_tr_b16 v[64:65], v117 offset:57120
	ds_read_b64_tr_b16 v[66:67], v117 offset:50240
	ds_read_b64_tr_b16 v[68:69], v117 offset:52544
	ds_read_b64_tr_b16 v[70:71], v117 offset:54848
	ds_read_b64_tr_b16 v[72:73], v117 offset:57152
	ds_read_b64_tr_b16 v[74:75], v117 offset:50272
	ds_read_b64_tr_b16 v[76:77], v117 offset:52576
	ds_read_b64_tr_b16 v[78:79], v117 offset:54880
	ds_read_b64_tr_b16 v[80:81], v117 offset:57184
	s_waitcnt lgkmcnt(9)
; #define LAS __attribute__((address_space(3)))
; __device__ __forceinline__ unsigned cvt_pk_bf16(float lo, float hi) { unsigned r; asm("v_cvt_pk_bf16_f32 %0, %1, %2" : "=v"(r) : "v"(lo), "v"(hi)); return r; }
; __device__ __forceinline__ f32x4 mfma16(bf16x8 a, bf16x8 b, f32x4 c) { return __builtin_amdgcn_mfma_f32_16x16x32_bf16(a, b, c, 0, 0, 0); }
; template <int D, class SF>
; __device__ __forceinline__ void attn_step(const bf16x8 (&qf)[D / 32], const LAS bf16_t* Ks, const LAS bf16_t* Vt, f32x4 (&o)[D / 16], float& m, float& lsum, float& alpha_out, bf16x8& pf0_out, bf16x8& pf1_out, const int lane, SF sf) {
;     ...
;         for (int r = 0; r < 4; ++r) v[4 * t + r] = sf(16 * t + 4 * i + r, s[t][r]);
;     float mx = fmaxf(fmaxf(fmaxf(v[0], v[1]), fmaxf(v[2], v[3])), fmaxf(fmaxf(v[4], v[5]), fmaxf(v[6], v[7])));
;     mx = fmaxf(mx, fmaxf(fmaxf(fmaxf(v[8], v[9]), fmaxf(v[10], v[11])), fmaxf(fmaxf(v[12], v[13]), fmaxf(v[14], v[15]))));
;     mx = rows_max(mx);
;     const float mnew = fmaxf(m, mx);
;     const float mc = fmaxf(mnew, -1e20f);
;     const float alpha = __builtin_amdgcn_exp2f(fmaxf(m, -1e20f) - mc);
;     float p[16], rs = 0.f;
; #pragma unroll
;     for (int r = 0; r < 16; ++r) { p[r] = __builtin_amdgcn_exp2f(v[r] - mc); rs += p[r]; }
;     rs = rows_sum(rs);
;     lsum = lsum * alpha + rs; m = mnew;
;     union { u32x4 u; bf16x8 b; } pk0, pk1;
;     pk0.u.x = cvt_pk_bf16(p[0], p[1]); pk0.u.y = cvt_pk_bf16(p[2], p[3]); pk0.u.z = cvt_pk_bf16(p[4], p[5]); pk0.u.w = cvt_pk_bf16(p[6], p[7]);
;     pk1.u.x = cvt_pk_bf16(p[8], p[9]); pk1.u.y = cvt_pk_bf16(p[10], p[11]); pk1.u.z = cvt_pk_bf16(p[12], p[13]); pk1.u.w = cvt_pk_bf16(p[14], p[15]);
;     if (__builtin_amdgcn_ballot_w64(alpha != 1.0f) != 0ull) {
; #pragma unroll
;         for (int dt = 0; dt < D / 16; ++dt) o[dt] *= alpha;
;     }
; #pragma unroll
;     for (int dt = 0; dt < D / 16; ++dt) {
;         const LAS bf16_t* vp = Vt + (16 * dt + c) * 72 + 4 * i;
;         union { u32x4 u; bf16x8 b; } vf0, vf1; const u32x2 a0 = *(const LAS u32x2*)vp, a1 = *(const LAS u32x2*)(vp + 16), b0 = *(const LAS u32x2*)(vp + 32), b1 = *(const LAS u32x2*)(vp + 48);
;         vf0.u.x = a0.x; vf0.u.y = a0.y; vf0.u.z = a1.x; vf0.u.w = a1.y; vf1.u.x = b0.x; vf1.u.y = b0.y; vf1.u.z = b1.x; vf1.u.w = b1.y;
;         o[dt] = mfma16(vf0.b, pk0.b, o[dt]); o[dt] = mfma16(vf1.b, pk1.b, o[dt]);
;     }
	v_fmamk_f32 v108, v108, 0x3fb8aa3b, v170
	v_fmamk_f32 v109, v109, 0x3fb8aa3b, v171
	v_fmamk_f32 v110, v110, 0x3fb8aa3b, v172
	v_fmamk_f32 v111, v111, 0x3fb8aa3b, v173
	v_fmamk_f32 v112, v112, 0x3fb8aa3b, v174
	v_fmamk_f32 v113, v113, 0x3fb8aa3b, v175
	v_fmamk_f32 v114, v114, 0x3fb8aa3b, v176
	v_fmamk_f32 v115, v115, 0x3fb8aa3b, v177
	v_cmp_le_i32_e32 vcc, 32, v90
	s_nop 1
	v_cndmask_b32_e32 v108, v243, v108, vcc
	v_cmp_le_i32_e32 vcc, 33, v90
	s_nop 1
	v_cndmask_b32_e32 v109, v243, v109, vcc
	v_cmp_le_i32_e32 vcc, 34, v90
	s_nop 1
	v_cndmask_b32_e32 v110, v243, v110, vcc
	v_cmp_le_i32_e32 vcc, 35, v90
	s_nop 1
	v_cndmask_b32_e32 v111, v243, v111, vcc
	v_cmp_le_i32_e32 vcc, 48, v90
	s_nop 1
	v_cndmask_b32_e32 v112, v243, v112, vcc
	v_cmp_le_i32_e32 vcc, 49, v90
	s_nop 1
	v_cndmask_b32_e32 v113, v243, v113, vcc
	v_cmp_le_i32_e32 vcc, 50, v90
	s_nop 1
	v_cndmask_b32_e32 v114, v243, v114, vcc
	v_cmp_le_i32_e32 vcc, 51, v90
	s_nop 1
	v_cndmask_b32_e32 v115, v243, v115, vcc
	v_max3_f32 v96, v100, v101, v102
	v_max3_f32 v91, v103, v104, v105
	v_max3_f32 v92, v106, v107, v108
	v_max3_f32 v93, v109, v110, v111
	v_max3_f32 v95, v112, v113, v114
	v_max3_f32 v96, v96, v91, v115
	v_max3_f32 v92, v92, v93, v95
	v_max_f32_e32 v96, v96, v92
	v_mov_b32_e32 v91, v96
	s_nop 1
	v_permlane16_swap_b32_e32 v96, v91
	v_max_f32_e32 v96, v96, v91
	v_mov_b32_e32 v91, v96
	s_nop 1
	v_permlane32_swap_b32_e32 v96, v91
	v_max_f32_e32 v96, v96, v91
	v_max_f32_e32 v92, v162, v96
	v_max_f32_e32 v94, 0xe0ad78ec, v162
	v_max_f32_e32 v93, 0xe0ad78ec, v92
	v_sub_f32_e32 v94, v94, v93
	v_mov_b32_e32 v162, v92
	v_exp_f32_e32 v94, v94
	v_sub_f32_e32 v100, v100, v93
	v_sub_f32_e32 v101, v101, v93
	v_sub_f32_e32 v102, v102, v93
	v_sub_f32_e32 v103, v103, v93
	v_exp_f32_e32 v100, v100
	v_exp_f32_e32 v101, v101
	v_exp_f32_e32 v102, v102
	v_exp_f32_e32 v103, v103
	v_sub_f32_e32 v104, v104, v93
	v_sub_f32_e32 v105, v105, v93
	v_sub_f32_e32 v106, v106, v93
	v_sub_f32_e32 v107, v107, v93
	v_exp_f32_e32 v104, v104
	v_exp_f32_e32 v105, v105
	v_exp_f32_e32 v106, v106
	v_exp_f32_e32 v107, v107
	v_sub_f32_e32 v108, v108, v93
	v_sub_f32_e32 v109, v109, v93
	v_sub_f32_e32 v110, v110, v93
	v_sub_f32_e32 v111, v111, v93
	v_exp_f32_e32 v108, v108
	v_exp_f32_e32 v109, v109
	v_exp_f32_e32 v110, v110
	v_exp_f32_e32 v111, v111
	v_sub_f32_e32 v112, v112, v93
	v_sub_f32_e32 v113, v113, v93
	v_sub_f32_e32 v114, v114, v93
	v_sub_f32_e32 v115, v115, v93
	v_exp_f32_e32 v112, v112
	v_exp_f32_e32 v113, v113
	v_exp_f32_e32 v114, v114
	v_exp_f32_e32 v115, v115
	s_nop 0
	v_add_f32_e32 v90, v100, v101
	v_add_f32_e32 v91, v102, v103
	v_add_f32_e32 v92, v104, v105
	v_add_f32_e32 v93, v106, v107
	v_add_f32_e32 v90, v90, v108
	v_add_f32_e32 v91, v91, v109
	v_add_f32_e32 v92, v92, v110
	v_add_f32_e32 v93, v93, v111
	v_add_f32_e32 v90, v90, v112
	v_add_f32_e32 v91, v91, v113
	v_add_f32_e32 v92, v92, v114
	v_add_f32_e32 v93, v93, v115
	v_add_f32_e32 v90, v90, v91
	v_add_f32_e32 v92, v92, v93
	v_add_f32_e32 v90, v90, v92
	v_cvt_pk_bf16_f32 v82, v100, v101
	v_cvt_pk_bf16_f32 v83, v102, v103
	v_cvt_pk_bf16_f32 v84, v104, v105
	v_cvt_pk_bf16_f32 v85, v106, v107
	v_cvt_pk_bf16_f32 v86, v108, v109
	v_cvt_pk_bf16_f32 v87, v110, v111
	v_cvt_pk_bf16_f32 v88, v112, v113
	v_cvt_pk_bf16_f32 v89, v114, v115
	v_mov_b32_e32 v91, v90
	s_nop 1
	v_permlane16_swap_b32_e32 v90, v91
	v_add_f32_e32 v90, v90, v91
	v_mov_b32_e32 v91, v90
	s_nop 1
	v_permlane32_swap_b32_e32 v90, v91
	v_add_f32_e32 v90, v90, v91
	v_fma_f32 v161, v161, v94, v90
	v_cmp_neq_f32_e64 s[4:5], 1.0, v94
	s_cmp_eq_u64 s[4:5], 0
	s_cbranch_scc1 .Lwn_nosc_24
	v_pk_mul_f32 v[46:47], v[46:47], v[94:95] op_sel_hi:[1,0]
	v_pk_mul_f32 v[48:49], v[48:49], v[94:95] op_sel_hi:[1,0]
	v_pk_mul_f32 v[42:43], v[42:43], v[94:95] op_sel_hi:[1,0]
	v_pk_mul_f32 v[44:45], v[44:45], v[94:95] op_sel_hi:[1,0]
	v_pk_mul_f32 v[38:39], v[38:39], v[94:95] op_sel_hi:[1,0]
	v_pk_mul_f32 v[40:41], v[40:41], v[94:95] op_sel_hi:[1,0]
	v_pk_mul_f32 v[34:35], v[34:35], v[94:95] op_sel_hi:[1,0]
	v_pk_mul_f32 v[36:37], v[36:37], v[94:95] op_sel_hi:[1,0]
.Lwn_nosc_24:
	s_waitcnt lgkmcnt(0)
	s_nop 1
	v_mfma_f32_16x16x32_bf16 v[46:49], v[50:53], v[82:85], v[46:49]
	v_mfma_f32_16x16x32_bf16 v[42:45], v[58:61], v[82:85], v[42:45]
	v_mfma_f32_16x16x32_bf16 v[38:41], v[66:69], v[82:85], v[38:41]
	v_mfma_f32_16x16x32_bf16 v[34:37], v[74:77], v[82:85], v[34:37]
	v_mfma_f32_16x16x32_bf16 v[46:49], v[54:57], v[86:89], v[46:49]
	v_mfma_f32_16x16x32_bf16 v[42:45], v[62:65], v[86:89], v[42:45]
	v_mfma_f32_16x16x32_bf16 v[38:41], v[70:73], v[86:89], v[38:41]
	v_mfma_f32_16x16x32_bf16 v[34:37], v[78:81], v[86:89], v[34:37]
	v_sub_u32_e32 v90, v180, v139
	v_subrev_u32_e32 v90, s21, v90
	v_subrev_u32_e32 v170, 0, v90
	v_min_u32_e32 v170, 0x3ff, v170
	v_lshl_add_u32 v170, v170, 2, v131
	ds_read_b32 v170, v170
	v_subrev_u32_e32 v171, 1, v90
	v_min_u32_e32 v171, 0x3ff, v171
	v_lshl_add_u32 v171, v171, 2, v131
	ds_read_b32 v171, v171
	v_subrev_u32_e32 v172, 2, v90
	v_min_u32_e32 v172, 0x3ff, v172
	v_lshl_add_u32 v172, v172, 2, v131
	ds_read_b32 v172, v172
	v_subrev_u32_e32 v173, 3, v90
	v_min_u32_e32 v173, 0x3ff, v173
	v_lshl_add_u32 v173, v173, 2, v131
	ds_read_b32 v173, v173
	v_subrev_u32_e32 v174, 16, v90
	v_min_u32_e32 v174, 0x3ff, v174
	v_lshl_add_u32 v174, v174, 2, v131
	ds_read_b32 v174, v174
	v_subrev_u32_e32 v175, 17, v90
	v_min_u32_e32 v175, 0x3ff, v175
	v_lshl_add_u32 v175, v175, 2, v131
	ds_read_b32 v175, v175
	v_subrev_u32_e32 v176, 18, v90
	v_min_u32_e32 v176, 0x3ff, v176
	v_lshl_add_u32 v176, v176, 2, v131
	ds_read_b32 v176, v176
	v_subrev_u32_e32 v177, 19, v90
	v_min_u32_e32 v177, 0x3ff, v177
	v_lshl_add_u32 v177, v177, 2, v131
	ds_read_b32 v177, v177
	ds_read_b128 v[50:53], v116 offset:40960
	ds_read_b128 v[58:61], v116 offset:43264
	ds_read_b128 v[54:57], v116 offset:41024
	ds_read_b128 v[62:65], v116 offset:43328
	ds_read_b128 v[66:69], v116 offset:45568
	ds_read_b128 v[74:77], v116 offset:47872
	ds_read_b128 v[70:73], v116 offset:45632
	ds_read_b128 v[78:81], v116 offset:47936
	s_waitcnt lgkmcnt(6)
; #define LAS __attribute__((address_space(3)))
; __device__ __forceinline__ unsigned cvt_pk_bf16(float lo, float hi) { unsigned r; asm("v_cvt_pk_bf16_f32 %0, %1, %2" : "=v"(r) : "v"(lo), "v"(hi)); return r; }
; __device__ __forceinline__ f32x4 mfma16(bf16x8 a, bf16x8 b, f32x4 c) { return __builtin_amdgcn_mfma_f32_16x16x32_bf16(a, b, c, 0, 0, 0); }
; template <int D, class SF>
; __device__ __forceinline__ void attn_step(const bf16x8 (&qf)[D / 32], const LAS bf16_t* Ks, const LAS bf16_t* Vt, f32x4 (&o)[D / 16], float& m, float& lsum, float& alpha_out, bf16x8& pf0_out, bf16x8& pf1_out, const int lane, SF sf) {
;     ...
;     for (int ks = 0; ks < D / 32; ++ks) {
; #pragma unroll
;         for (int t = 0; t < 4; ++t) { const bf16x8 kf = *(const LAS bf16x8*)(Ks + (16 * t + c) * KSTR + ks * 32 + 8 * i); s[t] = mfma16(kf, qf[ks], s[t]); }
;     }
;     float v[16];
; #pragma unroll
;     for (int t = 0; t < 4; ++t)
; #pragma unroll
;         for (int r = 0; r < 4; ++r) v[4 * t + r] = sf(16 * t + 4 * i + r, s[t][r]);
;     float mx = fmaxf(fmaxf(fmaxf(v[0], v[1]), fmaxf(v[2], v[3])), fmaxf(fmaxf(v[4], v[5]), fmaxf(v[6], v[7])));
;     mx = fmaxf(mx, fmaxf(fmaxf(fmaxf(v[8], v[9]), fmaxf(v[10], v[11])), fmaxf(fmaxf(v[12], v[13]), fmaxf(v[14], v[15]))));
;     mx = rows_max(mx);
;     const float mnew = fmaxf(m, mx);
;     const float mc = fmaxf(mnew, -1e20f);
;     const float alpha = __builtin_amdgcn_exp2f(fmaxf(m, -1e20f) - mc);
;     float p[16], rs = 0.f;
; #pragma unroll
;     for (int r = 0; r < 16; ++r) { p[r] = __builtin_amdgcn_exp2f(v[r] - mc); rs += p[r]; }
;     rs = rows_sum(rs);
;     lsum = lsum * alpha + rs; m = mnew;
;     union { u32x4 u; bf16x8 b; } pk0, pk1;
;     pk0.u.x = cvt_pk_bf16(p[0], p[1]); pk0.u.y = cvt_pk_bf16(p[2], p[3]); pk0.u.z = cvt_pk_bf16(p[4], p[5]); pk0.u.w = cvt_pk_bf16(p[6], p[7]);
;     pk1.u.x = cvt_pk_bf16(p[8], p[9]); pk1.u.y = cvt_pk_bf16(p[10], p[11]); pk1.u.z = cvt_pk_bf16(p[12], p[13]); pk1.u.w = cvt_pk_bf16(p[14], p[15]);
;     if (__builtin_amdgcn_ballot_w64(alpha != 1.0f) != 0ull) {
; #pragma unroll
;         for (int dt = 0; dt < D / 16; ++dt) o[dt] *= alpha;
;     }
	v_mfma_f32_16x16x32_bf16 v[100:103], v[50:53], v[10:13], 0
	v_mfma_f32_16x16x32_bf16 v[104:107], v[58:61], v[10:13], 0
	s_waitcnt lgkmcnt(4)
	v_mfma_f32_16x16x32_bf16 v[100:103], v[54:57], v[14:17], v[100:103]
	v_mfma_f32_16x16x32_bf16 v[104:107], v[62:65], v[14:17], v[104:107]
	s_waitcnt lgkmcnt(2)
	v_mfma_f32_16x16x32_bf16 v[108:111], v[66:69], v[10:13], 0
	v_mfma_f32_16x16x32_bf16 v[112:115], v[74:77], v[10:13], 0
	s_waitcnt lgkmcnt(0)
	v_mfma_f32_16x16x32_bf16 v[108:111], v[70:73], v[14:17], v[108:111]
	v_mfma_f32_16x16x32_bf16 v[112:115], v[78:81], v[14:17], v[112:115]
	ds_read_b64_tr_b16 v[50:51], v117 offset:50176
	ds_read_b64_tr_b16 v[52:53], v117 offset:52480
	ds_read_b64_tr_b16 v[54:55], v117 offset:54784
	ds_read_b64_tr_b16 v[56:57], v117 offset:57088
	ds_read_b64_tr_b16 v[58:59], v117 offset:50208
	ds_read_b64_tr_b16 v[60:61], v117 offset:52512
	ds_read_b64_tr_b16 v[62:63], v117 offset:54816
	v_fmamk_f32 v100, v100, 0x3fb8aa3b, v170
	v_fmamk_f32 v101, v101, 0x3fb8aa3b, v171
	v_fmamk_f32 v102, v102, 0x3fb8aa3b, v172
	v_fmamk_f32 v103, v103, 0x3fb8aa3b, v173
	v_fmamk_f32 v104, v104, 0x3fb8aa3b, v174
	v_fmamk_f32 v105, v105, 0x3fb8aa3b, v175
	v_fmamk_f32 v106, v106, 0x3fb8aa3b, v176
	v_fmamk_f32 v107, v107, 0x3fb8aa3b, v177
	v_cmp_le_i32_e32 vcc, 0, v90
	s_nop 1
	v_cndmask_b32_e32 v100, v243, v100, vcc
	v_cmp_le_i32_e32 vcc, 1, v90
	s_nop 1
	v_cndmask_b32_e32 v101, v243, v101, vcc
	v_cmp_le_i32_e32 vcc, 2, v90
	s_nop 1
	v_cndmask_b32_e32 v102, v243, v102, vcc
	v_cmp_le_i32_e32 vcc, 3, v90
	s_nop 1
	v_cndmask_b32_e32 v103, v243, v103, vcc
	v_cmp_le_i32_e32 vcc, 16, v90
	s_nop 1
	v_cndmask_b32_e32 v104, v243, v104, vcc
	v_cmp_le_i32_e32 vcc, 17, v90
	s_nop 1
	v_cndmask_b32_e32 v105, v243, v105, vcc
	v_cmp_le_i32_e32 vcc, 18, v90
	s_nop 1
	v_cndmask_b32_e32 v106, v243, v106, vcc
	v_cmp_le_i32_e32 vcc, 19, v90
	s_nop 1
	v_cndmask_b32_e32 v107, v243, v107, vcc
	v_subrev_u32_e32 v170, 32, v90
	v_min_u32_e32 v170, 0x3ff, v170
	v_lshl_add_u32 v170, v170, 2, v131
	ds_read_b32 v170, v170
	v_subrev_u32_e32 v171, 33, v90
	v_min_u32_e32 v171, 0x3ff, v171
	v_lshl_add_u32 v171, v171, 2, v131
	ds_read_b32 v171, v171
	v_subrev_u32_e32 v172, 34, v90
	v_min_u32_e32 v172, 0x3ff, v172
	v_lshl_add_u32 v172, v172, 2, v131
	ds_read_b32 v172, v172
	v_subrev_u32_e32 v173, 35, v90
	v_min_u32_e32 v173, 0x3ff, v173
	v_lshl_add_u32 v173, v173, 2, v131
	ds_read_b32 v173, v173
	v_subrev_u32_e32 v174, 48, v90
	v_min_u32_e32 v174, 0x3ff, v174
	v_lshl_add_u32 v174, v174, 2, v131
	ds_read_b32 v174, v174
	v_subrev_u32_e32 v175, 49, v90
	v_min_u32_e32 v175, 0x3ff, v175
	v_lshl_add_u32 v175, v175, 2, v131
	ds_read_b32 v175, v175
	v_subrev_u32_e32 v176, 50, v90
	v_min_u32_e32 v176, 0x3ff, v176
	v_lshl_add_u32 v176, v176, 2, v131
	ds_read_b32 v176, v176
	v_subrev_u32_e32 v177, 51, v90
	v_min_u32_e32 v177, 0x3ff, v177
	v_lshl_add_u32 v177, v177, 2, v131
	ds_read_b32 v177, v177
	ds_read_b64_tr_b16 v[64:65], v117 offset:57120
	ds_read_b64_tr_b16 v[66:67], v117 offset:50240
	ds_read_b64_tr_b16 v[68:69], v117 offset:52544
	ds_read_b64_tr_b16 v[70:71], v117 offset:54848
	ds_read_b64_tr_b16 v[72:73], v117 offset:57152
	ds_read_b64_tr_b16 v[74:75], v117 offset:50272
	ds_read_b64_tr_b16 v[76:77], v117 offset:52576
	ds_read_b64_tr_b16 v[78:79], v117 offset:54880
	ds_read_b64_tr_b16 v[80:81], v117 offset:57184
	s_waitcnt lgkmcnt(9)
	v_fmamk_f32 v108, v108, 0x3fb8aa3b, v170
	v_fmamk_f32 v109, v109, 0x3fb8aa3b, v171
	v_fmamk_f32 v110, v110, 0x3fb8aa3b, v172
	v_fmamk_f32 v111, v111, 0x3fb8aa3b, v173
	v_fmamk_f32 v112, v112, 0x3fb8aa3b, v174
	v_fmamk_f32 v113, v113, 0x3fb8aa3b, v175
	v_fmamk_f32 v114, v114, 0x3fb8aa3b, v176
	v_fmamk_f32 v115, v115, 0x3fb8aa3b, v177
	v_cmp_le_i32_e32 vcc, 32, v90
	s_nop 1
	v_cndmask_b32_e32 v108, v243, v108, vcc
	v_cmp_le_i32_e32 vcc, 33, v90
	s_nop 1
	v_cndmask_b32_e32 v109, v243, v109, vcc
	v_cmp_le_i32_e32 vcc, 34, v90
	s_nop 1
	v_cndmask_b32_e32 v110, v243, v110, vcc
	v_cmp_le_i32_e32 vcc, 35, v90
	s_nop 1
	v_cndmask_b32_e32 v111, v243, v111, vcc
	v_cmp_le_i32_e32 vcc, 48, v90
	s_nop 1
	v_cndmask_b32_e32 v112, v243, v112, vcc
	v_cmp_le_i32_e32 vcc, 49, v90
	s_nop 1
	v_cndmask_b32_e32 v113, v243, v113, vcc
	v_cmp_le_i32_e32 vcc, 50, v90
	s_nop 1
	v_cndmask_b32_e32 v114, v243, v114, vcc
	v_cmp_le_i32_e32 vcc, 51, v90
	s_nop 1
	v_cndmask_b32_e32 v115, v243, v115, vcc
	v_max3_f32 v96, v100, v101, v102
	v_max3_f32 v91, v103, v104, v105
	v_max3_f32 v92, v106, v107, v108
	v_max3_f32 v93, v109, v110, v111
	v_max3_f32 v95, v112, v113, v114
	v_max3_f32 v96, v96, v91, v115
	v_max3_f32 v92, v92, v93, v95
	v_max_f32_e32 v96, v96, v92
	v_mov_b32_e32 v91, v96
	s_nop 1
	v_permlane16_swap_b32_e32 v96, v91
	v_max_f32_e32 v96, v96, v91
	v_mov_b32_e32 v91, v96
	s_nop 1
	v_permlane32_swap_b32_e32 v96, v91
	v_max_f32_e32 v96, v96, v91
	v_max_f32_e32 v92, v160, v96
	v_max_f32_e32 v94, 0xe0ad78ec, v160
	v_max_f32_e32 v93, 0xe0ad78ec, v92
	v_sub_f32_e32 v94, v94, v93
	v_mov_b32_e32 v160, v92
	v_exp_f32_e32 v94, v94
	v_sub_f32_e32 v100, v100, v93
	v_sub_f32_e32 v101, v101, v93
	v_sub_f32_e32 v102, v102, v93
	v_sub_f32_e32 v103, v103, v93
	v_exp_f32_e32 v100, v100
	v_exp_f32_e32 v101, v101
	v_exp_f32_e32 v102, v102
	v_exp_f32_e32 v103, v103
	v_sub_f32_e32 v104, v104, v93
	v_sub_f32_e32 v105, v105, v93
	v_sub_f32_e32 v106, v106, v93
	v_sub_f32_e32 v107, v107, v93
	v_exp_f32_e32 v104, v104
	v_exp_f32_e32 v105, v105
	v_exp_f32_e32 v106, v106
	v_exp_f32_e32 v107, v107
	v_sub_f32_e32 v108, v108, v93
	v_sub_f32_e32 v109, v109, v93
	v_sub_f32_e32 v110, v110, v93
	v_sub_f32_e32 v111, v111, v93
	v_exp_f32_e32 v108, v108
	v_exp_f32_e32 v109, v109
	v_exp_f32_e32 v110, v110
	v_exp_f32_e32 v111, v111
	v_sub_f32_e32 v112, v112, v93
	v_sub_f32_e32 v113, v113, v93
	v_sub_f32_e32 v114, v114, v93
	v_sub_f32_e32 v115, v115, v93
	v_exp_f32_e32 v112, v112
	v_exp_f32_e32 v113, v113
	v_exp_f32_e32 v114, v114
	v_exp_f32_e32 v115, v115
	s_nop 0
	v_add_f32_e32 v90, v100, v101
	v_add_f32_e32 v91, v102, v103
	v_add_f32_e32 v92, v104, v105
	v_add_f32_e32 v93, v106, v107
	v_add_f32_e32 v90, v90, v108
	v_add_f32_e32 v91, v91, v109
	v_add_f32_e32 v92, v92, v110
	v_add_f32_e32 v93, v93, v111
	v_add_f32_e32 v90, v90, v112
	v_add_f32_e32 v91, v91, v113
	v_add_f32_e32 v92, v92, v114
	v_add_f32_e32 v93, v93, v115
	v_add_f32_e32 v90, v90, v91
	v_add_f32_e32 v92, v92, v93
	v_add_f32_e32 v90, v90, v92
	v_cvt_pk_bf16_f32 v82, v100, v101
	v_cvt_pk_bf16_f32 v83, v102, v103
	v_cvt_pk_bf16_f32 v84, v104, v105
	v_cvt_pk_bf16_f32 v85, v106, v107
	v_cvt_pk_bf16_f32 v86, v108, v109
	v_cvt_pk_bf16_f32 v87, v110, v111
	v_cvt_pk_bf16_f32 v88, v112, v113
	v_cvt_pk_bf16_f32 v89, v114, v115
	v_mov_b32_e32 v91, v90
	s_nop 1
	v_permlane16_swap_b32_e32 v90, v91
	v_add_f32_e32 v90, v90, v91
	v_mov_b32_e32 v91, v90
	s_nop 1
	v_permlane32_swap_b32_e32 v90, v91
	v_add_f32_e32 v90, v90, v91
	v_fma_f32 v159, v159, v94, v90
	v_cmp_neq_f32_e64 s[4:5], 1.0, v94
	s_cmp_eq_u64 s[4:5], 0
	s_cbranch_scc1 .Lwn_nosc_25
; template <int D, class SF>
; __device__ __forceinline__ void attn_step(const bf16x8 (&qf)[D / 32], const LAS bf16_t* Ks, const LAS bf16_t* Vt, f32x4 (&o)[D / 16], float& m, float& lsum, float& alpha_out, bf16x8& pf0_out, bf16x8& pf1_out, const int lane, SF sf) {
;     ...
;     if (__builtin_amdgcn_ballot_w64(alpha != 1.0f) != 0ull) {
; #pragma unroll
;         for (int dt = 0; dt < D / 16; ++dt) o[dt] *= alpha;
;     }
	v_pk_mul_f32 v[30:31], v[30:31], v[94:95] op_sel_hi:[1,0]
	v_pk_mul_f32 v[32:33], v[32:33], v[94:95] op_sel_hi:[1,0]
	v_pk_mul_f32 v[26:27], v[26:27], v[94:95] op_sel_hi:[1,0]
	v_pk_mul_f32 v[28:29], v[28:29], v[94:95] op_sel_hi:[1,0]
	v_pk_mul_f32 v[22:23], v[22:23], v[94:95] op_sel_hi:[1,0]
	v_pk_mul_f32 v[24:25], v[24:25], v[94:95] op_sel_hi:[1,0]
	v_pk_mul_f32 v[18:19], v[18:19], v[94:95] op_sel_hi:[1,0]
	v_pk_mul_f32 v[20:21], v[20:21], v[94:95] op_sel_hi:[1,0]

; #define LAS __attribute__((address_space(3)))
; __device__ __forceinline__ void nsa_unit(LAS unsigned char* lds, const Ctx& P, int l, int b, int hkv, int tb) {
;     ...
;         for (int k = kfirst; k < 5; k += 2) { const int p0 = t0 - 256 + 64 * k; const bool hasb = k + 1 < 5;
;             __syncthreads();
;             load2(kb, vb, LDH, p0, p0 + 64, hasb, SEQ - 1);
;             __syncthreads();
; #pragma unroll
;             for (int sl = 0; sl < 2; ++sl) if (sl == 0 || hasb) { const LAS bf16_t* Ks = KV + sl * 9216; const LAS bf16_t* Vt = Ks + 4608; const int kp0 = p0 + sl * 64;
; #pragma unroll
;                 for (int sb = 0; sb < 2; ++sb) { const int tqs = tq[sb];
;                     attn_step<64>(qf[sb], Ks, Vt, o[sb], m[sb], lsum[sb], alpha, pf, pf1, lane,
;                         [&](int kk, float s) { const int kpos = kp0 + kk, dist = tqs - kpos; return (dist >= 0 && dist < 256 && kpos >= 0) ? s * LOG2E + lut[min((unsigned)dist, 1023u)] : NEGBIG; }); }
;             }
;         }
.Lwn_wc_23:
	s_nop 7
	s_branch .LBB0_183

; __device__ __forceinline__ void fast_sync(unsigned* ctl, unsigned gen, unsigned nwg) {
;     __syncthreads();
;     if (threadIdx.x == 0) {
;         __builtin_amdgcn_fence(__ATOMIC_RELEASE, "agent");
;         asm volatile("s_waitcnt vmcnt(0) lgkmcnt(0)" ::: "memory");
;         bool last = false;
;         if (__hip_atomic_fetch_add(ctl + 256 + 32 * (blockIdx.x & 7), 1u, __ATOMIC_RELAXED, __HIP_MEMORY_SCOPE_AGENT) == gen * (nwg >> 3) - 1u) {
;             if (__hip_atomic_fetch_add(ctl, 1u, __ATOMIC_RELAXED, __HIP_MEMORY_SCOPE_AGENT) == gen * 8u - 1u) { __hip_atomic_store(ctl + 32, gen, __ATOMIC_RELAXED, __HIP_MEMORY_SCOPE_AGENT); last = true; } }
;         if (!last) while (__hip_atomic_load(ctl + 32, __ATOMIC_RELAXED, __HIP_MEMORY_SCOPE_AGENT) < gen) __builtin_amdgcn_s_sleep(1);
;         __builtin_amdgcn_fence(__ATOMIC_ACQUIRE, "agent");
;         asm volatile("s_waitcnt vmcnt(0) lgkmcnt(0)" ::: "memory");
;     }
; __global__ void __launch_bounds__(512, 2) fwd_megakernel(Params PK) {
;     ...
;         if (gp + 1 < ph_hi) { if (gp == ph_lo) grid.sync(); else { ++nbar; fast_sync((unsigned*)ws, nbar, (unsigned)G); } }
.LBB0_1076:
	v_readlane_b32 s0, v255, 34
	s_add_i32 s11, s0, 1
	s_waitcnt vmcnt(0)
	s_barrier
	s_mov_b64 s[0:1], exec
	v_readlane_b32 s4, v253, 2
	v_readlane_b32 s5, v253, 3
	s_and_b64 s[4:5], s[0:1], s[4:5]
	s_mov_b64 exec, s[4:5]
	s_cbranch_execz .LBB0_1085
	s_mov_b64 s[4:5], exec
	buffer_wbl2 sc1
	s_waitcnt vmcnt(0) lgkmcnt(0)
	v_mbcnt_lo_u32_b32 v0, s4, 0
	v_mbcnt_hi_u32_b32 v0, s5, v0
	v_cmp_eq_u32_e32 vcc, 0, v0
	s_and_saveexec_b64 s[6:7], vcc
	s_cbranch_execz .LBB0_1080
	s_bcnt1_i32_b64 s4, s[4:5]
	v_readlane_b32 s5, v254, 44
	v_mov_b32_e32 v3, s4
	s_nop 0
	v_mov_b32_e32 v2, s5
	global_atomic_add v2, v2, v3, s[68:69] offset:1024 sc0
